# rotated GEMM k-loops: the five ds_reads feeding the first MFMA group issued ahead of the prefetch loads after each barrier, on top of v_rot2
# baseline (speedup 1.0000x reference)
.LBB0_208:
	ds_read_b128 v[204:207], v178 offset:32768
	ds_read_b128 v[208:211], v178 offset:33792
	ds_read_b128 v[212:215], v178 offset:34816
	ds_read_b128 v[216:219], v178 offset:35840
	ds_read_b128 v[222:225], v176
	global_load_dwordx4 v[180:183], v[180:181], off
	ds_read_b128 v[226:229], v176 offset:1024
	global_load_dwordx4 v[184:187], v[184:185], off
	ds_read_b128 v[230:233], v176 offset:2048
	global_load_dwordx4 v[188:191], v[188:189], off
	ds_read_b128 v[234:237], v176 offset:3072
	global_load_dwordx4 v[192:195], v[192:193], off
	ds_read_b128 v[238:241], v176 offset:4096
	global_load_dwordx4 v[196:199], v[196:197], off
	ds_read_b128 v[242:245], v176 offset:5120
	global_load_dwordx4 v[200:203], v[200:201], off
	ds_read_b128 v[246:249], v176 offset:6144
	ds_read_b128 v[250:253], v176 offset:7168
	s_setprio 1
	s_waitcnt lgkmcnt(7)
	v_mfma_f32_16x16x32_bf16 v[124:127], v[222:225], v[204:207], v[124:127]
	v_mfma_f32_16x16x32_bf16 v[120:123], v[222:225], v[208:211], v[120:123]
	v_mfma_f32_16x16x32_bf16 v[60:63], v[222:225], v[212:215], v[60:63]
	v_mfma_f32_16x16x32_bf16 v[56:59], v[222:225], v[216:219], v[56:59]
	s_waitcnt vmcnt(11)
	ds_write_b128 v152, v[128:131] offset:16384
	s_waitcnt lgkmcnt(7)
	v_mfma_f32_16x16x32_bf16 v[116:119], v[226:229], v[204:207], v[116:119]
	v_mfma_f32_16x16x32_bf16 v[112:115], v[226:229], v[208:211], v[112:115]
	v_mfma_f32_16x16x32_bf16 v[52:55], v[226:229], v[212:215], v[52:55]
	v_mfma_f32_16x16x32_bf16 v[48:51], v[226:229], v[216:219], v[48:51]
	s_waitcnt vmcnt(9)
	ds_write_b128 v152, v[136:139] offset:20480
	s_waitcnt lgkmcnt(7)
	v_mfma_f32_16x16x32_bf16 v[108:111], v[230:233], v[204:207], v[108:111]
	v_mfma_f32_16x16x32_bf16 v[104:107], v[230:233], v[208:211], v[104:107]
	v_mfma_f32_16x16x32_bf16 v[44:47], v[230:233], v[212:215], v[44:47]
	v_mfma_f32_16x16x32_bf16 v[40:43], v[230:233], v[216:219], v[40:43]
	s_waitcnt vmcnt(8)
	ds_write_b128 v152, v[140:143] offset:24576
	s_waitcnt lgkmcnt(7)
	v_mfma_f32_16x16x32_bf16 v[100:103], v[234:237], v[204:207], v[100:103]
	v_mfma_f32_16x16x32_bf16 v[96:99], v[234:237], v[208:211], v[96:99]
	v_mfma_f32_16x16x32_bf16 v[36:39], v[234:237], v[212:215], v[36:39]
	v_mfma_f32_16x16x32_bf16 v[32:35], v[234:237], v[216:219], v[32:35]
	s_waitcnt vmcnt(7)
	ds_write_b128 v152, v[144:147] offset:28672
	s_waitcnt lgkmcnt(7)
	v_mfma_f32_16x16x32_bf16 v[92:95], v[238:241], v[204:207], v[92:95]
	v_mfma_f32_16x16x32_bf16 v[88:91], v[238:241], v[208:211], v[88:91]
	v_mfma_f32_16x16x32_bf16 v[28:31], v[238:241], v[212:215], v[28:31]
	v_mfma_f32_16x16x32_bf16 v[24:27], v[238:241], v[216:219], v[24:27]
	s_waitcnt vmcnt(7)
	ds_write_b128 v152, v[132:135] offset:40960
	s_waitcnt lgkmcnt(7)
	v_mfma_f32_16x16x32_bf16 v[84:87], v[242:245], v[204:207], v[84:87]
	v_mfma_f32_16x16x32_bf16 v[80:83], v[242:245], v[208:211], v[80:83]
	v_mfma_f32_16x16x32_bf16 v[20:23], v[242:245], v[212:215], v[20:23]
	v_mfma_f32_16x16x32_bf16 v[16:19], v[242:245], v[216:219], v[16:19]
	s_waitcnt vmcnt(6)
	ds_write_b128 v152, v[148:151] offset:45056
	s_waitcnt lgkmcnt(7)
	v_mfma_f32_16x16x32_bf16 v[76:79], v[246:249], v[204:207], v[76:79]
	v_mfma_f32_16x16x32_bf16 v[72:75], v[246:249], v[208:211], v[72:75]
	v_mfma_f32_16x16x32_bf16 v[12:15], v[246:249], v[212:215], v[12:15]
	v_mfma_f32_16x16x32_bf16 v[8:11], v[246:249], v[216:219], v[8:11]
	s_waitcnt lgkmcnt(6)
	v_mfma_f32_16x16x32_bf16 v[68:71], v[250:253], v[204:207], v[68:71]
	v_mfma_f32_16x16x32_bf16 v[64:67], v[250:253], v[208:211], v[64:67]
	v_mfma_f32_16x16x32_bf16 v[4:7], v[250:253], v[212:215], v[4:7]
	v_mfma_f32_16x16x32_bf16 v[0:3], v[250:253], v[216:219], v[0:3]
	s_setprio 0
	s_min_u32 s5, s5, 0x380
	s_lshl_b32 s30, s5, 1
	s_mov_b32 s53, s31
	s_add_i32 s52, s30, 0xc0
	v_lshl_add_u64 v[128:129], v[154:155], 0, s[30:31]
	v_lshl_add_u64 v[132:133], v[156:157], 0, s[30:31]
	v_lshl_add_u64 v[136:137], v[158:159], 0, s[52:53]
	v_lshl_add_u64 v[140:141], v[160:161], 0, s[52:53]
	v_lshl_add_u64 v[144:145], v[162:163], 0, s[52:53]
	v_lshl_add_u64 v[148:149], v[164:165], 0, s[52:53]
	s_waitcnt lgkmcnt(0)
	s_barrier
	ds_read_b128 v[204:207], v175 offset:40960
	ds_read_b128 v[208:211], v175 offset:41984
	ds_read_b128 v[212:215], v175 offset:43008
	ds_read_b128 v[216:219], v175 offset:44032
	ds_read_b128 v[222:225], v177
	global_load_dwordx4 v[128:131], v[128:129], off offset:192
	ds_read_b128 v[226:229], v177 offset:1024
	global_load_dwordx4 v[132:135], v[132:133], off offset:192
	ds_read_b128 v[230:233], v177 offset:2048
	global_load_dwordx4 v[136:139], v[136:137], off
	ds_read_b128 v[234:237], v177 offset:3072
	global_load_dwordx4 v[140:143], v[140:141], off
	ds_read_b128 v[238:241], v177 offset:4096
	global_load_dwordx4 v[144:147], v[144:145], off
	ds_read_b128 v[242:245], v177 offset:5120
	global_load_dwordx4 v[148:151], v[148:149], off
	ds_read_b128 v[246:249], v177 offset:6144
	ds_read_b128 v[250:253], v177 offset:7168
	s_setprio 1
	s_waitcnt lgkmcnt(7)
	v_mfma_f32_16x16x32_bf16 v[124:127], v[222:225], v[204:207], v[124:127]
	v_mfma_f32_16x16x32_bf16 v[120:123], v[222:225], v[208:211], v[120:123]
	v_mfma_f32_16x16x32_bf16 v[60:63], v[222:225], v[212:215], v[60:63]
	v_mfma_f32_16x16x32_bf16 v[56:59], v[222:225], v[216:219], v[56:59]
	s_waitcnt vmcnt(11)
	ds_write_b128 v152, v[180:183]
	s_waitcnt lgkmcnt(7)
	v_mfma_f32_16x16x32_bf16 v[116:119], v[226:229], v[204:207], v[116:119]
	v_mfma_f32_16x16x32_bf16 v[112:115], v[226:229], v[208:211], v[112:115]
	v_mfma_f32_16x16x32_bf16 v[52:55], v[226:229], v[212:215], v[52:55]
	v_mfma_f32_16x16x32_bf16 v[48:51], v[226:229], v[216:219], v[48:51]
	s_waitcnt vmcnt(10)
	ds_write_b128 v152, v[184:187] offset:4096
	s_waitcnt lgkmcnt(7)
	v_mfma_f32_16x16x32_bf16 v[108:111], v[230:233], v[204:207], v[108:111]
	v_mfma_f32_16x16x32_bf16 v[104:107], v[230:233], v[208:211], v[104:107]
	v_mfma_f32_16x16x32_bf16 v[44:47], v[230:233], v[212:215], v[44:47]
	v_mfma_f32_16x16x32_bf16 v[40:43], v[230:233], v[216:219], v[40:43]
	s_waitcnt vmcnt(9)
	ds_write_b128 v152, v[188:191] offset:8192
	s_waitcnt lgkmcnt(7)
	v_mfma_f32_16x16x32_bf16 v[100:103], v[234:237], v[204:207], v[100:103]
	v_mfma_f32_16x16x32_bf16 v[96:99], v[234:237], v[208:211], v[96:99]
	v_mfma_f32_16x16x32_bf16 v[36:39], v[234:237], v[212:215], v[36:39]
	v_mfma_f32_16x16x32_bf16 v[32:35], v[234:237], v[216:219], v[32:35]
	s_waitcnt vmcnt(8)
	ds_write_b128 v152, v[192:195] offset:12288
	s_waitcnt lgkmcnt(7)
	v_mfma_f32_16x16x32_bf16 v[92:95], v[238:241], v[204:207], v[92:95]
	v_mfma_f32_16x16x32_bf16 v[88:91], v[238:241], v[208:211], v[88:91]
	v_mfma_f32_16x16x32_bf16 v[28:31], v[238:241], v[212:215], v[28:31]
	v_mfma_f32_16x16x32_bf16 v[24:27], v[238:241], v[216:219], v[24:27]
	s_waitcnt vmcnt(7)
	ds_write_b128 v152, v[196:199] offset:32768
	s_waitcnt lgkmcnt(7)
	v_mfma_f32_16x16x32_bf16 v[84:87], v[242:245], v[204:207], v[84:87]
	v_mfma_f32_16x16x32_bf16 v[80:83], v[242:245], v[208:211], v[80:83]
	v_mfma_f32_16x16x32_bf16 v[20:23], v[242:245], v[212:215], v[20:23]
	v_mfma_f32_16x16x32_bf16 v[16:19], v[242:245], v[216:219], v[16:19]
	s_waitcnt vmcnt(6)
	ds_write_b128 v152, v[200:203] offset:36864
	s_waitcnt lgkmcnt(7)
	v_mfma_f32_16x16x32_bf16 v[76:79], v[246:249], v[204:207], v[76:79]
	v_mfma_f32_16x16x32_bf16 v[72:75], v[246:249], v[208:211], v[72:75]
	v_mfma_f32_16x16x32_bf16 v[12:15], v[246:249], v[212:215], v[12:15]
	v_mfma_f32_16x16x32_bf16 v[8:11], v[246:249], v[216:219], v[8:11]
	s_waitcnt lgkmcnt(6)
	v_mfma_f32_16x16x32_bf16 v[68:71], v[250:253], v[204:207], v[68:71]
	v_mfma_f32_16x16x32_bf16 v[64:67], v[250:253], v[208:211], v[64:67]
	v_mfma_f32_16x16x32_bf16 v[4:7], v[250:253], v[212:215], v[4:7]
	v_mfma_f32_16x16x32_bf16 v[0:3], v[250:253], v[216:219], v[0:3]
	s_setprio 0
	s_add_i32 s1, s1, 2
	s_mov_b32 s5, s27
	s_add_i32 s27, s5, 64
	s_min_u32 s30, s27, 0x3e0
	s_lshl_b32 s30, s30, 1
	v_lshl_add_u64 v[180:181], v[154:155], 0, s[30:31]
	v_lshl_add_u64 v[184:185], v[158:159], 0, s[30:31]
	v_lshl_add_u64 v[188:189], v[160:161], 0, s[30:31]
	v_lshl_add_u64 v[192:193], v[162:163], 0, s[30:31]
	v_lshl_add_u64 v[196:197], v[156:157], 0, s[30:31]
	v_lshl_add_u64 v[200:201], v[164:165], 0, s[30:31]
	s_cmp_lt_u32 s1, 30
	s_waitcnt lgkmcnt(0)
	s_cbranch_scc1 .Lrot_5
	s_barrier
	s_waitcnt vmcnt(5)
	v_mov_b32_e32 v128, v220
	s_cmp_gt_i32 s26, 15
	v_and_b32_e32 v158, 15, v128
	v_and_b32_e32 v160, 64, v128
	v_and_b32_e32 v129, 0xffffff80, v128
	v_lshrrev_b32_e32 v128, 2, v128
	v_add_u32_e32 v130, s4, v129
	v_and_b32_e32 v159, 12, v128
	s_waitcnt vmcnt(3)
	v_or_b32_e32 v136, v130, v159
	v_ashrrev_i32_e32 v128, 14, v130
	s_waitcnt vmcnt(0)
	v_or_b32_e32 v150, 16, v136
	v_or_b32_e32 v148, 32, v136
	v_or_b32_e32 v146, 48, v136
	v_or_b32_e32 v142, 64, v136
	v_or_b32_e32 v140, 0x50, v136
	v_or_b32_e32 v138, 0x60, v136
	v_or_b32_e32 v134, 0x70, v136
	s_mov_b64 s[4:5], -1
	v_ashrrev_i32_e32 v137, 31, v136
	v_lshlrev_b32_e32 v132, 1, v159
	v_mov_b32_e32 v250, s0
	v_and_b32_e32 v250, 0x80, v250
	v_add_u32_e32 v250, v250, v160
	v_mul_u32_u24_e32 v250, 30, v250
	v_lshrrev_b32_e32 v251, 3, v158
	v_mul_u32_u24_e32 v251, 0xf0, v251
	v_add_u32_e32 v250, v250, v251
	v_lshrrev_b32_e32 v251, 2, v159
	v_mul_u32_u24_e32 v251, 0x7c0, v251
	v_sub_u32_e32 v250, v250, v251
	v_ashrrev_i32_e32 v251, 31, v250
	v_and_b32_e32 v252, 8, v159
	v_lshlrev_b32_e32 v252, 5, v252
	v_and_b32_e32 v253, 4, v159
	v_lshl_or_b32 v252, v253, 1, v252
	v_lshl_or_b32 v252, v158, 4, v252
	v_mov_b32_e32 v253, 0
	v_ashrrev_i32_e32 v129, 31, v128
	v_ashrrev_i32_e32 v151, 31, v150
	v_ashrrev_i32_e32 v149, 31, v148
	v_ashrrev_i32_e32 v147, 31, v146
	v_ashrrev_i32_e32 v143, 31, v142
	v_ashrrev_i32_e32 v141, 31, v140
	v_ashrrev_i32_e32 v139, 31, v138
	v_ashrrev_i32_e32 v135, 31, v134
	s_cbranch_scc0 .LBB0_211
	v_lshl_add_u64 v[144:145], v[136:137], 2, s[8:9]
	global_load_dwordx4 v[162:165], v[144:145], off
	s_add_i32 s1, s0, 0xfffff800
	s_and_b32 s5, s0, 0x180
	s_ashr_i32 s4, s1, 9
	v_or_b32_e32 v154, s5, v160
	s_ashr_i32 s5, s4, 31
	v_lshlrev_b64 v[144:145], 9, v[128:129]
	s_lshl_b64 s[4:5], s[4:5], 7
	v_lshrrev_b32_e32 v152, 7, v130
	v_lshl_add_u64 v[130:131], v[144:145], 0, s[4:5]
	v_and_or_b32 v130, v152, s38, v130
	v_lshlrev_b64 v[130:131], 16, v[130:131]
	v_mov_b32_e32 v133, v153
	v_lshl_or_b32 v130, v154, 7, v130
	v_lshl_add_u64 v[178:179], s[12:13], 0, v[252:253]
	v_mov_b32_e32 v145, v131
	v_mov_b32_e32 v181, v131
	v_lshlrev_b64 v[156:157], 1, v[130:131]
	v_or_b32_e32 v144, 0x800, v130
	v_or_b32_e32 v180, 0x1000, v130
	v_or_b32_e32 v130, 0x1800, v130
	v_lshl_add_u64 v[182:183], v[178:179], 0, v[156:157]
	v_lshlrev_b64 v[154:155], 1, v[144:145]
	v_lshlrev_b64 v[144:145], 1, v[180:181]
	v_lshlrev_b64 v[130:131], 1, v[130:131]
	v_lshl_add_u64 v[176:177], v[150:151], 2, s[8:9]
	v_lshl_add_u64 v[180:181], v[178:179], 0, v[154:155]
	v_lshl_add_u64 v[184:185], v[178:179], 0, v[144:145]
	v_lshl_add_u64 v[178:179], v[178:179], 0, v[130:131]
	s_waitcnt vmcnt(0)
	v_mul_f32_e32 v133, v124, v162
	v_mul_f32_e32 v152, v125, v163
	v_mul_f32_e32 v161, v126, v164
	v_mul_f32_e32 v175, v127, v165
	v_mul_f32_e32 v186, v120, v162
	v_mul_f32_e32 v187, v121, v163
	v_mul_f32_e32 v188, v122, v164
	v_mul_f32_e32 v189, v123, v165
	v_mul_f32_e32 v190, v60, v162
	v_mul_f32_e32 v191, v61, v163
	v_mul_f32_e32 v194, v56, v162
	v_mul_f32_e32 v195, v57, v163
	v_cvt_pk_bf16_f32 v162, v133, v152
	v_cvt_pk_bf16_f32 v163, v161, v175
	v_mul_f32_e32 v192, v62, v164
	v_mul_f32_e32 v193, v63, v165
	v_mul_f32_e32 v196, v58, v164
	v_mul_f32_e32 v197, v59, v165
	v_cvt_pk_bf16_f32 v164, v186, v187
	v_cvt_pk_bf16_f32 v165, v188, v189
	v_cvt_pk_bf16_f32 v186, v190, v191
	v_cvt_pk_bf16_f32 v187, v192, v193
	v_cvt_pk_bf16_f32 v188, v194, v195
	v_cvt_pk_bf16_f32 v189, v196, v197
	global_store_dwordx2 v[182:183], v[162:163], off
	global_store_dwordx2 v[180:181], v[164:165], off
	global_store_dwordx2 v[184:185], v[186:187], off
	global_store_dwordx2 v[178:179], v[188:189], off
	global_load_dwordx4 v[162:165], v[176:177], off
	v_bitop3_b32 v133, v136, 28, 16 bitop3:0xc8
	v_lshlrev_b32_e32 v152, 1, v133
	v_lshl_add_u64 v[178:179], s[12:13], 0, v[252:253]
	v_lshl_add_u64 v[180:181], v[178:179], 0, v[156:157]
	v_lshl_add_u64 v[176:177], v[148:149], 2, s[8:9]
	v_lshl_add_u64 v[182:183], v[178:179], 0, v[154:155]
	v_lshl_add_u64 v[184:185], v[178:179], 0, v[144:145]
	v_lshl_add_u64 v[178:179], v[178:179], 0, v[130:131]
	s_waitcnt vmcnt(0)
	v_mul_f32_e32 v133, v116, v162
	v_mul_f32_e32 v152, v117, v163
	v_mul_f32_e32 v161, v118, v164
	v_mul_f32_e32 v175, v119, v165
	v_mul_f32_e32 v186, v112, v162
	v_mul_f32_e32 v187, v113, v163
	v_mul_f32_e32 v188, v114, v164
	v_mul_f32_e32 v189, v115, v165
	global_load_dwordx4 v[116:119], v[176:177], off
	v_mul_f32_e32 v190, v52, v162
	v_mul_f32_e32 v191, v53, v163
	v_mul_f32_e32 v194, v48, v162
	v_mul_f32_e32 v195, v49, v163
	v_cvt_pk_bf16_f32 v162, v133, v152
	v_cvt_pk_bf16_f32 v163, v161, v175
	v_mul_f32_e32 v192, v54, v164
	v_mul_f32_e32 v193, v55, v165
	v_mul_f32_e32 v196, v50, v164
	v_mul_f32_e32 v197, v51, v165
	v_cvt_pk_bf16_f32 v164, v186, v187
	v_cvt_pk_bf16_f32 v165, v188, v189
	v_cvt_pk_bf16_f32 v186, v190, v191
	v_cvt_pk_bf16_f32 v187, v192, v193
	v_cvt_pk_bf16_f32 v188, v194, v195
	v_cvt_pk_bf16_f32 v189, v196, v197
	global_store_dwordx2 v[180:181], v[162:163], off offset:512
	global_store_dwordx2 v[182:183], v[164:165], off offset:512
	global_store_dwordx2 v[184:185], v[186:187], off offset:512
	global_store_dwordx2 v[178:179], v[188:189], off offset:512
	v_bitop3_b32 v133, v136, 44, 32 bitop3:0xc8
	v_lshlrev_b32_e32 v152, 1, v133
	v_lshl_add_u64 v[178:179], s[12:13], 0, v[252:253]
	v_lshl_add_u64 v[180:181], v[178:179], 0, v[156:157]
	v_lshl_add_u64 v[176:177], v[146:147], 2, s[8:9]
	global_load_dwordx4 v[112:115], v[176:177], off
	v_lshl_add_u64 v[182:183], v[178:179], 0, v[154:155]
	v_lshl_add_u64 v[184:185], v[178:179], 0, v[144:145]
	v_lshl_add_u64 v[178:179], v[178:179], 0, v[130:131]
	s_waitcnt vmcnt(5)
	v_mov_b32_e32 v162, v116
	v_mov_b32_e32 v163, v117
	v_mov_b32_e32 v164, v118
	v_mov_b32_e32 v165, v119
	v_mul_f32_e32 v133, v108, v162
	v_mul_f32_e32 v152, v109, v163
	v_mul_f32_e32 v161, v110, v164
	v_mul_f32_e32 v175, v111, v165
	v_mul_f32_e32 v186, v104, v162
	v_mul_f32_e32 v187, v105, v163
	v_mul_f32_e32 v188, v106, v164
	v_mul_f32_e32 v189, v107, v165
	v_mul_f32_e32 v190, v44, v162
	v_mul_f32_e32 v191, v45, v163
	v_mul_f32_e32 v194, v40, v162
	v_mul_f32_e32 v195, v41, v163
	v_cvt_pk_bf16_f32 v162, v133, v152
	v_cvt_pk_bf16_f32 v163, v161, v175
	v_mul_f32_e32 v192, v46, v164
	v_mul_f32_e32 v193, v47, v165
	v_mul_f32_e32 v196, v42, v164
	v_mul_f32_e32 v197, v43, v165
	v_cvt_pk_bf16_f32 v164, v186, v187
	v_cvt_pk_bf16_f32 v165, v188, v189
	v_cvt_pk_bf16_f32 v186, v190, v191
	v_cvt_pk_bf16_f32 v187, v192, v193
	v_cvt_pk_bf16_f32 v188, v194, v195
	v_cvt_pk_bf16_f32 v189, v196, v197
	global_store_dwordx2 v[180:181], v[162:163], off offset:1024
	global_store_dwordx2 v[182:183], v[164:165], off offset:1024
	global_store_dwordx2 v[184:185], v[186:187], off offset:1024
	global_store_dwordx2 v[178:179], v[188:189], off offset:1024
	v_bitop3_b32 v133, v136, 60, 48 bitop3:0xc8
	v_lshlrev_b32_e32 v152, 1, v133
	v_lshl_add_u64 v[178:179], s[12:13], 0, v[252:253]
	v_lshl_add_u64 v[180:181], v[178:179], 0, v[156:157]
	v_lshl_add_u64 v[176:177], v[142:143], 2, s[8:9]
	global_load_dwordx4 v[116:119], v[176:177], off
	v_lshl_add_u64 v[182:183], v[178:179], 0, v[154:155]
	v_lshl_add_u64 v[184:185], v[178:179], 0, v[144:145]
	v_lshl_add_u64 v[178:179], v[178:179], 0, v[130:131]
	s_waitcnt vmcnt(5)
	v_mov_b32_e32 v162, v112
	v_mov_b32_e32 v163, v113
	v_mov_b32_e32 v164, v114
	v_mov_b32_e32 v165, v115
	v_mul_f32_e32 v133, v100, v162
	v_mul_f32_e32 v152, v101, v163
	v_mul_f32_e32 v161, v102, v164
	v_mul_f32_e32 v175, v103, v165
	v_mul_f32_e32 v186, v96, v162
	v_mul_f32_e32 v187, v97, v163
	v_mul_f32_e32 v188, v98, v164
	v_mul_f32_e32 v189, v99, v165
	v_mul_f32_e32 v190, v36, v162
	v_mul_f32_e32 v191, v37, v163
	v_mul_f32_e32 v194, v32, v162
	v_mul_f32_e32 v195, v33, v163
	v_cvt_pk_bf16_f32 v162, v133, v152
	v_cvt_pk_bf16_f32 v163, v161, v175
	v_mul_f32_e32 v192, v38, v164
	v_mul_f32_e32 v193, v39, v165
	v_mul_f32_e32 v196, v34, v164
	v_mul_f32_e32 v197, v35, v165
	v_cvt_pk_bf16_f32 v164, v186, v187
	v_cvt_pk_bf16_f32 v165, v188, v189
	v_cvt_pk_bf16_f32 v186, v190, v191
	v_cvt_pk_bf16_f32 v187, v192, v193
	v_cvt_pk_bf16_f32 v188, v194, v195
	v_cvt_pk_bf16_f32 v189, v196, v197
	global_store_dwordx2 v[180:181], v[162:163], off offset:1536
	global_store_dwordx2 v[182:183], v[164:165], off offset:1536
	global_store_dwordx2 v[184:185], v[186:187], off offset:1536
	global_store_dwordx2 v[178:179], v[188:189], off offset:1536
	v_bitop3_b32 v133, v136, s39, 64 bitop3:0xc8
	v_lshlrev_b32_e32 v152, 1, v133
	v_lshl_add_u64 v[178:179], s[12:13], 0, v[252:253]
	v_lshl_add_u64 v[180:181], v[178:179], 0, v[156:157]
	v_lshl_add_u64 v[176:177], v[140:141], 2, s[8:9]
	global_load_dwordx4 v[112:115], v[176:177], off
	v_lshl_add_u64 v[182:183], v[178:179], 0, v[154:155]
	v_lshl_add_u64 v[184:185], v[178:179], 0, v[144:145]
	v_lshl_add_u64 v[178:179], v[178:179], 0, v[130:131]
	s_waitcnt vmcnt(5)
	v_mov_b32_e32 v162, v116
	v_mov_b32_e32 v163, v117
	v_mov_b32_e32 v164, v118
	v_mov_b32_e32 v165, v119
	v_mul_f32_e32 v133, v92, v162
	v_mul_f32_e32 v152, v93, v163
	v_mul_f32_e32 v161, v94, v164
	v_mul_f32_e32 v175, v95, v165
	v_mul_f32_e32 v186, v88, v162
	v_mul_f32_e32 v187, v89, v163
	v_mul_f32_e32 v188, v90, v164
	v_mul_f32_e32 v189, v91, v165
	v_mul_f32_e32 v190, v28, v162
	v_mul_f32_e32 v191, v29, v163
	v_mul_f32_e32 v194, v24, v162
	v_mul_f32_e32 v195, v25, v163
	v_cvt_pk_bf16_f32 v162, v133, v152
	v_cvt_pk_bf16_f32 v163, v161, v175
	v_mul_f32_e32 v192, v30, v164
	v_mul_f32_e32 v193, v31, v165
	v_mul_f32_e32 v196, v26, v164
	v_mul_f32_e32 v197, v27, v165
	v_cvt_pk_bf16_f32 v164, v186, v187
	v_cvt_pk_bf16_f32 v165, v188, v189
	v_cvt_pk_bf16_f32 v186, v190, v191
	v_cvt_pk_bf16_f32 v187, v192, v193
	v_cvt_pk_bf16_f32 v188, v194, v195
	v_cvt_pk_bf16_f32 v189, v196, v197
	global_store_dwordx2 v[180:181], v[162:163], off offset:2048
	global_store_dwordx2 v[182:183], v[164:165], off offset:2048
	global_store_dwordx2 v[184:185], v[186:187], off offset:2048
	global_store_dwordx2 v[178:179], v[188:189], off offset:2048
	v_bitop3_b32 v133, v136, s40, v166 bitop3:0xc8
	v_lshlrev_b32_e32 v152, 1, v133
	v_lshl_add_u64 v[178:179], s[12:13], 0, v[252:253]
	v_lshl_add_u64 v[180:181], v[178:179], 0, v[156:157]
	v_lshl_add_u64 v[176:177], v[138:139], 2, s[8:9]
	global_load_dwordx4 v[116:119], v[176:177], off
	v_lshl_add_u64 v[182:183], v[178:179], 0, v[154:155]
	v_lshl_add_u64 v[184:185], v[178:179], 0, v[144:145]
	v_lshl_add_u64 v[178:179], v[178:179], 0, v[130:131]
	s_waitcnt vmcnt(5)
	v_mov_b32_e32 v162, v112
	v_mov_b32_e32 v163, v113
	v_mov_b32_e32 v164, v114
	v_mov_b32_e32 v165, v115
	v_mul_f32_e32 v133, v84, v162
	v_mul_f32_e32 v152, v85, v163
	v_mul_f32_e32 v161, v86, v164
	v_mul_f32_e32 v175, v87, v165
	v_mul_f32_e32 v186, v80, v162
	v_mul_f32_e32 v187, v81, v163
	v_mul_f32_e32 v188, v82, v164
	v_mul_f32_e32 v189, v83, v165
	v_mul_f32_e32 v190, v20, v162
	v_mul_f32_e32 v191, v21, v163
	v_mul_f32_e32 v194, v16, v162
	v_mul_f32_e32 v195, v17, v163
	v_cvt_pk_bf16_f32 v162, v133, v152
	v_cvt_pk_bf16_f32 v163, v161, v175
	v_mul_f32_e32 v192, v22, v164
	v_mul_f32_e32 v193, v23, v165
	v_mul_f32_e32 v196, v18, v164
	v_mul_f32_e32 v197, v19, v165
	v_cvt_pk_bf16_f32 v164, v186, v187
	v_cvt_pk_bf16_f32 v165, v188, v189
	v_cvt_pk_bf16_f32 v186, v190, v191
	v_cvt_pk_bf16_f32 v187, v192, v193
	v_cvt_pk_bf16_f32 v188, v194, v195
	v_cvt_pk_bf16_f32 v189, v196, v197
	global_store_dwordx2 v[180:181], v[162:163], off offset:2560
	global_store_dwordx2 v[182:183], v[164:165], off offset:2560
	global_store_dwordx2 v[184:185], v[186:187], off offset:2560
	global_store_dwordx2 v[178:179], v[188:189], off offset:2560
	v_bitop3_b32 v133, v136, s41, v167 bitop3:0xc8
	v_lshlrev_b32_e32 v152, 1, v133
	v_lshl_add_u64 v[178:179], s[12:13], 0, v[252:253]
	v_lshl_add_u64 v[180:181], v[178:179], 0, v[156:157]
	v_lshl_add_u64 v[176:177], v[134:135], 2, s[8:9]
	global_load_dwordx4 v[112:115], v[176:177], off
	v_lshl_add_u64 v[182:183], v[178:179], 0, v[154:155]
	v_lshl_add_u64 v[184:185], v[178:179], 0, v[144:145]
	v_lshl_add_u64 v[178:179], v[178:179], 0, v[130:131]
	s_waitcnt vmcnt(5)
	v_mov_b32_e32 v162, v116
	v_mov_b32_e32 v163, v117
	v_mov_b32_e32 v164, v118
	v_mov_b32_e32 v165, v119
	v_mul_f32_e32 v133, v76, v162
	v_mul_f32_e32 v152, v77, v163
	v_mul_f32_e32 v161, v78, v164
	v_mul_f32_e32 v175, v79, v165
	v_mul_f32_e32 v186, v72, v162
	v_mul_f32_e32 v187, v73, v163
	v_mul_f32_e32 v188, v74, v164
	v_mul_f32_e32 v189, v75, v165
	v_mul_f32_e32 v190, v12, v162
	v_mul_f32_e32 v191, v13, v163
	v_mul_f32_e32 v194, v8, v162
	v_mul_f32_e32 v195, v9, v163
	v_cvt_pk_bf16_f32 v162, v133, v152
	v_cvt_pk_bf16_f32 v163, v161, v175
	v_mul_f32_e32 v192, v14, v164
	v_mul_f32_e32 v193, v15, v165
	v_mul_f32_e32 v196, v10, v164
	v_mul_f32_e32 v197, v11, v165
	v_cvt_pk_bf16_f32 v164, v186, v187
	v_cvt_pk_bf16_f32 v165, v188, v189
	v_cvt_pk_bf16_f32 v186, v190, v191
	v_cvt_pk_bf16_f32 v187, v192, v193
	v_cvt_pk_bf16_f32 v188, v194, v195
	v_cvt_pk_bf16_f32 v189, v196, v197
	global_store_dwordx2 v[180:181], v[162:163], off offset:3072
	global_store_dwordx2 v[182:183], v[164:165], off offset:3072
	global_store_dwordx2 v[184:185], v[186:187], off offset:3072
	global_store_dwordx2 v[178:179], v[188:189], off offset:3072
	v_bitop3_b32 v133, v136, s42, v168 bitop3:0xc8
	v_lshlrev_b32_e32 v152, 1, v133
	v_lshl_add_u64 v[176:177], s[12:13], 0, v[252:253]
	v_lshl_add_u64 v[156:157], v[176:177], 0, v[156:157]
	v_lshl_add_u64 v[154:155], v[176:177], 0, v[154:155]
	v_lshl_add_u64 v[144:145], v[176:177], 0, v[144:145]
	v_lshl_add_u64 v[130:131], v[176:177], 0, v[130:131]
	s_waitcnt vmcnt(4)
	v_mov_b32_e32 v162, v112
	v_mov_b32_e32 v163, v113
	v_mov_b32_e32 v164, v114
	v_mov_b32_e32 v165, v115
	v_mul_f32_e32 v133, v68, v162
	v_mul_f32_e32 v152, v69, v163
	v_mul_f32_e32 v161, v70, v164
	v_mul_f32_e32 v175, v71, v165
	v_mul_f32_e32 v176, v64, v162
	v_mul_f32_e32 v177, v65, v163
	v_mul_f32_e32 v178, v66, v164
	v_mul_f32_e32 v179, v67, v165
	v_mul_f32_e32 v180, v4, v162
	v_mul_f32_e32 v181, v5, v163
	v_mul_f32_e32 v184, v0, v162
	v_mul_f32_e32 v185, v1, v163
	v_cvt_pk_bf16_f32 v162, v133, v152
	v_cvt_pk_bf16_f32 v163, v161, v175
	v_mul_f32_e32 v182, v6, v164
	v_mul_f32_e32 v183, v7, v165
	v_mul_f32_e32 v186, v2, v164
	v_mul_f32_e32 v187, v3, v165
	v_cvt_pk_bf16_f32 v164, v176, v177
	v_cvt_pk_bf16_f32 v165, v178, v179
	v_cvt_pk_bf16_f32 v176, v180, v181
	v_cvt_pk_bf16_f32 v177, v182, v183
	v_cvt_pk_bf16_f32 v178, v184, v185
	v_cvt_pk_bf16_f32 v179, v186, v187
	global_store_dwordx2 v[156:157], v[162:163], off offset:3584
	global_store_dwordx2 v[154:155], v[164:165], off offset:3584
	global_store_dwordx2 v[144:145], v[176:177], off offset:3584
	global_store_dwordx2 v[130:131], v[178:179], off offset:3584
	s_cbranch_execnz .LBB0_206
	s_branch .LBB0_212

.LBB0_503:
	ds_read_b128 v[196:199], v169 offset:32768
	ds_read_b128 v[200:203], v169 offset:33792
	ds_read_b128 v[204:207], v169 offset:34816
	ds_read_b128 v[208:211], v169 offset:35840
	ds_read_b128 v[212:215], v167
	global_load_dwordx4 v[170:173], v[170:171], off
	ds_read_b128 v[216:219], v167 offset:1024
	global_load_dwordx4 v[174:177], v[174:175], off
	ds_read_b128 v[222:225], v167 offset:2048
	global_load_dwordx4 v[178:181], v[178:179], off
	ds_read_b128 v[226:229], v167 offset:3072
	global_load_dwordx4 v[182:185], v[182:183], off
	ds_read_b128 v[230:233], v167 offset:4096
	global_load_dwordx4 v[186:189], v[186:187], off
	ds_read_b128 v[234:237], v167 offset:5120
	global_load_dwordx4 v[190:193], v[190:191], off
	ds_read_b128 v[238:241], v167 offset:6144
	ds_read_b128 v[242:245], v167 offset:7168
	s_setprio 1
	s_waitcnt lgkmcnt(7)
	v_mfma_f32_16x16x32_bf16 v[148:151], v[196:199], v[212:215], v[148:151]
	v_mfma_f32_16x16x32_bf16 v[136:139], v[200:203], v[212:215], v[136:139]
	v_mfma_f32_16x16x32_bf16 v[132:135], v[204:207], v[212:215], v[132:135]
	v_mfma_f32_16x16x32_bf16 v[128:131], v[208:211], v[212:215], v[128:131]
	s_waitcnt vmcnt(11)
	ds_write_b128 v152, v[44:47] offset:16384
	s_waitcnt lgkmcnt(7)
	v_mfma_f32_16x16x32_bf16 v[124:127], v[196:199], v[216:219], v[124:127]
	v_mfma_f32_16x16x32_bf16 v[120:123], v[200:203], v[216:219], v[120:123]
	v_mfma_f32_16x16x32_bf16 v[116:119], v[204:207], v[216:219], v[116:119]
	v_mfma_f32_16x16x32_bf16 v[112:115], v[208:211], v[216:219], v[112:115]
	s_waitcnt vmcnt(9)
	ds_write_b128 v152, v[60:63] offset:20480
	s_waitcnt lgkmcnt(7)
	v_mfma_f32_16x16x32_bf16 v[108:111], v[196:199], v[222:225], v[108:111]
	v_mfma_f32_16x16x32_bf16 v[104:107], v[200:203], v[222:225], v[104:107]
	v_mfma_f32_16x16x32_bf16 v[100:103], v[204:207], v[222:225], v[100:103]
	v_mfma_f32_16x16x32_bf16 v[96:99], v[208:211], v[222:225], v[96:99]
	s_waitcnt vmcnt(8)
	ds_write_b128 v152, v[68:71] offset:24576
	s_waitcnt lgkmcnt(7)
	v_mfma_f32_16x16x32_bf16 v[92:95], v[196:199], v[226:229], v[92:95]
	v_mfma_f32_16x16x32_bf16 v[88:91], v[200:203], v[226:229], v[88:91]
	v_mfma_f32_16x16x32_bf16 v[84:87], v[204:207], v[226:229], v[84:87]
	v_mfma_f32_16x16x32_bf16 v[80:83], v[208:211], v[226:229], v[80:83]
	s_waitcnt vmcnt(7)
	ds_write_b128 v152, v[140:143] offset:28672
	s_waitcnt lgkmcnt(7)
	v_mfma_f32_16x16x32_bf16 v[76:79], v[196:199], v[230:233], v[76:79]
	v_mfma_f32_16x16x32_bf16 v[72:75], v[200:203], v[230:233], v[72:75]
	v_mfma_f32_16x16x32_bf16 v[64:67], v[204:207], v[230:233], v[64:67]
	v_mfma_f32_16x16x32_bf16 v[56:59], v[208:211], v[230:233], v[56:59]
	s_waitcnt vmcnt(7)
	ds_write_b128 v152, v[52:55] offset:40960
	s_waitcnt lgkmcnt(7)
	v_mfma_f32_16x16x32_bf16 v[48:51], v[196:199], v[234:237], v[48:51]
	v_mfma_f32_16x16x32_bf16 v[40:43], v[200:203], v[234:237], v[40:43]
	v_mfma_f32_16x16x32_bf16 v[36:39], v[204:207], v[234:237], v[36:39]
	v_mfma_f32_16x16x32_bf16 v[32:35], v[208:211], v[234:237], v[32:35]
	s_waitcnt vmcnt(6)
	ds_write_b128 v152, v[144:147] offset:45056
	s_waitcnt lgkmcnt(7)
	v_mfma_f32_16x16x32_bf16 v[28:31], v[196:199], v[238:241], v[28:31]
	v_mfma_f32_16x16x32_bf16 v[24:27], v[200:203], v[238:241], v[24:27]
	v_mfma_f32_16x16x32_bf16 v[20:23], v[204:207], v[238:241], v[20:23]
	v_mfma_f32_16x16x32_bf16 v[16:19], v[208:211], v[238:241], v[16:19]
	s_waitcnt lgkmcnt(6)
	v_mfma_f32_16x16x32_bf16 v[12:15], v[196:199], v[242:245], v[12:15]
	v_mfma_f32_16x16x32_bf16 v[8:11], v[200:203], v[242:245], v[8:11]
	v_mfma_f32_16x16x32_bf16 v[4:7], v[204:207], v[242:245], v[4:7]
	v_mfma_f32_16x16x32_bf16 v[0:3], v[208:211], v[242:245], v[0:3]
	s_setprio 0
	s_min_u32 s14, s36, 0x380
	s_lshl_b32 s14, s14, 1
	s_mov_b32 s39, s15
	s_add_i32 s38, s14, 0xc0
	v_lshl_add_u64 v[44:45], v[154:155], 0, s[14:15]
	v_lshl_add_u64 v[52:53], v[156:157], 0, s[14:15]
	v_lshl_add_u64 v[60:61], v[158:159], 0, s[38:39]
	v_lshl_add_u64 v[68:69], v[160:161], 0, s[38:39]
	v_lshl_add_u64 v[140:141], v[162:163], 0, s[38:39]
	v_lshl_add_u64 v[144:145], v[164:165], 0, s[38:39]
	s_waitcnt lgkmcnt(0)
	s_barrier
	ds_read_b128 v[196:199], v166 offset:40960
	ds_read_b128 v[200:203], v166 offset:41984
	ds_read_b128 v[204:207], v166 offset:43008
	ds_read_b128 v[208:211], v166 offset:44032
	ds_read_b128 v[212:215], v168
	global_load_dwordx4 v[44:47], v[44:45], off offset:192
	ds_read_b128 v[216:219], v168 offset:1024
	global_load_dwordx4 v[52:55], v[52:53], off offset:192
	ds_read_b128 v[222:225], v168 offset:2048
	global_load_dwordx4 v[60:63], v[60:61], off
	ds_read_b128 v[226:229], v168 offset:3072
	global_load_dwordx4 v[68:71], v[68:69], off
	ds_read_b128 v[230:233], v168 offset:4096
	global_load_dwordx4 v[140:143], v[140:141], off
	ds_read_b128 v[234:237], v168 offset:5120
	global_load_dwordx4 v[144:147], v[144:145], off
	ds_read_b128 v[238:241], v168 offset:6144
	ds_read_b128 v[242:245], v168 offset:7168
	s_setprio 1
	s_waitcnt lgkmcnt(7)
	v_mfma_f32_16x16x32_bf16 v[148:151], v[196:199], v[212:215], v[148:151]
	v_mfma_f32_16x16x32_bf16 v[136:139], v[200:203], v[212:215], v[136:139]
	v_mfma_f32_16x16x32_bf16 v[132:135], v[204:207], v[212:215], v[132:135]
	v_mfma_f32_16x16x32_bf16 v[128:131], v[208:211], v[212:215], v[128:131]
	s_waitcnt vmcnt(11)
	ds_write_b128 v152, v[170:173]
	s_waitcnt lgkmcnt(7)
	v_mfma_f32_16x16x32_bf16 v[124:127], v[196:199], v[216:219], v[124:127]
	v_mfma_f32_16x16x32_bf16 v[120:123], v[200:203], v[216:219], v[120:123]
	v_mfma_f32_16x16x32_bf16 v[116:119], v[204:207], v[216:219], v[116:119]
	v_mfma_f32_16x16x32_bf16 v[112:115], v[208:211], v[216:219], v[112:115]
	s_waitcnt vmcnt(10)
	ds_write_b128 v152, v[174:177] offset:4096
	s_waitcnt lgkmcnt(7)
	v_mfma_f32_16x16x32_bf16 v[108:111], v[196:199], v[222:225], v[108:111]
	v_mfma_f32_16x16x32_bf16 v[104:107], v[200:203], v[222:225], v[104:107]
	v_mfma_f32_16x16x32_bf16 v[100:103], v[204:207], v[222:225], v[100:103]
	v_mfma_f32_16x16x32_bf16 v[96:99], v[208:211], v[222:225], v[96:99]
	s_waitcnt vmcnt(9)
	ds_write_b128 v152, v[178:181] offset:8192
	s_waitcnt lgkmcnt(7)
	v_mfma_f32_16x16x32_bf16 v[92:95], v[196:199], v[226:229], v[92:95]
	v_mfma_f32_16x16x32_bf16 v[88:91], v[200:203], v[226:229], v[88:91]
	v_mfma_f32_16x16x32_bf16 v[84:87], v[204:207], v[226:229], v[84:87]
	v_mfma_f32_16x16x32_bf16 v[80:83], v[208:211], v[226:229], v[80:83]
	s_waitcnt vmcnt(8)
	ds_write_b128 v152, v[182:185] offset:12288
	s_waitcnt lgkmcnt(7)
	v_mfma_f32_16x16x32_bf16 v[76:79], v[196:199], v[230:233], v[76:79]
	v_mfma_f32_16x16x32_bf16 v[72:75], v[200:203], v[230:233], v[72:75]
	v_mfma_f32_16x16x32_bf16 v[64:67], v[204:207], v[230:233], v[64:67]
	v_mfma_f32_16x16x32_bf16 v[56:59], v[208:211], v[230:233], v[56:59]
	s_waitcnt vmcnt(7)
	ds_write_b128 v152, v[186:189] offset:32768
	s_waitcnt lgkmcnt(7)
	v_mfma_f32_16x16x32_bf16 v[48:51], v[196:199], v[234:237], v[48:51]
	v_mfma_f32_16x16x32_bf16 v[40:43], v[200:203], v[234:237], v[40:43]
	v_mfma_f32_16x16x32_bf16 v[36:39], v[204:207], v[234:237], v[36:39]
	v_mfma_f32_16x16x32_bf16 v[32:35], v[208:211], v[234:237], v[32:35]
	s_waitcnt vmcnt(6)
	ds_write_b128 v152, v[190:193] offset:36864
	s_waitcnt lgkmcnt(7)
	v_mfma_f32_16x16x32_bf16 v[28:31], v[196:199], v[238:241], v[28:31]
	v_mfma_f32_16x16x32_bf16 v[24:27], v[200:203], v[238:241], v[24:27]
	v_mfma_f32_16x16x32_bf16 v[20:23], v[204:207], v[238:241], v[20:23]
	v_mfma_f32_16x16x32_bf16 v[16:19], v[208:211], v[238:241], v[16:19]
	s_waitcnt lgkmcnt(6)
	v_mfma_f32_16x16x32_bf16 v[12:15], v[196:199], v[242:245], v[12:15]
	v_mfma_f32_16x16x32_bf16 v[8:11], v[200:203], v[242:245], v[8:11]
	v_mfma_f32_16x16x32_bf16 v[4:7], v[204:207], v[242:245], v[4:7]
	v_mfma_f32_16x16x32_bf16 v[0:3], v[208:211], v[242:245], v[0:3]
	s_setprio 0
	s_add_i32 s29, s29, 2
	s_mov_b32 s36, s37
	s_add_i32 s37, s36, 64
	s_min_u32 s14, s37, 0x3e0
	s_lshl_b32 s14, s14, 1
	v_lshl_add_u64 v[170:171], v[154:155], 0, s[14:15]
	v_lshl_add_u64 v[174:175], v[158:159], 0, s[14:15]
	v_lshl_add_u64 v[178:179], v[160:161], 0, s[14:15]
	v_lshl_add_u64 v[182:183], v[162:163], 0, s[14:15]
	v_lshl_add_u64 v[186:187], v[156:157], 0, s[14:15]
	v_lshl_add_u64 v[190:191], v[164:165], 0, s[14:15]
	s_cmp_lt_u32 s29, 30
	s_waitcnt lgkmcnt(0)
	s_cbranch_scc1 .Lrot_4
	s_barrier
	s_waitcnt vmcnt(1)
	v_mov_b32_e32 v142, v220
	v_readlane_b32 s36, v254, 6
	v_and_b32_e32 v45, 0xffffff80, v142
	v_add_u32_e32 v143, s28, v45
	v_lshrrev_b32_e32 v45, 2, v142
	v_and_b32_e32 v44, 64, v142
	v_and_b32_e32 v45, 12, v45
	s_ashr_i32 s28, s33, 2
	v_or3_b32 v140, v44, v45, s35
	s_ashr_i32 s29, s28, 31
	v_ashrrev_i32_e32 v141, 31, v140
	v_readlane_b32 s44, v254, 14
	v_readlane_b32 s45, v254, 15
	s_waitcnt vmcnt(0)
	v_and_or_b32 v144, v142, 15, v143
	s_lshl_b64 s[28:29], s[28:29], 3
	v_lshl_add_u64 v[44:45], v[140:141], 2, s[44:45]
	s_add_u32 s28, s5, s28
	v_lshlrev_b64 v[140:141], 1, v[140:141]
	v_ashrrev_i32_e32 v145, 31, v144
	s_addc_u32 s29, s26, s29
	v_lshl_add_u64 v[142:143], s[70:71], 0, v[140:141]
	v_lshl_add_u64 v[146:147], v[144:145], 2, s[6:7]
	v_lshlrev_b64 v[154:155], 5, v[144:145]
	v_lshlrev_b64 v[190:191], 12, v[144:145]
	global_load_dwordx4 v[68:71], v[44:45], off
	global_load_dwordx4 v[60:63], v[44:45], off offset:64
	global_load_dwordx4 v[52:55], v[44:45], off offset:128
	s_nop 0
	global_load_dwordx4 v[44:47], v[44:45], off offset:192
	v_lshl_add_u64 v[154:155], s[28:29], 0, v[154:155]
	global_load_dword v202, v[146:147], off
	global_load_dwordx2 v[184:185], v[154:155], off
	v_lshl_add_u64 v[146:147], v[142:143], 0, v[190:191]
	global_load_dwordx2 v[196:197], v[146:147], off
	global_load_dwordx2 v[198:199], v[146:147], off offset:32
	global_load_dwordx2 v[200:201], v[146:147], off offset:64
	global_load_dwordx2 v[192:193], v[146:147], off offset:96
	v_or_b32_e32 v146, 16, v144
	v_ashrrev_i32_e32 v147, 31, v146
	v_lshlrev_b64 v[188:189], 12, v[146:147]
	v_lshl_add_u64 v[154:155], v[146:147], 2, s[6:7]
	v_lshlrev_b64 v[156:157], 5, v[146:147]
	v_lshl_add_u64 v[146:147], v[142:143], 0, v[188:189]
	v_lshl_add_u64 v[156:157], s[28:29], 0, v[156:157]
	global_load_dword v195, v[154:155], off
	global_load_dwordx2 v[172:173], v[156:157], off
	global_load_dwordx2 v[186:187], v[146:147], off
	global_load_dwordx2 v[182:183], v[146:147], off offset:32
	global_load_dwordx2 v[180:181], v[146:147], off offset:64
	global_load_dwordx2 v[178:179], v[146:147], off offset:96
	v_or_b32_e32 v146, 32, v144
	v_ashrrev_i32_e32 v147, 31, v146
	v_lshl_add_u64 v[154:155], v[146:147], 2, s[6:7]
	v_lshlrev_b64 v[156:157], 5, v[146:147]
	v_lshl_add_u64 v[156:157], s[28:29], 0, v[156:157]
	global_load_dword v152, v[154:155], off
	global_load_dwordx2 v[160:161], v[156:157], off
	v_or_b32_e32 v154, 48, v144
	v_lshlrev_b64 v[176:177], 12, v[146:147]
	v_ashrrev_i32_e32 v155, 31, v154
	v_lshl_add_u64 v[146:147], v[142:143], 0, v[176:177]
	v_lshlrev_b64 v[156:157], 5, v[154:155]
	v_lshlrev_b64 v[164:165], 12, v[154:155]
	global_load_dwordx2 v[174:175], v[146:147], off
	global_load_dwordx2 v[170:171], v[146:147], off offset:32
	global_load_dwordx2 v[168:169], v[146:147], off offset:64
	global_load_dwordx2 v[166:167], v[146:147], off offset:96
	v_lshl_add_u64 v[146:147], v[154:155], 2, s[6:7]
	v_lshl_add_u64 v[156:157], s[28:29], 0, v[156:157]
	v_lshl_add_u64 v[154:155], v[142:143], 0, v[164:165]
	global_load_dword v145, v[146:147], off
	s_nop 0
	global_load_dwordx2 v[146:147], v[156:157], off
	global_load_dwordx2 v[162:163], v[154:155], off
	global_load_dwordx2 v[158:159], v[154:155], off offset:32
	s_nop 0
	global_load_dwordx2 v[156:157], v[154:155], off offset:64
	s_nop 0
	global_load_dwordx2 v[154:155], v[154:155], off offset:96
	v_readlane_b32 s37, v254, 7
	v_readlane_b32 s38, v254, 8
	v_readlane_b32 s39, v254, 9
	v_readlane_b32 s40, v254, 10
	v_readlane_b32 s41, v254, 11
	v_readlane_b32 s42, v254, 12
	v_readlane_b32 s43, v254, 13
	v_readlane_b32 s46, v254, 16
	v_readlane_b32 s47, v254, 17
	v_readlane_b32 s48, v254, 18
	v_readlane_b32 s49, v254, 19
	v_readlane_b32 s50, v254, 20
	v_readlane_b32 s51, v254, 21
	v_lshl_add_u64 v[140:141], s[8:9], 0, v[140:141]
	s_waitcnt vmcnt(23)
	v_mul_f32_e32 v148, v148, v202
	v_mul_f32_e32 v205, 0xbfb8aa3b, v148
	v_exp_f32_e32 v205, v205
	v_mul_f32_e32 v149, v149, v202
	v_mul_f32_e32 v206, 0xbfb8aa3b, v149
	v_exp_f32_e32 v206, v206
	v_add_f32_e32 v205, 1.0, v205
	v_rcp_f32_e32 v205, v205
	s_waitcnt vmcnt(21)
	v_lshlrev_b32_e32 v203, 16, v196
	v_mul_f32_e32 v150, v150, v202
	v_sub_f32_e32 v203, v203, v184
	v_mul_f32_e32 v148, v148, v205
	v_add_f32_e32 v205, 1.0, v206
	v_rcp_f32_e32 v205, v205
	v_mul_f32_e32 v148, v148, v203
	v_mul_f32_e32 v203, 0xbfb8aa3b, v150
	v_exp_f32_e32 v203, v203
	v_and_b32_e32 v196, 0xffff0000, v196
	v_mul_f32_e32 v151, v151, v202
	v_mul_f32_e32 v149, v149, v205
	v_sub_f32_e32 v196, v196, v184
	v_mul_f32_e32 v149, v149, v196
	v_add_f32_e32 v196, 1.0, v203
	v_mul_f32_e32 v203, 0xbfb8aa3b, v151
	v_exp_f32_e32 v203, v203
	v_rcp_f32_e32 v196, v196
	v_lshlrev_b32_e32 v204, 16, v197
	v_and_b32_e32 v197, 0xffff0000, v197
	v_add_f32_e32 v203, 1.0, v203
	v_rcp_f32_e32 v203, v203
	v_mul_f32_e32 v150, v150, v196
	v_sub_f32_e32 v196, v204, v184
	v_mul_f32_e32 v150, v150, v196
	v_mul_f32_e32 v151, v151, v203
	v_sub_f32_e32 v196, v197, v184
	v_mul_f32_e32 v151, v151, v196
	v_mul_f32_e32 v148, v185, v148
	v_mul_f32_e32 v149, v185, v149
	v_mul_f32_e32 v151, v185, v151
	v_mul_f32_e32 v148, v68, v148
	v_mul_f32_e32 v149, v69, v149
	v_mul_f32_e32 v150, v185, v150
	v_mul_f32_e32 v151, v71, v151
	v_mul_f32_e32 v136, v136, v202
	v_mul_f32_e32 v150, v70, v150
	v_cvt_pk_bf16_f32 v148, v148, v149
	v_cvt_pk_bf16_f32 v149, v150, v151
	v_mul_f32_e32 v151, 0xbfb8aa3b, v136
	v_exp_f32_e32 v151, v151
	v_mul_f32_e32 v137, v137, v202
	v_mul_f32_e32 v197, 0xbfb8aa3b, v137
	v_exp_f32_e32 v197, v197
	v_add_f32_e32 v151, 1.0, v151
	v_rcp_f32_e32 v151, v151
	v_lshl_add_u64 v[190:191], v[140:141], 0, v[190:191]
	global_store_dwordx2 v[190:191], v[148:149], off
	s_waitcnt vmcnt(21)
	v_lshlrev_b32_e32 v148, 16, v198
	v_mul_f32_e32 v136, v136, v151
	v_add_f32_e32 v151, 1.0, v197
	v_rcp_f32_e32 v151, v151
	v_and_b32_e32 v149, 0xffff0000, v198
	v_mul_f32_e32 v138, v138, v202
	v_sub_f32_e32 v148, v148, v184
	v_mul_f32_e32 v139, v139, v202
	v_mul_f32_e32 v136, v136, v148
	v_mul_f32_e32 v137, v137, v151
	v_mul_f32_e32 v148, 0xbfb8aa3b, v138
	v_sub_f32_e32 v149, v149, v184
	v_exp_f32_e32 v148, v148
	v_mul_f32_e32 v137, v137, v149
	v_mul_f32_e32 v149, 0xbfb8aa3b, v139
	v_exp_f32_e32 v149, v149
	v_add_f32_e32 v148, 1.0, v148
	v_rcp_f32_e32 v148, v148
	v_lshlrev_b32_e32 v150, 16, v199
	v_add_f32_e32 v149, 1.0, v149
	v_rcp_f32_e32 v149, v149
	v_and_b32_e32 v196, 0xffff0000, v199
	v_mul_f32_e32 v138, v138, v148
	v_sub_f32_e32 v148, v150, v184
	v_mul_f32_e32 v138, v138, v148
	v_mul_f32_e32 v139, v139, v149
	v_sub_f32_e32 v148, v196, v184
	v_mul_f32_e32 v139, v139, v148
	v_mul_f32_e32 v136, v185, v136
	v_mul_f32_e32 v137, v185, v137
	v_mul_f32_e32 v139, v185, v139
	v_mul_f32_e32 v136, v60, v136
	v_mul_f32_e32 v137, v61, v137
	v_mul_f32_e32 v138, v185, v138
	v_mul_f32_e32 v139, v63, v139
	v_mul_f32_e32 v132, v132, v202
	v_mul_f32_e32 v138, v62, v138
	v_cvt_pk_bf16_f32 v136, v136, v137
	v_cvt_pk_bf16_f32 v137, v138, v139
	v_mul_f32_e32 v139, 0xbfb8aa3b, v132
	v_exp_f32_e32 v139, v139
	v_mul_f32_e32 v133, v133, v202
	v_mul_f32_e32 v149, 0xbfb8aa3b, v133
	v_exp_f32_e32 v149, v149
	v_add_f32_e32 v139, 1.0, v139
	v_rcp_f32_e32 v139, v139
	global_store_dwordx2 v[190:191], v[136:137], off offset:32
	s_waitcnt vmcnt(21)
	v_lshlrev_b32_e32 v136, 16, v200
	v_and_b32_e32 v137, 0xffff0000, v200
	v_mul_f32_e32 v132, v132, v139
	v_add_f32_e32 v139, 1.0, v149
	v_rcp_f32_e32 v139, v139
	v_mul_f32_e32 v134, v134, v202
	v_sub_f32_e32 v136, v136, v184
	v_mul_f32_e32 v135, v135, v202
	v_mul_f32_e32 v132, v132, v136
	v_mul_f32_e32 v133, v133, v139
	v_mul_f32_e32 v136, 0xbfb8aa3b, v134
	v_sub_f32_e32 v137, v137, v184
	v_exp_f32_e32 v136, v136
	v_mul_f32_e32 v133, v133, v137
	v_mul_f32_e32 v137, 0xbfb8aa3b, v135
	v_exp_f32_e32 v137, v137
	v_add_f32_e32 v136, 1.0, v136
	v_rcp_f32_e32 v136, v136
	v_lshlrev_b32_e32 v138, 16, v201
	v_add_f32_e32 v137, 1.0, v137
	v_rcp_f32_e32 v137, v137
	v_and_b32_e32 v148, 0xffff0000, v201
	v_mul_f32_e32 v134, v134, v136
	v_sub_f32_e32 v136, v138, v184
	v_mul_f32_e32 v134, v134, v136
	v_mul_f32_e32 v135, v135, v137
	v_sub_f32_e32 v136, v148, v184
	v_mul_f32_e32 v135, v135, v136
	v_mul_f32_e32 v132, v185, v132
	v_mul_f32_e32 v133, v185, v133
	v_mul_f32_e32 v135, v185, v135
	v_mul_f32_e32 v132, v52, v132
	v_mul_f32_e32 v133, v53, v133
	v_mul_f32_e32 v134, v185, v134
	v_mul_f32_e32 v135, v55, v135
	v_mul_f32_e32 v128, v128, v202
	v_mul_f32_e32 v134, v54, v134
	v_cvt_pk_bf16_f32 v132, v132, v133
	v_cvt_pk_bf16_f32 v133, v134, v135
	v_mul_f32_e32 v135, 0xbfb8aa3b, v128
	v_exp_f32_e32 v135, v135
	v_mul_f32_e32 v129, v129, v202
	v_mul_f32_e32 v137, 0xbfb8aa3b, v129
	v_exp_f32_e32 v137, v137
	v_add_f32_e32 v135, 1.0, v135
	v_rcp_f32_e32 v135, v135
	global_store_dwordx2 v[190:191], v[132:133], off offset:64
	s_waitcnt vmcnt(21)
	v_and_b32_e32 v133, 0xffff0000, v192
	v_mul_f32_e32 v131, v131, v202
	v_mul_f32_e32 v128, v128, v135
	v_add_f32_e32 v135, 1.0, v137
	v_rcp_f32_e32 v135, v135
	v_sub_f32_e32 v133, v133, v184
	v_lshlrev_b32_e32 v132, 16, v192
	v_mul_f32_e32 v130, v130, v202
	v_mul_f32_e32 v129, v129, v135
	v_mul_f32_e32 v129, v129, v133
	v_mul_f32_e32 v133, 0xbfb8aa3b, v131
	v_exp_f32_e32 v133, v133
	v_sub_f32_e32 v132, v132, v184
	v_mul_f32_e32 v128, v128, v132
	v_mul_f32_e32 v132, 0xbfb8aa3b, v130
	v_add_f32_e32 v133, 1.0, v133
	v_rcp_f32_e32 v133, v133
	s_waitcnt vmcnt(20)
	v_mul_f32_e32 v124, v124, v195
	v_exp_f32_e32 v132, v132
	v_mul_f32_e32 v125, v125, v195
	v_mul_f32_e32 v131, v131, v133
	v_mul_f32_e32 v133, 0xbfb8aa3b, v124
	v_exp_f32_e32 v133, v133
	v_add_f32_e32 v132, 1.0, v132
	v_rcp_f32_e32 v132, v132
	v_mul_f32_e32 v135, 0xbfb8aa3b, v125
	v_add_f32_e32 v133, 1.0, v133
	v_rcp_f32_e32 v133, v133
	v_exp_f32_e32 v135, v135
	v_lshlrev_b32_e32 v134, 16, v193
	v_and_b32_e32 v136, 0xffff0000, v193
	v_mul_f32_e32 v130, v130, v132
	v_sub_f32_e32 v132, v134, v184
	v_mul_f32_e32 v130, v130, v132
	v_sub_f32_e32 v132, v136, v184
	v_mul_f32_e32 v124, v124, v133
	v_add_f32_e32 v133, 1.0, v135
	v_mul_f32_e32 v128, v185, v128
	v_mul_f32_e32 v129, v185, v129
	v_mul_f32_e32 v130, v185, v130
	v_mul_f32_e32 v131, v131, v132
	v_rcp_f32_e32 v133, v133
	v_mul_f32_e32 v128, v44, v128
	v_mul_f32_e32 v129, v45, v129
	v_mul_f32_e32 v130, v46, v130
	v_mul_f32_e32 v131, v185, v131
	v_mul_f32_e32 v131, v47, v131
	v_cvt_pk_bf16_f32 v128, v128, v129
	v_cvt_pk_bf16_f32 v129, v130, v131
	s_waitcnt vmcnt(18)
	v_lshlrev_b32_e32 v130, 16, v186
	v_and_b32_e32 v131, 0xffff0000, v186
	v_mul_f32_e32 v126, v126, v195
	v_sub_f32_e32 v130, v130, v172
	v_mul_f32_e32 v127, v127, v195
	v_mul_f32_e32 v124, v124, v130
	v_mul_f32_e32 v125, v125, v133
	v_mul_f32_e32 v130, 0xbfb8aa3b, v126
	v_sub_f32_e32 v131, v131, v172
	v_exp_f32_e32 v130, v130
	v_mul_f32_e32 v125, v125, v131
	v_mul_f32_e32 v131, 0xbfb8aa3b, v127
	v_exp_f32_e32 v131, v131
	v_add_f32_e32 v130, 1.0, v130
	v_rcp_f32_e32 v130, v130
	v_lshlrev_b32_e32 v132, 16, v187
	v_add_f32_e32 v131, 1.0, v131
	v_rcp_f32_e32 v131, v131
	v_and_b32_e32 v134, 0xffff0000, v187
	v_mul_f32_e32 v126, v126, v130
	v_sub_f32_e32 v130, v132, v172
	v_mul_f32_e32 v126, v126, v130
	v_mul_f32_e32 v127, v127, v131
	v_sub_f32_e32 v130, v134, v172
	v_mul_f32_e32 v127, v127, v130
	v_mul_f32_e32 v124, v173, v124
	v_mul_f32_e32 v125, v173, v125
	v_mul_f32_e32 v127, v173, v127
	v_mul_f32_e32 v124, v68, v124
	v_mul_f32_e32 v125, v69, v125
	v_mul_f32_e32 v126, v173, v126
	v_mul_f32_e32 v127, v71, v127
	v_mul_f32_e32 v120, v120, v195
	v_mul_f32_e32 v126, v70, v126
	v_cvt_pk_bf16_f32 v124, v124, v125
	v_cvt_pk_bf16_f32 v125, v126, v127
	v_mul_f32_e32 v127, 0xbfb8aa3b, v120
	v_exp_f32_e32 v127, v127
	v_mul_f32_e32 v121, v121, v195
	v_mul_f32_e32 v131, 0xbfb8aa3b, v121
	v_exp_f32_e32 v131, v131
	v_add_f32_e32 v127, 1.0, v127
	v_rcp_f32_e32 v127, v127
	global_store_dwordx2 v[190:191], v[128:129], off offset:96
	v_lshl_add_u64 v[128:129], v[140:141], 0, v[188:189]
	global_store_dwordx2 v[128:129], v[124:125], off
	v_mul_f32_e32 v120, v120, v127
	v_add_f32_e32 v127, 1.0, v131
	v_rcp_f32_e32 v127, v127
	s_waitcnt vmcnt(19)
	v_lshlrev_b32_e32 v124, 16, v182
	v_and_b32_e32 v125, 0xffff0000, v182
	v_mul_f32_e32 v122, v122, v195
	v_sub_f32_e32 v124, v124, v172
	v_mul_f32_e32 v123, v123, v195
	v_mul_f32_e32 v120, v120, v124
	v_mul_f32_e32 v121, v121, v127
	v_mul_f32_e32 v124, 0xbfb8aa3b, v122
	v_sub_f32_e32 v125, v125, v172
	v_exp_f32_e32 v124, v124
	v_mul_f32_e32 v121, v121, v125
	v_mul_f32_e32 v125, 0xbfb8aa3b, v123
	v_exp_f32_e32 v125, v125
	v_add_f32_e32 v124, 1.0, v124
	v_rcp_f32_e32 v124, v124
	v_lshlrev_b32_e32 v126, 16, v183
	v_add_f32_e32 v125, 1.0, v125
	v_rcp_f32_e32 v125, v125
	v_and_b32_e32 v130, 0xffff0000, v183
	v_mul_f32_e32 v122, v122, v124
	v_sub_f32_e32 v124, v126, v172
	v_mul_f32_e32 v122, v122, v124
	v_mul_f32_e32 v123, v123, v125
	v_sub_f32_e32 v124, v130, v172
	v_mul_f32_e32 v123, v123, v124
	v_mul_f32_e32 v120, v173, v120
	v_mul_f32_e32 v121, v173, v121
	v_mul_f32_e32 v123, v173, v123
	v_mul_f32_e32 v120, v60, v120
	v_mul_f32_e32 v121, v61, v121
	v_mul_f32_e32 v122, v173, v122
	v_mul_f32_e32 v123, v63, v123
	v_mul_f32_e32 v116, v116, v195
	v_mul_f32_e32 v122, v62, v122
	v_cvt_pk_bf16_f32 v120, v120, v121
	v_cvt_pk_bf16_f32 v121, v122, v123
	v_mul_f32_e32 v123, 0xbfb8aa3b, v116
	v_exp_f32_e32 v123, v123
	v_mul_f32_e32 v117, v117, v195
	v_mul_f32_e32 v125, 0xbfb8aa3b, v117
	v_exp_f32_e32 v125, v125
	v_add_f32_e32 v123, 1.0, v123
	v_rcp_f32_e32 v123, v123
	global_store_dwordx2 v[128:129], v[120:121], off offset:32
	s_waitcnt vmcnt(19)
	v_lshlrev_b32_e32 v120, 16, v180
	v_and_b32_e32 v121, 0xffff0000, v180
	v_mul_f32_e32 v116, v116, v123
	v_add_f32_e32 v123, 1.0, v125
	v_rcp_f32_e32 v123, v123
	v_mul_f32_e32 v118, v118, v195
	v_sub_f32_e32 v120, v120, v172
	v_mul_f32_e32 v119, v119, v195
	v_mul_f32_e32 v116, v116, v120
	v_mul_f32_e32 v117, v117, v123
	v_mul_f32_e32 v120, 0xbfb8aa3b, v118
	v_sub_f32_e32 v121, v121, v172
	v_exp_f32_e32 v120, v120
	v_mul_f32_e32 v117, v117, v121
	v_mul_f32_e32 v121, 0xbfb8aa3b, v119
	v_exp_f32_e32 v121, v121
	v_add_f32_e32 v120, 1.0, v120
	v_rcp_f32_e32 v120, v120
	v_lshlrev_b32_e32 v122, 16, v181
	v_add_f32_e32 v121, 1.0, v121
	v_rcp_f32_e32 v121, v121
	v_and_b32_e32 v124, 0xffff0000, v181
	v_mul_f32_e32 v118, v118, v120
	v_sub_f32_e32 v120, v122, v172
	v_mul_f32_e32 v118, v118, v120
	v_mul_f32_e32 v119, v119, v121
	v_sub_f32_e32 v120, v124, v172
	v_mul_f32_e32 v119, v119, v120
	v_mul_f32_e32 v116, v173, v116
	v_mul_f32_e32 v117, v173, v117
	v_mul_f32_e32 v119, v173, v119
	v_mul_f32_e32 v116, v52, v116
	v_mul_f32_e32 v117, v53, v117
	v_mul_f32_e32 v118, v173, v118
	v_mul_f32_e32 v119, v55, v119
	v_mul_f32_e32 v112, v112, v195
	v_mul_f32_e32 v118, v54, v118
	v_cvt_pk_bf16_f32 v116, v116, v117
	v_cvt_pk_bf16_f32 v117, v118, v119
	v_mul_f32_e32 v119, 0xbfb8aa3b, v112
	v_exp_f32_e32 v119, v119
	v_mul_f32_e32 v113, v113, v195
	v_mul_f32_e32 v121, 0xbfb8aa3b, v113
	v_exp_f32_e32 v121, v121
	v_add_f32_e32 v119, 1.0, v119
	v_rcp_f32_e32 v119, v119
	global_store_dwordx2 v[128:129], v[116:117], off offset:64
	s_waitcnt vmcnt(19)
	v_and_b32_e32 v117, 0xffff0000, v178
	v_mul_f32_e32 v115, v115, v195
	v_mul_f32_e32 v112, v112, v119
	v_add_f32_e32 v119, 1.0, v121
	v_rcp_f32_e32 v119, v119
	v_sub_f32_e32 v117, v117, v172
	v_lshlrev_b32_e32 v116, 16, v178
	v_mul_f32_e32 v114, v114, v195
	v_mul_f32_e32 v113, v113, v119
	v_mul_f32_e32 v113, v113, v117
	v_mul_f32_e32 v117, 0xbfb8aa3b, v115
	v_exp_f32_e32 v117, v117
	v_sub_f32_e32 v116, v116, v172
	v_mul_f32_e32 v112, v112, v116
	v_mul_f32_e32 v116, 0xbfb8aa3b, v114
	v_add_f32_e32 v117, 1.0, v117
	v_rcp_f32_e32 v117, v117
	s_waitcnt vmcnt(18)
	v_mul_f32_e32 v108, v108, v152
	v_exp_f32_e32 v116, v116
	v_mul_f32_e32 v109, v109, v152
	v_mul_f32_e32 v115, v115, v117
	v_mul_f32_e32 v117, 0xbfb8aa3b, v108
	v_exp_f32_e32 v117, v117
	v_add_f32_e32 v116, 1.0, v116
	v_rcp_f32_e32 v116, v116
	v_mul_f32_e32 v119, 0xbfb8aa3b, v109
	v_add_f32_e32 v117, 1.0, v117
	v_rcp_f32_e32 v117, v117
	v_exp_f32_e32 v119, v119
	v_lshlrev_b32_e32 v118, 16, v179
	v_and_b32_e32 v120, 0xffff0000, v179
	v_mul_f32_e32 v114, v114, v116
	v_sub_f32_e32 v116, v118, v172
	v_mul_f32_e32 v114, v114, v116
	v_sub_f32_e32 v116, v120, v172
	v_mul_f32_e32 v108, v108, v117
	v_add_f32_e32 v117, 1.0, v119
	v_mul_f32_e32 v112, v173, v112
	v_mul_f32_e32 v113, v173, v113
	v_mul_f32_e32 v114, v173, v114
	v_mul_f32_e32 v115, v115, v116
	v_rcp_f32_e32 v117, v117
	v_mul_f32_e32 v112, v44, v112
	v_mul_f32_e32 v113, v45, v113
	v_mul_f32_e32 v114, v46, v114
	v_mul_f32_e32 v115, v173, v115
	v_mul_f32_e32 v115, v47, v115
	v_cvt_pk_bf16_f32 v112, v112, v113
	v_cvt_pk_bf16_f32 v113, v114, v115
	s_waitcnt vmcnt(16)
	v_lshlrev_b32_e32 v114, 16, v174
	v_and_b32_e32 v115, 0xffff0000, v174
	v_mul_f32_e32 v110, v110, v152
	v_sub_f32_e32 v114, v114, v160
	v_mul_f32_e32 v111, v111, v152
	v_mul_f32_e32 v108, v108, v114
	v_mul_f32_e32 v109, v109, v117
	v_mul_f32_e32 v114, 0xbfb8aa3b, v110
	v_sub_f32_e32 v115, v115, v160
	v_exp_f32_e32 v114, v114
	v_mul_f32_e32 v109, v109, v115
	v_mul_f32_e32 v115, 0xbfb8aa3b, v111
	v_exp_f32_e32 v115, v115
	v_add_f32_e32 v114, 1.0, v114
	v_rcp_f32_e32 v114, v114
	v_lshlrev_b32_e32 v116, 16, v175
	v_add_f32_e32 v115, 1.0, v115
	v_rcp_f32_e32 v115, v115
	v_and_b32_e32 v118, 0xffff0000, v175
	v_mul_f32_e32 v110, v110, v114
	v_sub_f32_e32 v114, v116, v160
	v_mul_f32_e32 v110, v110, v114
	v_mul_f32_e32 v111, v111, v115
	v_sub_f32_e32 v114, v118, v160
	v_mul_f32_e32 v111, v111, v114
	v_mul_f32_e32 v108, v161, v108
	v_mul_f32_e32 v109, v161, v109
	v_mul_f32_e32 v111, v161, v111
	v_mul_f32_e32 v108, v68, v108
	v_mul_f32_e32 v109, v69, v109
	v_mul_f32_e32 v110, v161, v110
	v_mul_f32_e32 v111, v71, v111
	v_mul_f32_e32 v104, v104, v152
	v_mul_f32_e32 v110, v70, v110
	v_cvt_pk_bf16_f32 v108, v108, v109
	v_cvt_pk_bf16_f32 v109, v110, v111
	v_mul_f32_e32 v111, 0xbfb8aa3b, v104
	v_exp_f32_e32 v111, v111
	v_mul_f32_e32 v105, v105, v152
	v_mul_f32_e32 v115, 0xbfb8aa3b, v105
	v_exp_f32_e32 v115, v115
	v_add_f32_e32 v111, 1.0, v111
	v_rcp_f32_e32 v111, v111
	global_store_dwordx2 v[128:129], v[112:113], off offset:96
	v_lshl_add_u64 v[112:113], v[140:141], 0, v[176:177]
	global_store_dwordx2 v[112:113], v[108:109], off
	v_mul_f32_e32 v104, v104, v111
	v_add_f32_e32 v111, 1.0, v115
	v_rcp_f32_e32 v111, v111
	s_waitcnt vmcnt(17)
	v_lshlrev_b32_e32 v108, 16, v170
	v_and_b32_e32 v109, 0xffff0000, v170
	v_mul_f32_e32 v106, v106, v152
	v_sub_f32_e32 v108, v108, v160
	v_mul_f32_e32 v107, v107, v152
	v_mul_f32_e32 v104, v104, v108
	v_mul_f32_e32 v105, v105, v111
	v_mul_f32_e32 v108, 0xbfb8aa3b, v106
	v_sub_f32_e32 v109, v109, v160
	v_exp_f32_e32 v108, v108
	v_mul_f32_e32 v105, v105, v109
	v_mul_f32_e32 v109, 0xbfb8aa3b, v107
	v_exp_f32_e32 v109, v109
	v_add_f32_e32 v108, 1.0, v108
	v_rcp_f32_e32 v108, v108
	v_lshlrev_b32_e32 v110, 16, v171
	v_add_f32_e32 v109, 1.0, v109
	v_rcp_f32_e32 v109, v109
	v_and_b32_e32 v114, 0xffff0000, v171
	v_mul_f32_e32 v106, v106, v108
	v_sub_f32_e32 v108, v110, v160
	v_mul_f32_e32 v106, v106, v108
	v_mul_f32_e32 v107, v107, v109
	v_sub_f32_e32 v108, v114, v160
	v_mul_f32_e32 v107, v107, v108
	v_mul_f32_e32 v104, v161, v104
	v_mul_f32_e32 v105, v161, v105
	v_mul_f32_e32 v107, v161, v107
	v_mul_f32_e32 v104, v60, v104
	v_mul_f32_e32 v105, v61, v105
	v_mul_f32_e32 v106, v161, v106
	v_mul_f32_e32 v107, v63, v107
	v_mul_f32_e32 v100, v100, v152
	v_mul_f32_e32 v106, v62, v106
	v_cvt_pk_bf16_f32 v104, v104, v105
	v_cvt_pk_bf16_f32 v105, v106, v107
	v_mul_f32_e32 v107, 0xbfb8aa3b, v100
	v_exp_f32_e32 v107, v107
	v_mul_f32_e32 v101, v101, v152
	v_mul_f32_e32 v109, 0xbfb8aa3b, v101
	v_exp_f32_e32 v109, v109
	v_add_f32_e32 v107, 1.0, v107
	v_rcp_f32_e32 v107, v107
	global_store_dwordx2 v[112:113], v[104:105], off offset:32
	s_waitcnt vmcnt(17)
	v_lshlrev_b32_e32 v104, 16, v168
	v_and_b32_e32 v105, 0xffff0000, v168
	v_mul_f32_e32 v100, v100, v107
	v_add_f32_e32 v107, 1.0, v109
	v_rcp_f32_e32 v107, v107
	v_mul_f32_e32 v102, v102, v152
	v_sub_f32_e32 v104, v104, v160
	v_mul_f32_e32 v103, v103, v152
	v_mul_f32_e32 v100, v100, v104
	v_mul_f32_e32 v101, v101, v107
	v_mul_f32_e32 v104, 0xbfb8aa3b, v102
	v_sub_f32_e32 v105, v105, v160
	v_exp_f32_e32 v104, v104
	v_mul_f32_e32 v101, v101, v105
	v_mul_f32_e32 v105, 0xbfb8aa3b, v103
	v_exp_f32_e32 v105, v105
	v_add_f32_e32 v104, 1.0, v104
	v_rcp_f32_e32 v104, v104
	v_lshlrev_b32_e32 v106, 16, v169
	v_add_f32_e32 v105, 1.0, v105
	v_rcp_f32_e32 v105, v105
	v_and_b32_e32 v108, 0xffff0000, v169
	v_mul_f32_e32 v102, v102, v104
	v_sub_f32_e32 v104, v106, v160
	v_mul_f32_e32 v102, v102, v104
	v_mul_f32_e32 v103, v103, v105
	v_sub_f32_e32 v104, v108, v160
	v_mul_f32_e32 v103, v103, v104
	v_mul_f32_e32 v100, v161, v100
	v_mul_f32_e32 v101, v161, v101
	v_mul_f32_e32 v103, v161, v103
	v_mul_f32_e32 v100, v52, v100
	v_mul_f32_e32 v101, v53, v101
	v_mul_f32_e32 v102, v161, v102
	v_mul_f32_e32 v103, v55, v103
	v_mul_f32_e32 v96, v96, v152
	v_mul_f32_e32 v102, v54, v102
	v_cvt_pk_bf16_f32 v100, v100, v101
	v_cvt_pk_bf16_f32 v101, v102, v103
	v_mul_f32_e32 v103, 0xbfb8aa3b, v96
	v_exp_f32_e32 v103, v103
	v_mul_f32_e32 v97, v97, v152
	v_mul_f32_e32 v105, 0xbfb8aa3b, v97
	v_exp_f32_e32 v105, v105
	v_add_f32_e32 v103, 1.0, v103
	v_rcp_f32_e32 v103, v103
	global_store_dwordx2 v[112:113], v[100:101], off offset:64
	s_waitcnt vmcnt(17)
	v_and_b32_e32 v101, 0xffff0000, v166
	v_mul_f32_e32 v99, v99, v152
	v_mul_f32_e32 v96, v96, v103
	v_add_f32_e32 v103, 1.0, v105
	v_rcp_f32_e32 v103, v103
	v_sub_f32_e32 v101, v101, v160
	v_lshlrev_b32_e32 v100, 16, v166
	v_mul_f32_e32 v98, v98, v152
	v_mul_f32_e32 v97, v97, v103
	v_mul_f32_e32 v97, v97, v101
	v_mul_f32_e32 v101, 0xbfb8aa3b, v99
	v_exp_f32_e32 v101, v101
	v_sub_f32_e32 v100, v100, v160
	v_mul_f32_e32 v96, v96, v100
	v_mul_f32_e32 v100, 0xbfb8aa3b, v98
	v_add_f32_e32 v101, 1.0, v101
	v_rcp_f32_e32 v101, v101
	s_waitcnt vmcnt(16)
	v_mul_f32_e32 v92, v92, v145
	v_exp_f32_e32 v100, v100
	v_mul_f32_e32 v93, v93, v145
	v_mul_f32_e32 v99, v99, v101
	v_mul_f32_e32 v101, 0xbfb8aa3b, v92
	v_exp_f32_e32 v101, v101
	v_add_f32_e32 v100, 1.0, v100
	v_rcp_f32_e32 v100, v100
	v_mul_f32_e32 v103, 0xbfb8aa3b, v93
	v_add_f32_e32 v101, 1.0, v101
	v_rcp_f32_e32 v101, v101
	v_exp_f32_e32 v103, v103
	v_lshlrev_b32_e32 v102, 16, v167
	v_and_b32_e32 v104, 0xffff0000, v167
	v_mul_f32_e32 v98, v98, v100
	v_sub_f32_e32 v100, v102, v160
	v_mul_f32_e32 v98, v98, v100
	v_sub_f32_e32 v100, v104, v160
	v_mul_f32_e32 v92, v92, v101
	v_add_f32_e32 v101, 1.0, v103
	v_mul_f32_e32 v96, v161, v96
	v_mul_f32_e32 v97, v161, v97
	v_mul_f32_e32 v98, v161, v98
	v_mul_f32_e32 v99, v99, v100
	v_rcp_f32_e32 v101, v101
	v_mul_f32_e32 v96, v44, v96
	v_mul_f32_e32 v97, v45, v97
	v_mul_f32_e32 v98, v46, v98
	v_mul_f32_e32 v99, v161, v99
	v_mul_f32_e32 v99, v47, v99
	v_cvt_pk_bf16_f32 v96, v96, v97
	v_cvt_pk_bf16_f32 v97, v98, v99
	s_waitcnt vmcnt(14)
	v_lshlrev_b32_e32 v98, 16, v162
	v_and_b32_e32 v99, 0xffff0000, v162
	v_mul_f32_e32 v94, v94, v145
	v_sub_f32_e32 v98, v98, v146
	v_mul_f32_e32 v95, v95, v145
	v_mul_f32_e32 v92, v92, v98
	v_mul_f32_e32 v93, v93, v101
	v_mul_f32_e32 v98, 0xbfb8aa3b, v94
	v_sub_f32_e32 v99, v99, v146
	v_exp_f32_e32 v98, v98
	v_mul_f32_e32 v93, v93, v99
	v_mul_f32_e32 v99, 0xbfb8aa3b, v95
	v_exp_f32_e32 v99, v99
	v_add_f32_e32 v98, 1.0, v98
	v_rcp_f32_e32 v98, v98
	v_lshlrev_b32_e32 v100, 16, v163
	v_add_f32_e32 v99, 1.0, v99
	v_rcp_f32_e32 v99, v99
	v_and_b32_e32 v102, 0xffff0000, v163
	v_mul_f32_e32 v94, v94, v98
	v_sub_f32_e32 v98, v100, v146
	v_mul_f32_e32 v94, v94, v98
	v_mul_f32_e32 v95, v95, v99
	v_sub_f32_e32 v98, v102, v146
	v_mul_f32_e32 v95, v95, v98
	v_mul_f32_e32 v92, v147, v92
	v_mul_f32_e32 v93, v147, v93
	v_mul_f32_e32 v95, v147, v95
	v_mul_f32_e32 v92, v68, v92
	v_mul_f32_e32 v93, v69, v93
	v_mul_f32_e32 v94, v147, v94
	v_mul_f32_e32 v95, v71, v95
	v_mul_f32_e32 v88, v88, v145
	v_mul_f32_e32 v94, v70, v94
	v_cvt_pk_bf16_f32 v92, v92, v93
	v_cvt_pk_bf16_f32 v93, v94, v95
	v_mul_f32_e32 v95, 0xbfb8aa3b, v88
	v_exp_f32_e32 v95, v95
	v_mul_f32_e32 v89, v89, v145
	v_mul_f32_e32 v99, 0xbfb8aa3b, v89
	v_exp_f32_e32 v99, v99
	v_add_f32_e32 v95, 1.0, v95
	v_rcp_f32_e32 v95, v95
	global_store_dwordx2 v[112:113], v[96:97], off offset:96
	v_lshl_add_u64 v[96:97], v[140:141], 0, v[164:165]
	global_store_dwordx2 v[96:97], v[92:93], off
	v_mul_f32_e32 v88, v88, v95
	v_add_f32_e32 v95, 1.0, v99
	v_rcp_f32_e32 v95, v95
	s_waitcnt vmcnt(15)
	v_lshlrev_b32_e32 v92, 16, v158
	v_and_b32_e32 v93, 0xffff0000, v158
	v_mul_f32_e32 v90, v90, v145
	v_sub_f32_e32 v92, v92, v146
	v_mul_f32_e32 v91, v91, v145
	v_mul_f32_e32 v88, v88, v92
	v_mul_f32_e32 v89, v89, v95
	v_mul_f32_e32 v92, 0xbfb8aa3b, v90
	v_sub_f32_e32 v93, v93, v146
	v_exp_f32_e32 v92, v92
	v_mul_f32_e32 v89, v89, v93
	v_mul_f32_e32 v93, 0xbfb8aa3b, v91
	v_exp_f32_e32 v93, v93
	v_add_f32_e32 v92, 1.0, v92
	v_rcp_f32_e32 v92, v92
	v_lshlrev_b32_e32 v94, 16, v159
	v_add_f32_e32 v93, 1.0, v93
	v_rcp_f32_e32 v93, v93
	v_and_b32_e32 v98, 0xffff0000, v159
	v_mul_f32_e32 v90, v90, v92
	v_sub_f32_e32 v92, v94, v146
	v_mul_f32_e32 v90, v90, v92
	v_mul_f32_e32 v91, v91, v93
	v_sub_f32_e32 v92, v98, v146
	v_mul_f32_e32 v91, v91, v92
	v_mul_f32_e32 v88, v147, v88
	v_mul_f32_e32 v89, v147, v89
	v_mul_f32_e32 v91, v147, v91
	v_mul_f32_e32 v88, v60, v88
	v_mul_f32_e32 v89, v61, v89
	v_mul_f32_e32 v90, v147, v90
	v_mul_f32_e32 v91, v63, v91
	v_mul_f32_e32 v84, v84, v145
	v_mul_f32_e32 v90, v62, v90
	v_cvt_pk_bf16_f32 v88, v88, v89
	v_cvt_pk_bf16_f32 v89, v90, v91
	v_mul_f32_e32 v91, 0xbfb8aa3b, v84
	v_exp_f32_e32 v91, v91
	v_mul_f32_e32 v85, v85, v145
	v_mul_f32_e32 v93, 0xbfb8aa3b, v85
	v_exp_f32_e32 v93, v93
	v_add_f32_e32 v91, 1.0, v91
	v_rcp_f32_e32 v91, v91
	global_store_dwordx2 v[96:97], v[88:89], off offset:32
	s_waitcnt vmcnt(15)
	v_lshlrev_b32_e32 v88, 16, v156
	v_and_b32_e32 v89, 0xffff0000, v156
	v_mul_f32_e32 v84, v84, v91
	v_add_f32_e32 v91, 1.0, v93
	v_rcp_f32_e32 v91, v91
	v_mul_f32_e32 v86, v86, v145
	v_sub_f32_e32 v88, v88, v146
	v_mul_f32_e32 v87, v87, v145
	v_mul_f32_e32 v84, v84, v88
	v_mul_f32_e32 v85, v85, v91
	v_mul_f32_e32 v88, 0xbfb8aa3b, v86
	v_sub_f32_e32 v89, v89, v146
	v_exp_f32_e32 v88, v88
	v_mul_f32_e32 v85, v85, v89
	v_mul_f32_e32 v89, 0xbfb8aa3b, v87
	v_exp_f32_e32 v89, v89
	v_add_f32_e32 v88, 1.0, v88
	v_rcp_f32_e32 v88, v88
	v_lshlrev_b32_e32 v90, 16, v157
	v_add_f32_e32 v89, 1.0, v89
	v_rcp_f32_e32 v89, v89
	v_and_b32_e32 v92, 0xffff0000, v157
	v_mul_f32_e32 v86, v86, v88
	v_sub_f32_e32 v88, v90, v146
	v_mul_f32_e32 v86, v86, v88
	v_mul_f32_e32 v87, v87, v89
	v_sub_f32_e32 v88, v92, v146
	v_mul_f32_e32 v87, v87, v88
	v_mul_f32_e32 v84, v147, v84
	v_mul_f32_e32 v85, v147, v85
	v_mul_f32_e32 v87, v147, v87
	v_mul_f32_e32 v84, v52, v84
	v_mul_f32_e32 v85, v53, v85
	v_mul_f32_e32 v86, v147, v86
	v_mul_f32_e32 v87, v55, v87
	v_mul_f32_e32 v80, v80, v145
	v_mul_f32_e32 v86, v54, v86
	v_cvt_pk_bf16_f32 v84, v84, v85
	v_cvt_pk_bf16_f32 v85, v86, v87
	v_mul_f32_e32 v87, 0xbfb8aa3b, v80
	v_exp_f32_e32 v87, v87
	v_mul_f32_e32 v81, v81, v145
	v_mul_f32_e32 v89, 0xbfb8aa3b, v81
	v_exp_f32_e32 v89, v89
	v_add_f32_e32 v87, 1.0, v87
	v_rcp_f32_e32 v87, v87
	global_store_dwordx2 v[96:97], v[84:85], off offset:64
	s_waitcnt vmcnt(15)
	v_lshlrev_b32_e32 v84, 16, v154
	v_and_b32_e32 v85, 0xffff0000, v154
	v_mul_f32_e32 v80, v80, v87
	v_add_f32_e32 v87, 1.0, v89
	v_rcp_f32_e32 v87, v87
	v_mul_f32_e32 v82, v82, v145
	v_sub_f32_e32 v84, v84, v146
	v_mul_f32_e32 v83, v83, v145
	v_mul_f32_e32 v80, v80, v84
	v_mul_f32_e32 v81, v81, v87
	v_mul_f32_e32 v84, 0xbfb8aa3b, v82
	v_sub_f32_e32 v85, v85, v146
	v_exp_f32_e32 v84, v84
	v_mul_f32_e32 v81, v81, v85
	v_mul_f32_e32 v85, 0xbfb8aa3b, v83
	v_exp_f32_e32 v85, v85
	v_add_f32_e32 v84, 1.0, v84
	v_rcp_f32_e32 v84, v84
	v_lshlrev_b32_e32 v86, 16, v155
	v_add_f32_e32 v85, 1.0, v85
	v_rcp_f32_e32 v85, v85
	v_and_b32_e32 v88, 0xffff0000, v155
	v_mul_f32_e32 v82, v82, v84
	v_sub_f32_e32 v84, v86, v146
	v_mul_f32_e32 v82, v82, v84
	v_mul_f32_e32 v83, v83, v85
	v_sub_f32_e32 v84, v88, v146
	v_mul_f32_e32 v80, v147, v80
	v_mul_f32_e32 v81, v147, v81
	v_mul_f32_e32 v83, v83, v84
	v_mul_f32_e32 v80, v44, v80
	v_mul_f32_e32 v81, v45, v81
	v_mul_f32_e32 v82, v147, v82
	v_mul_f32_e32 v83, v147, v83
	v_mul_f32_e32 v82, v46, v82
	v_mul_f32_e32 v83, v47, v83
	v_cvt_pk_bf16_f32 v80, v80, v81
	v_cvt_pk_bf16_f32 v81, v82, v83
	global_store_dwordx2 v[96:97], v[80:81], off offset:96
	v_or_b32_e32 v80, 64, v144
	v_ashrrev_i32_e32 v81, 31, v80
	v_lshlrev_b64 v[118:119], 12, v[80:81]
	v_lshl_add_u64 v[82:83], v[80:81], 2, s[6:7]
	v_lshlrev_b64 v[84:85], 5, v[80:81]
	v_lshl_add_u64 v[80:81], v[142:143], 0, v[118:119]
	v_lshl_add_u64 v[84:85], s[28:29], 0, v[84:85]
	global_load_dword v125, v[82:83], off
	global_load_dwordx2 v[112:113], v[84:85], off
	global_load_dwordx2 v[126:127], v[80:81], off
	global_load_dwordx2 v[128:129], v[80:81], off offset:32
	global_load_dwordx2 v[130:131], v[80:81], off offset:64
	global_load_dwordx2 v[120:121], v[80:81], off offset:96
	v_or_b32_e32 v80, 0x50, v144
	v_ashrrev_i32_e32 v81, 31, v80
	v_lshlrev_b64 v[116:117], 12, v[80:81]
	v_lshl_add_u64 v[82:83], v[80:81], 2, s[6:7]
	v_lshlrev_b64 v[84:85], 5, v[80:81]
	v_lshl_add_u64 v[80:81], v[142:143], 0, v[116:117]
	v_lshl_add_u64 v[84:85], s[28:29], 0, v[84:85]
	global_load_dword v124, v[82:83], off
	global_load_dwordx2 v[100:101], v[84:85], off
	global_load_dwordx2 v[114:115], v[80:81], off
	global_load_dwordx2 v[110:111], v[80:81], off offset:32
	global_load_dwordx2 v[108:109], v[80:81], off offset:64
	global_load_dwordx2 v[106:107], v[80:81], off offset:96
	v_or_b32_e32 v80, 0x60, v144
	v_ashrrev_i32_e32 v81, 31, v80
	v_lshl_add_u64 v[82:83], v[80:81], 2, s[6:7]
	v_lshlrev_b64 v[84:85], 5, v[80:81]
	v_lshl_add_u64 v[84:85], s[28:29], 0, v[84:85]
	global_load_dword v123, v[82:83], off
	global_load_dwordx2 v[88:89], v[84:85], off
	v_or_b32_e32 v82, 0x70, v144
	v_lshlrev_b64 v[104:105], 12, v[80:81]
	v_ashrrev_i32_e32 v83, 31, v82
	v_lshl_add_u64 v[80:81], v[142:143], 0, v[104:105]
	v_lshlrev_b64 v[84:85], 5, v[82:83]
	v_lshlrev_b64 v[92:93], 12, v[82:83]
	global_load_dwordx2 v[102:103], v[80:81], off
	global_load_dwordx2 v[98:99], v[80:81], off offset:32
	global_load_dwordx2 v[96:97], v[80:81], off offset:64
	global_load_dwordx2 v[94:95], v[80:81], off offset:96
	v_lshl_add_u64 v[80:81], v[82:83], 2, s[6:7]
	v_lshl_add_u64 v[84:85], s[28:29], 0, v[84:85]
	v_lshl_add_u64 v[82:83], v[142:143], 0, v[92:93]
	global_load_dword v122, v[80:81], off
	s_nop 0
	global_load_dwordx2 v[80:81], v[84:85], off
	global_load_dwordx2 v[90:91], v[82:83], off
	global_load_dwordx2 v[86:87], v[82:83], off offset:32
	s_nop 0
	global_load_dwordx2 v[84:85], v[82:83], off offset:64
	s_nop 0
	global_load_dwordx2 v[82:83], v[82:83], off offset:96
	s_waitcnt vmcnt(23)
	v_mul_f32_e32 v76, v76, v125
	v_mul_f32_e32 v134, 0xbfb8aa3b, v76
	v_exp_f32_e32 v134, v134
	v_mul_f32_e32 v77, v77, v125
	v_mul_f32_e32 v135, 0xbfb8aa3b, v77
	v_exp_f32_e32 v135, v135
	v_add_f32_e32 v134, 1.0, v134
	v_rcp_f32_e32 v134, v134
	s_waitcnt vmcnt(21)
	v_lshlrev_b32_e32 v132, 16, v126
	v_mul_f32_e32 v78, v78, v125
	v_sub_f32_e32 v132, v132, v112
	v_mul_f32_e32 v76, v76, v134
	v_add_f32_e32 v134, 1.0, v135
	v_rcp_f32_e32 v134, v134
	v_mul_f32_e32 v76, v76, v132
	v_mul_f32_e32 v132, 0xbfb8aa3b, v78
	v_exp_f32_e32 v132, v132
	v_and_b32_e32 v126, 0xffff0000, v126
	v_mul_f32_e32 v79, v79, v125
	v_mul_f32_e32 v77, v77, v134
	v_sub_f32_e32 v126, v126, v112
	v_mul_f32_e32 v77, v77, v126
	v_add_f32_e32 v126, 1.0, v132
	v_mul_f32_e32 v132, 0xbfb8aa3b, v79
	v_exp_f32_e32 v132, v132
	v_rcp_f32_e32 v126, v126
	v_lshlrev_b32_e32 v133, 16, v127
	v_and_b32_e32 v127, 0xffff0000, v127
	v_add_f32_e32 v132, 1.0, v132
	v_rcp_f32_e32 v132, v132
	v_mul_f32_e32 v78, v78, v126
	v_sub_f32_e32 v126, v133, v112
	v_mul_f32_e32 v78, v78, v126
	v_mul_f32_e32 v79, v79, v132
	v_sub_f32_e32 v126, v127, v112
	v_mul_f32_e32 v79, v79, v126
	v_mul_f32_e32 v76, v113, v76
	v_mul_f32_e32 v77, v113, v77
	v_mul_f32_e32 v79, v113, v79
	v_mul_f32_e32 v76, v68, v76
	v_mul_f32_e32 v77, v69, v77
	v_mul_f32_e32 v78, v113, v78
	v_mul_f32_e32 v79, v71, v79
	v_mul_f32_e32 v72, v72, v125
	v_mul_f32_e32 v78, v70, v78
	v_cvt_pk_bf16_f32 v76, v76, v77
	v_cvt_pk_bf16_f32 v77, v78, v79
	v_mul_f32_e32 v79, 0xbfb8aa3b, v72
	v_exp_f32_e32 v79, v79
	v_mul_f32_e32 v73, v73, v125
	v_mul_f32_e32 v127, 0xbfb8aa3b, v73
	v_exp_f32_e32 v127, v127
	v_add_f32_e32 v79, 1.0, v79
	v_rcp_f32_e32 v79, v79
	v_lshl_add_u64 v[118:119], v[140:141], 0, v[118:119]
	global_store_dwordx2 v[118:119], v[76:77], off
	s_waitcnt vmcnt(21)
	v_lshlrev_b32_e32 v76, 16, v128
	v_mul_f32_e32 v72, v72, v79
	v_add_f32_e32 v79, 1.0, v127
	v_rcp_f32_e32 v79, v79
	v_and_b32_e32 v77, 0xffff0000, v128
	v_mul_f32_e32 v74, v74, v125
	v_sub_f32_e32 v76, v76, v112
	v_mul_f32_e32 v75, v75, v125
	v_mul_f32_e32 v72, v72, v76
	v_mul_f32_e32 v73, v73, v79
	v_mul_f32_e32 v76, 0xbfb8aa3b, v74
	v_sub_f32_e32 v77, v77, v112
	v_exp_f32_e32 v76, v76
	v_mul_f32_e32 v73, v73, v77
	v_mul_f32_e32 v77, 0xbfb8aa3b, v75
	v_exp_f32_e32 v77, v77
	v_add_f32_e32 v76, 1.0, v76
	v_rcp_f32_e32 v76, v76
	v_lshlrev_b32_e32 v78, 16, v129
	v_add_f32_e32 v77, 1.0, v77
	v_rcp_f32_e32 v77, v77
	v_and_b32_e32 v126, 0xffff0000, v129
	v_mul_f32_e32 v74, v74, v76
	v_sub_f32_e32 v76, v78, v112
	v_mul_f32_e32 v74, v74, v76
	v_mul_f32_e32 v75, v75, v77
	v_sub_f32_e32 v76, v126, v112
	v_mul_f32_e32 v75, v75, v76
	v_mul_f32_e32 v72, v113, v72
	v_mul_f32_e32 v73, v113, v73
	v_mul_f32_e32 v75, v113, v75
	v_mul_f32_e32 v72, v60, v72
	v_mul_f32_e32 v73, v61, v73
	v_mul_f32_e32 v74, v113, v74
	v_mul_f32_e32 v75, v63, v75
	v_mul_f32_e32 v64, v64, v125
	v_mul_f32_e32 v74, v62, v74
	v_cvt_pk_bf16_f32 v72, v72, v73
	v_cvt_pk_bf16_f32 v73, v74, v75
	v_mul_f32_e32 v75, 0xbfb8aa3b, v64
	v_exp_f32_e32 v75, v75
	v_mul_f32_e32 v65, v65, v125
	v_mul_f32_e32 v77, 0xbfb8aa3b, v65
	v_exp_f32_e32 v77, v77
	v_add_f32_e32 v75, 1.0, v75
	v_rcp_f32_e32 v75, v75
	global_store_dwordx2 v[118:119], v[72:73], off offset:32
	s_waitcnt vmcnt(21)
	v_lshlrev_b32_e32 v72, 16, v130
	v_and_b32_e32 v73, 0xffff0000, v130
	v_mul_f32_e32 v64, v64, v75
	v_add_f32_e32 v75, 1.0, v77
	v_rcp_f32_e32 v75, v75
	v_mul_f32_e32 v66, v66, v125
	v_sub_f32_e32 v72, v72, v112
	v_mul_f32_e32 v67, v67, v125
	v_mul_f32_e32 v64, v64, v72
	v_mul_f32_e32 v65, v65, v75
	v_mul_f32_e32 v72, 0xbfb8aa3b, v66
	v_sub_f32_e32 v73, v73, v112
	v_exp_f32_e32 v72, v72
	v_mul_f32_e32 v65, v65, v73
	v_mul_f32_e32 v73, 0xbfb8aa3b, v67
	v_exp_f32_e32 v73, v73
	v_add_f32_e32 v72, 1.0, v72
	v_rcp_f32_e32 v72, v72
	v_lshlrev_b32_e32 v74, 16, v131
	v_add_f32_e32 v73, 1.0, v73
	v_rcp_f32_e32 v73, v73
	v_and_b32_e32 v76, 0xffff0000, v131
	v_mul_f32_e32 v66, v66, v72
	v_sub_f32_e32 v72, v74, v112
	v_mul_f32_e32 v66, v66, v72
	v_mul_f32_e32 v67, v67, v73
	v_sub_f32_e32 v72, v76, v112
	v_mul_f32_e32 v67, v67, v72
	v_mul_f32_e32 v64, v113, v64
	v_mul_f32_e32 v65, v113, v65
	v_mul_f32_e32 v67, v113, v67
	v_mul_f32_e32 v64, v52, v64
	v_mul_f32_e32 v65, v53, v65
	v_mul_f32_e32 v66, v113, v66
	v_mul_f32_e32 v67, v55, v67
	v_mul_f32_e32 v56, v56, v125
	v_mul_f32_e32 v66, v54, v66
	v_cvt_pk_bf16_f32 v64, v64, v65
	v_cvt_pk_bf16_f32 v65, v66, v67
	v_mul_f32_e32 v67, 0xbfb8aa3b, v56
	v_exp_f32_e32 v67, v67
	v_mul_f32_e32 v57, v57, v125
	v_mul_f32_e32 v73, 0xbfb8aa3b, v57
	v_exp_f32_e32 v73, v73
	v_add_f32_e32 v67, 1.0, v67
	v_rcp_f32_e32 v67, v67
	global_store_dwordx2 v[118:119], v[64:65], off offset:64
	s_waitcnt vmcnt(21)
	v_and_b32_e32 v65, 0xffff0000, v120
	v_mul_f32_e32 v59, v59, v125
	v_mul_f32_e32 v56, v56, v67
	v_add_f32_e32 v67, 1.0, v73
	v_rcp_f32_e32 v67, v67
	v_sub_f32_e32 v65, v65, v112
	v_lshlrev_b32_e32 v64, 16, v120
	v_mul_f32_e32 v58, v58, v125
	v_mul_f32_e32 v57, v57, v67
	v_mul_f32_e32 v57, v57, v65
	v_mul_f32_e32 v65, 0xbfb8aa3b, v59
	v_exp_f32_e32 v65, v65
	v_sub_f32_e32 v64, v64, v112
	v_mul_f32_e32 v56, v56, v64
	v_mul_f32_e32 v64, 0xbfb8aa3b, v58
	v_add_f32_e32 v65, 1.0, v65
	v_rcp_f32_e32 v65, v65
	s_waitcnt vmcnt(20)
	v_mul_f32_e32 v48, v48, v124
	v_exp_f32_e32 v64, v64
	v_mul_f32_e32 v49, v49, v124
	v_mul_f32_e32 v59, v59, v65
	v_mul_f32_e32 v65, 0xbfb8aa3b, v48
	v_exp_f32_e32 v65, v65
	v_add_f32_e32 v64, 1.0, v64
	v_rcp_f32_e32 v64, v64
	v_mul_f32_e32 v67, 0xbfb8aa3b, v49
	v_add_f32_e32 v65, 1.0, v65
	v_rcp_f32_e32 v65, v65
	v_exp_f32_e32 v67, v67
	v_lshlrev_b32_e32 v66, 16, v121
	v_and_b32_e32 v72, 0xffff0000, v121
	v_mul_f32_e32 v58, v58, v64
	v_sub_f32_e32 v64, v66, v112
	v_mul_f32_e32 v58, v58, v64
	v_sub_f32_e32 v64, v72, v112
	v_mul_f32_e32 v48, v48, v65
	v_add_f32_e32 v65, 1.0, v67
	v_mul_f32_e32 v56, v113, v56
	v_mul_f32_e32 v57, v113, v57
	v_mul_f32_e32 v58, v113, v58
	v_mul_f32_e32 v59, v59, v64
	v_rcp_f32_e32 v65, v65
	v_mul_f32_e32 v56, v44, v56
	v_mul_f32_e32 v57, v45, v57
	v_mul_f32_e32 v58, v46, v58
	v_mul_f32_e32 v59, v113, v59
	v_mul_f32_e32 v59, v47, v59
	v_cvt_pk_bf16_f32 v56, v56, v57
	v_cvt_pk_bf16_f32 v57, v58, v59
	s_waitcnt vmcnt(18)
	v_lshlrev_b32_e32 v58, 16, v114
	v_and_b32_e32 v59, 0xffff0000, v114
	v_mul_f32_e32 v50, v50, v124
	v_sub_f32_e32 v58, v58, v100
	v_mul_f32_e32 v51, v51, v124
	v_mul_f32_e32 v48, v48, v58
	v_mul_f32_e32 v49, v49, v65
	v_mul_f32_e32 v58, 0xbfb8aa3b, v50
	v_sub_f32_e32 v59, v59, v100
	v_exp_f32_e32 v58, v58
	v_mul_f32_e32 v49, v49, v59
	v_mul_f32_e32 v59, 0xbfb8aa3b, v51
	v_exp_f32_e32 v59, v59
	v_add_f32_e32 v58, 1.0, v58
	v_rcp_f32_e32 v58, v58
	v_lshlrev_b32_e32 v64, 16, v115
	v_add_f32_e32 v59, 1.0, v59
	v_rcp_f32_e32 v59, v59
	v_and_b32_e32 v66, 0xffff0000, v115
	v_mul_f32_e32 v50, v50, v58
	v_sub_f32_e32 v58, v64, v100
	v_mul_f32_e32 v50, v50, v58
	v_mul_f32_e32 v51, v51, v59
	v_sub_f32_e32 v58, v66, v100
	v_mul_f32_e32 v51, v51, v58
	v_mul_f32_e32 v48, v101, v48
	v_mul_f32_e32 v49, v101, v49
	v_mul_f32_e32 v51, v101, v51
	v_mul_f32_e32 v48, v68, v48
	v_mul_f32_e32 v49, v69, v49
	v_mul_f32_e32 v50, v101, v50
	v_mul_f32_e32 v51, v71, v51
	v_mul_f32_e32 v40, v40, v124
	v_mul_f32_e32 v50, v70, v50
	v_cvt_pk_bf16_f32 v48, v48, v49
	v_cvt_pk_bf16_f32 v49, v50, v51
	v_mul_f32_e32 v51, 0xbfb8aa3b, v40
	v_exp_f32_e32 v51, v51
	v_mul_f32_e32 v41, v41, v124
	v_mul_f32_e32 v59, 0xbfb8aa3b, v41
	v_exp_f32_e32 v59, v59
	v_add_f32_e32 v51, 1.0, v51
	v_rcp_f32_e32 v51, v51
	global_store_dwordx2 v[118:119], v[56:57], off offset:96
	v_lshl_add_u64 v[56:57], v[140:141], 0, v[116:117]
	global_store_dwordx2 v[56:57], v[48:49], off
	v_mul_f32_e32 v40, v40, v51
	v_add_f32_e32 v51, 1.0, v59
	v_rcp_f32_e32 v51, v51
	s_waitcnt vmcnt(19)
	v_lshlrev_b32_e32 v48, 16, v110
	v_and_b32_e32 v49, 0xffff0000, v110
	v_mul_f32_e32 v42, v42, v124
	v_sub_f32_e32 v48, v48, v100
	v_mul_f32_e32 v43, v43, v124
	v_mul_f32_e32 v40, v40, v48
	v_mul_f32_e32 v41, v41, v51
	v_mul_f32_e32 v48, 0xbfb8aa3b, v42
	v_sub_f32_e32 v49, v49, v100
	v_exp_f32_e32 v48, v48
	v_mul_f32_e32 v41, v41, v49
	v_mul_f32_e32 v49, 0xbfb8aa3b, v43
	v_exp_f32_e32 v49, v49
	v_add_f32_e32 v48, 1.0, v48
	v_rcp_f32_e32 v48, v48
	v_lshlrev_b32_e32 v50, 16, v111
	v_add_f32_e32 v49, 1.0, v49
	v_rcp_f32_e32 v49, v49
	v_and_b32_e32 v58, 0xffff0000, v111
	v_mul_f32_e32 v42, v42, v48
	v_sub_f32_e32 v48, v50, v100
	v_mul_f32_e32 v42, v42, v48
	v_mul_f32_e32 v43, v43, v49
	v_sub_f32_e32 v48, v58, v100
	v_mul_f32_e32 v43, v43, v48
	v_mul_f32_e32 v40, v101, v40
	v_mul_f32_e32 v41, v101, v41
	v_mul_f32_e32 v43, v101, v43
	v_mul_f32_e32 v40, v60, v40
	v_mul_f32_e32 v41, v61, v41
	v_mul_f32_e32 v42, v101, v42
	v_mul_f32_e32 v43, v63, v43
	v_mul_f32_e32 v36, v36, v124
	v_mul_f32_e32 v42, v62, v42
	v_cvt_pk_bf16_f32 v40, v40, v41
	v_cvt_pk_bf16_f32 v41, v42, v43
	v_mul_f32_e32 v43, 0xbfb8aa3b, v36
	v_exp_f32_e32 v43, v43
	v_mul_f32_e32 v37, v37, v124
	v_mul_f32_e32 v49, 0xbfb8aa3b, v37
	v_exp_f32_e32 v49, v49
	v_add_f32_e32 v43, 1.0, v43
	v_rcp_f32_e32 v43, v43
	global_store_dwordx2 v[56:57], v[40:41], off offset:32
	s_waitcnt vmcnt(19)
	v_lshlrev_b32_e32 v40, 16, v108
	v_and_b32_e32 v41, 0xffff0000, v108
	v_mul_f32_e32 v36, v36, v43
	v_add_f32_e32 v43, 1.0, v49
	v_rcp_f32_e32 v43, v43
	v_mul_f32_e32 v38, v38, v124
	v_sub_f32_e32 v40, v40, v100
	v_mul_f32_e32 v39, v39, v124
	v_mul_f32_e32 v36, v36, v40
	v_mul_f32_e32 v37, v37, v43
	v_mul_f32_e32 v40, 0xbfb8aa3b, v38
	v_sub_f32_e32 v41, v41, v100
	v_exp_f32_e32 v40, v40
	v_mul_f32_e32 v37, v37, v41
	v_mul_f32_e32 v41, 0xbfb8aa3b, v39
	v_exp_f32_e32 v41, v41
	v_add_f32_e32 v40, 1.0, v40
	v_rcp_f32_e32 v40, v40
	v_lshlrev_b32_e32 v42, 16, v109
	v_add_f32_e32 v41, 1.0, v41
	v_rcp_f32_e32 v41, v41
	v_and_b32_e32 v48, 0xffff0000, v109
	v_mul_f32_e32 v38, v38, v40
	v_sub_f32_e32 v40, v42, v100
	v_mul_f32_e32 v38, v38, v40
	v_mul_f32_e32 v39, v39, v41
	v_sub_f32_e32 v40, v48, v100
	v_mul_f32_e32 v39, v39, v40
	v_mul_f32_e32 v36, v101, v36
	v_mul_f32_e32 v37, v101, v37
	v_mul_f32_e32 v39, v101, v39
	v_mul_f32_e32 v36, v52, v36
	v_mul_f32_e32 v37, v53, v37
	v_mul_f32_e32 v38, v101, v38
	v_mul_f32_e32 v39, v55, v39
	v_mul_f32_e32 v32, v32, v124
	v_mul_f32_e32 v38, v54, v38
	v_cvt_pk_bf16_f32 v36, v36, v37
	v_cvt_pk_bf16_f32 v37, v38, v39
	v_mul_f32_e32 v39, 0xbfb8aa3b, v32
	v_exp_f32_e32 v39, v39
	v_mul_f32_e32 v33, v33, v124
	v_mul_f32_e32 v41, 0xbfb8aa3b, v33
	v_exp_f32_e32 v41, v41
	v_add_f32_e32 v39, 1.0, v39
	v_rcp_f32_e32 v39, v39
	global_store_dwordx2 v[56:57], v[36:37], off offset:64
	s_waitcnt vmcnt(19)
	v_and_b32_e32 v37, 0xffff0000, v106
	v_mul_f32_e32 v35, v35, v124
	v_mul_f32_e32 v32, v32, v39
	v_add_f32_e32 v39, 1.0, v41
	v_rcp_f32_e32 v39, v39
	v_sub_f32_e32 v37, v37, v100
	v_lshlrev_b32_e32 v36, 16, v106
	v_mul_f32_e32 v34, v34, v124
	v_mul_f32_e32 v33, v33, v39
	v_mul_f32_e32 v33, v33, v37
	v_mul_f32_e32 v37, 0xbfb8aa3b, v35
	v_exp_f32_e32 v37, v37
	v_sub_f32_e32 v36, v36, v100
	v_mul_f32_e32 v32, v32, v36
	v_mul_f32_e32 v36, 0xbfb8aa3b, v34
	v_add_f32_e32 v37, 1.0, v37
	v_rcp_f32_e32 v37, v37
	s_waitcnt vmcnt(18)
	v_mul_f32_e32 v28, v28, v123
	v_exp_f32_e32 v36, v36
	v_mul_f32_e32 v29, v29, v123
	v_mul_f32_e32 v35, v35, v37
	v_mul_f32_e32 v37, 0xbfb8aa3b, v28
	v_exp_f32_e32 v37, v37
	v_add_f32_e32 v36, 1.0, v36
	v_rcp_f32_e32 v36, v36
	v_mul_f32_e32 v39, 0xbfb8aa3b, v29
	v_add_f32_e32 v37, 1.0, v37
	v_rcp_f32_e32 v37, v37
	v_exp_f32_e32 v39, v39
	v_lshlrev_b32_e32 v38, 16, v107
	v_and_b32_e32 v40, 0xffff0000, v107
	v_mul_f32_e32 v34, v34, v36
	v_sub_f32_e32 v36, v38, v100
	v_mul_f32_e32 v34, v34, v36
	v_sub_f32_e32 v36, v40, v100
	v_mul_f32_e32 v28, v28, v37
	v_add_f32_e32 v37, 1.0, v39
	v_mul_f32_e32 v32, v101, v32
	v_mul_f32_e32 v33, v101, v33
	v_mul_f32_e32 v34, v101, v34
	v_mul_f32_e32 v35, v35, v36
	v_rcp_f32_e32 v37, v37
	v_mul_f32_e32 v32, v44, v32
	v_mul_f32_e32 v33, v45, v33
	v_mul_f32_e32 v34, v46, v34
	v_mul_f32_e32 v35, v101, v35
	v_mul_f32_e32 v35, v47, v35
	v_cvt_pk_bf16_f32 v32, v32, v33
	v_cvt_pk_bf16_f32 v33, v34, v35
	s_waitcnt vmcnt(16)
	v_lshlrev_b32_e32 v34, 16, v102
	v_and_b32_e32 v35, 0xffff0000, v102
	v_mul_f32_e32 v30, v30, v123
	v_sub_f32_e32 v34, v34, v88
	v_mul_f32_e32 v31, v31, v123
	v_mul_f32_e32 v28, v28, v34
	v_mul_f32_e32 v29, v29, v37
	v_mul_f32_e32 v34, 0xbfb8aa3b, v30
	v_sub_f32_e32 v35, v35, v88
	v_exp_f32_e32 v34, v34
	v_mul_f32_e32 v29, v29, v35
	v_mul_f32_e32 v35, 0xbfb8aa3b, v31
	v_exp_f32_e32 v35, v35
	v_add_f32_e32 v34, 1.0, v34
	v_rcp_f32_e32 v34, v34
	v_lshlrev_b32_e32 v36, 16, v103
	v_add_f32_e32 v35, 1.0, v35
	v_rcp_f32_e32 v35, v35
	v_and_b32_e32 v38, 0xffff0000, v103
	v_mul_f32_e32 v30, v30, v34
	v_sub_f32_e32 v34, v36, v88
	v_mul_f32_e32 v30, v30, v34
	v_mul_f32_e32 v31, v31, v35
	v_sub_f32_e32 v34, v38, v88
	v_mul_f32_e32 v31, v31, v34
	v_mul_f32_e32 v28, v89, v28
	v_mul_f32_e32 v29, v89, v29
	v_mul_f32_e32 v31, v89, v31
	v_mul_f32_e32 v28, v68, v28
	v_mul_f32_e32 v29, v69, v29
	v_mul_f32_e32 v30, v89, v30
	v_mul_f32_e32 v31, v71, v31
	v_mul_f32_e32 v24, v24, v123
	v_mul_f32_e32 v30, v70, v30
	v_cvt_pk_bf16_f32 v28, v28, v29
	v_cvt_pk_bf16_f32 v29, v30, v31
	v_mul_f32_e32 v31, 0xbfb8aa3b, v24
	v_exp_f32_e32 v31, v31
	v_mul_f32_e32 v25, v25, v123
	v_mul_f32_e32 v35, 0xbfb8aa3b, v25
	v_exp_f32_e32 v35, v35
	v_add_f32_e32 v31, 1.0, v31
	v_rcp_f32_e32 v31, v31
	global_store_dwordx2 v[56:57], v[32:33], off offset:96
	v_lshl_add_u64 v[32:33], v[140:141], 0, v[104:105]
	global_store_dwordx2 v[32:33], v[28:29], off
	v_mul_f32_e32 v24, v24, v31
	v_add_f32_e32 v31, 1.0, v35
	v_rcp_f32_e32 v31, v31
	s_waitcnt vmcnt(17)
	v_lshlrev_b32_e32 v28, 16, v98
	v_and_b32_e32 v29, 0xffff0000, v98
	v_mul_f32_e32 v26, v26, v123
	v_sub_f32_e32 v28, v28, v88
	v_mul_f32_e32 v27, v27, v123
	v_mul_f32_e32 v24, v24, v28
	v_mul_f32_e32 v25, v25, v31
	v_mul_f32_e32 v28, 0xbfb8aa3b, v26
	v_sub_f32_e32 v29, v29, v88
	v_exp_f32_e32 v28, v28
	v_mul_f32_e32 v25, v25, v29
	v_mul_f32_e32 v29, 0xbfb8aa3b, v27
	v_exp_f32_e32 v29, v29
	v_add_f32_e32 v28, 1.0, v28
	v_rcp_f32_e32 v28, v28
	v_lshlrev_b32_e32 v30, 16, v99
	v_add_f32_e32 v29, 1.0, v29
	v_rcp_f32_e32 v29, v29
	v_and_b32_e32 v34, 0xffff0000, v99
	v_mul_f32_e32 v26, v26, v28
	v_sub_f32_e32 v28, v30, v88
	v_mul_f32_e32 v26, v26, v28
	v_mul_f32_e32 v27, v27, v29
	v_sub_f32_e32 v28, v34, v88
	v_mul_f32_e32 v27, v27, v28
	v_mul_f32_e32 v24, v89, v24
	v_mul_f32_e32 v25, v89, v25
	v_mul_f32_e32 v27, v89, v27
	v_mul_f32_e32 v24, v60, v24
	v_mul_f32_e32 v25, v61, v25
	v_mul_f32_e32 v26, v89, v26
	v_mul_f32_e32 v27, v63, v27
	v_mul_f32_e32 v20, v20, v123
	v_mul_f32_e32 v26, v62, v26
	v_cvt_pk_bf16_f32 v24, v24, v25
	v_cvt_pk_bf16_f32 v25, v26, v27
	v_mul_f32_e32 v27, 0xbfb8aa3b, v20
	v_exp_f32_e32 v27, v27
	v_mul_f32_e32 v21, v21, v123
	v_mul_f32_e32 v29, 0xbfb8aa3b, v21
	v_exp_f32_e32 v29, v29
	v_add_f32_e32 v27, 1.0, v27
	v_rcp_f32_e32 v27, v27
	global_store_dwordx2 v[32:33], v[24:25], off offset:32
	s_waitcnt vmcnt(17)
	v_lshlrev_b32_e32 v24, 16, v96
	v_and_b32_e32 v25, 0xffff0000, v96
	v_mul_f32_e32 v20, v20, v27
	v_add_f32_e32 v27, 1.0, v29
	v_rcp_f32_e32 v27, v27
	v_mul_f32_e32 v22, v22, v123
	v_sub_f32_e32 v24, v24, v88
	v_mul_f32_e32 v23, v23, v123
	v_mul_f32_e32 v20, v20, v24
	v_mul_f32_e32 v21, v21, v27
	v_mul_f32_e32 v24, 0xbfb8aa3b, v22
	v_sub_f32_e32 v25, v25, v88
	v_exp_f32_e32 v24, v24
	v_mul_f32_e32 v21, v21, v25
	v_mul_f32_e32 v25, 0xbfb8aa3b, v23
	v_exp_f32_e32 v25, v25
	v_add_f32_e32 v24, 1.0, v24
	v_rcp_f32_e32 v24, v24
	v_lshlrev_b32_e32 v26, 16, v97
	v_add_f32_e32 v25, 1.0, v25
	v_rcp_f32_e32 v25, v25
	v_and_b32_e32 v28, 0xffff0000, v97
	v_mul_f32_e32 v22, v22, v24
	v_sub_f32_e32 v24, v26, v88
	v_mul_f32_e32 v22, v22, v24
	v_mul_f32_e32 v23, v23, v25
	v_sub_f32_e32 v24, v28, v88
	v_mul_f32_e32 v23, v23, v24
	v_mul_f32_e32 v20, v89, v20
	v_mul_f32_e32 v21, v89, v21
	v_mul_f32_e32 v23, v89, v23
	v_mul_f32_e32 v20, v52, v20
	v_mul_f32_e32 v21, v53, v21
	v_mul_f32_e32 v22, v89, v22
	v_mul_f32_e32 v23, v55, v23
	v_mul_f32_e32 v16, v16, v123
	v_mul_f32_e32 v22, v54, v22
	v_cvt_pk_bf16_f32 v20, v20, v21
	v_cvt_pk_bf16_f32 v21, v22, v23
	v_mul_f32_e32 v23, 0xbfb8aa3b, v16
	v_exp_f32_e32 v23, v23
	v_mul_f32_e32 v17, v17, v123
	v_mul_f32_e32 v25, 0xbfb8aa3b, v17
	v_exp_f32_e32 v25, v25
	v_add_f32_e32 v23, 1.0, v23
	v_rcp_f32_e32 v23, v23
	global_store_dwordx2 v[32:33], v[20:21], off offset:64
	s_waitcnt vmcnt(17)
	v_and_b32_e32 v21, 0xffff0000, v94
	v_mul_f32_e32 v19, v19, v123
	v_mul_f32_e32 v16, v16, v23
	v_add_f32_e32 v23, 1.0, v25
	v_rcp_f32_e32 v23, v23
	v_sub_f32_e32 v21, v21, v88
	v_lshlrev_b32_e32 v20, 16, v94
	v_mul_f32_e32 v18, v18, v123
	v_mul_f32_e32 v17, v17, v23
	v_mul_f32_e32 v17, v17, v21
	v_mul_f32_e32 v21, 0xbfb8aa3b, v19
	v_exp_f32_e32 v21, v21
	v_sub_f32_e32 v20, v20, v88
	v_mul_f32_e32 v16, v16, v20
	v_mul_f32_e32 v20, 0xbfb8aa3b, v18
	v_add_f32_e32 v21, 1.0, v21
	v_rcp_f32_e32 v21, v21
	s_waitcnt vmcnt(16)
	v_mul_f32_e32 v12, v12, v122
	v_exp_f32_e32 v20, v20
	v_mul_f32_e32 v13, v13, v122
	v_mul_f32_e32 v19, v19, v21
	v_mul_f32_e32 v21, 0xbfb8aa3b, v12
	v_exp_f32_e32 v21, v21
	v_add_f32_e32 v20, 1.0, v20
	v_rcp_f32_e32 v20, v20
	v_mul_f32_e32 v23, 0xbfb8aa3b, v13
	v_add_f32_e32 v21, 1.0, v21
	v_rcp_f32_e32 v21, v21
	v_exp_f32_e32 v23, v23
	v_lshlrev_b32_e32 v22, 16, v95
	v_and_b32_e32 v24, 0xffff0000, v95
	v_mul_f32_e32 v18, v18, v20
	v_sub_f32_e32 v20, v22, v88
	v_mul_f32_e32 v18, v18, v20
	v_sub_f32_e32 v20, v24, v88
	v_mul_f32_e32 v12, v12, v21
	v_add_f32_e32 v21, 1.0, v23
	v_mul_f32_e32 v16, v89, v16
	v_mul_f32_e32 v17, v89, v17
	v_mul_f32_e32 v18, v89, v18
	v_mul_f32_e32 v19, v19, v20
	v_rcp_f32_e32 v21, v21
	v_mul_f32_e32 v16, v44, v16
	v_mul_f32_e32 v17, v45, v17
	v_mul_f32_e32 v18, v46, v18
	v_mul_f32_e32 v19, v89, v19
	v_mul_f32_e32 v19, v47, v19
	v_cvt_pk_bf16_f32 v16, v16, v17
	v_cvt_pk_bf16_f32 v17, v18, v19
	s_waitcnt vmcnt(14)
	v_lshlrev_b32_e32 v18, 16, v90
	v_and_b32_e32 v19, 0xffff0000, v90
	v_mul_f32_e32 v14, v14, v122
	v_sub_f32_e32 v18, v18, v80
	v_mul_f32_e32 v15, v15, v122
	v_mul_f32_e32 v12, v12, v18
	v_mul_f32_e32 v13, v13, v21
	v_mul_f32_e32 v18, 0xbfb8aa3b, v14
	v_sub_f32_e32 v19, v19, v80
	v_exp_f32_e32 v18, v18
	v_mul_f32_e32 v13, v13, v19
	v_mul_f32_e32 v19, 0xbfb8aa3b, v15
	v_exp_f32_e32 v19, v19
	v_add_f32_e32 v18, 1.0, v18
	v_rcp_f32_e32 v18, v18
	v_lshlrev_b32_e32 v20, 16, v91
	v_add_f32_e32 v19, 1.0, v19
	v_rcp_f32_e32 v19, v19
	v_and_b32_e32 v22, 0xffff0000, v91
	v_mul_f32_e32 v14, v14, v18
	v_sub_f32_e32 v18, v20, v80
	v_mul_f32_e32 v14, v14, v18
	v_mul_f32_e32 v15, v15, v19
	v_sub_f32_e32 v18, v22, v80
	v_mul_f32_e32 v15, v15, v18
	v_mul_f32_e32 v12, v81, v12
	v_mul_f32_e32 v13, v81, v13
	v_mul_f32_e32 v15, v81, v15
	v_mul_f32_e32 v12, v68, v12
	v_mul_f32_e32 v13, v69, v13
	v_mul_f32_e32 v14, v81, v14
	v_mul_f32_e32 v15, v71, v15
	v_mul_f32_e32 v8, v8, v122
	v_mul_f32_e32 v14, v70, v14
	v_cvt_pk_bf16_f32 v12, v12, v13
	v_cvt_pk_bf16_f32 v13, v14, v15
	v_mul_f32_e32 v15, 0xbfb8aa3b, v8
	v_exp_f32_e32 v15, v15
	v_mul_f32_e32 v9, v9, v122
	v_mul_f32_e32 v19, 0xbfb8aa3b, v9
	v_exp_f32_e32 v19, v19
	v_add_f32_e32 v15, 1.0, v15
	v_rcp_f32_e32 v15, v15
	global_store_dwordx2 v[32:33], v[16:17], off offset:96
	v_lshl_add_u64 v[16:17], v[140:141], 0, v[92:93]
	global_store_dwordx2 v[16:17], v[12:13], off
	v_mul_f32_e32 v8, v8, v15
	v_add_f32_e32 v15, 1.0, v19
	v_rcp_f32_e32 v15, v15
	s_waitcnt vmcnt(15)
	v_lshlrev_b32_e32 v12, 16, v86
	v_and_b32_e32 v13, 0xffff0000, v86
	v_mul_f32_e32 v10, v10, v122
	v_sub_f32_e32 v12, v12, v80
	v_mul_f32_e32 v11, v11, v122
	v_mul_f32_e32 v8, v8, v12
	v_mul_f32_e32 v9, v9, v15
	v_mul_f32_e32 v12, 0xbfb8aa3b, v10
	v_sub_f32_e32 v13, v13, v80
	v_exp_f32_e32 v12, v12
	v_mul_f32_e32 v9, v9, v13
	v_mul_f32_e32 v13, 0xbfb8aa3b, v11
	v_exp_f32_e32 v13, v13
	v_add_f32_e32 v12, 1.0, v12
	v_rcp_f32_e32 v12, v12
	v_lshlrev_b32_e32 v14, 16, v87
	v_add_f32_e32 v13, 1.0, v13
	v_rcp_f32_e32 v13, v13
	v_and_b32_e32 v18, 0xffff0000, v87
	v_mul_f32_e32 v10, v10, v12
	v_sub_f32_e32 v12, v14, v80
	v_mul_f32_e32 v10, v10, v12
	v_mul_f32_e32 v11, v11, v13
	v_sub_f32_e32 v12, v18, v80
	v_mul_f32_e32 v11, v11, v12
	v_mul_f32_e32 v8, v81, v8
	v_mul_f32_e32 v9, v81, v9
	v_mul_f32_e32 v11, v81, v11
	v_mul_f32_e32 v8, v60, v8
	v_mul_f32_e32 v9, v61, v9
	v_mul_f32_e32 v10, v81, v10
	v_mul_f32_e32 v11, v63, v11
	v_mul_f32_e32 v4, v4, v122
	v_mul_f32_e32 v10, v62, v10
	v_cvt_pk_bf16_f32 v8, v8, v9
	v_cvt_pk_bf16_f32 v9, v10, v11
	v_mul_f32_e32 v11, 0xbfb8aa3b, v4
	v_exp_f32_e32 v11, v11
	v_mul_f32_e32 v5, v5, v122
	v_mul_f32_e32 v13, 0xbfb8aa3b, v5
	v_exp_f32_e32 v13, v13
	v_add_f32_e32 v11, 1.0, v11
	v_rcp_f32_e32 v11, v11
	global_store_dwordx2 v[16:17], v[8:9], off offset:32
	s_waitcnt vmcnt(15)
	v_lshlrev_b32_e32 v8, 16, v84
	v_and_b32_e32 v9, 0xffff0000, v84
	v_mul_f32_e32 v4, v4, v11
	v_add_f32_e32 v11, 1.0, v13
	v_rcp_f32_e32 v11, v11
	v_mul_f32_e32 v6, v6, v122
	v_sub_f32_e32 v8, v8, v80
	v_mul_f32_e32 v7, v7, v122
	v_mul_f32_e32 v4, v4, v8
	v_mul_f32_e32 v5, v5, v11
	v_mul_f32_e32 v8, 0xbfb8aa3b, v6
	v_sub_f32_e32 v9, v9, v80
	v_exp_f32_e32 v8, v8
	v_mul_f32_e32 v5, v5, v9
	v_mul_f32_e32 v9, 0xbfb8aa3b, v7
	v_exp_f32_e32 v9, v9
	v_add_f32_e32 v8, 1.0, v8
	v_rcp_f32_e32 v8, v8
	v_lshlrev_b32_e32 v10, 16, v85
	v_add_f32_e32 v9, 1.0, v9
	v_rcp_f32_e32 v9, v9
	v_and_b32_e32 v12, 0xffff0000, v85
	v_mul_f32_e32 v6, v6, v8
	v_sub_f32_e32 v8, v10, v80
	v_mul_f32_e32 v6, v6, v8
	v_mul_f32_e32 v7, v7, v9
	v_sub_f32_e32 v8, v12, v80
	v_mul_f32_e32 v7, v7, v8
	v_mul_f32_e32 v4, v81, v4
	v_mul_f32_e32 v5, v81, v5
	v_mul_f32_e32 v7, v81, v7
	v_mul_f32_e32 v4, v52, v4
	v_mul_f32_e32 v5, v53, v5
	v_mul_f32_e32 v6, v81, v6
	v_mul_f32_e32 v7, v55, v7
	v_mul_f32_e32 v0, v0, v122
	v_mul_f32_e32 v6, v54, v6
	v_cvt_pk_bf16_f32 v4, v4, v5
	v_cvt_pk_bf16_f32 v5, v6, v7
	v_mul_f32_e32 v7, 0xbfb8aa3b, v0
	v_exp_f32_e32 v7, v7
	v_mul_f32_e32 v1, v1, v122
	v_mul_f32_e32 v9, 0xbfb8aa3b, v1
	v_exp_f32_e32 v9, v9
	v_add_f32_e32 v7, 1.0, v7
	v_rcp_f32_e32 v7, v7
	global_store_dwordx2 v[16:17], v[4:5], off offset:64
	s_waitcnt vmcnt(15)
	v_lshlrev_b32_e32 v4, 16, v82
	v_and_b32_e32 v5, 0xffff0000, v82
	v_mul_f32_e32 v0, v0, v7
	v_add_f32_e32 v7, 1.0, v9
	v_rcp_f32_e32 v7, v7
	v_mul_f32_e32 v2, v2, v122
	v_sub_f32_e32 v4, v4, v80
	v_mul_f32_e32 v3, v3, v122
	v_mul_f32_e32 v0, v0, v4
	v_mul_f32_e32 v1, v1, v7
	v_mul_f32_e32 v4, 0xbfb8aa3b, v2
	v_sub_f32_e32 v5, v5, v80
	v_exp_f32_e32 v4, v4
	v_mul_f32_e32 v1, v1, v5
	v_mul_f32_e32 v5, 0xbfb8aa3b, v3
	v_exp_f32_e32 v5, v5
	v_add_f32_e32 v4, 1.0, v4
	v_rcp_f32_e32 v4, v4
	v_lshlrev_b32_e32 v6, 16, v83
	v_add_f32_e32 v5, 1.0, v5
	v_rcp_f32_e32 v5, v5
	v_and_b32_e32 v8, 0xffff0000, v83
	v_mul_f32_e32 v2, v2, v4
	v_sub_f32_e32 v4, v6, v80
	v_mul_f32_e32 v2, v2, v4
	v_mul_f32_e32 v3, v3, v5
	v_sub_f32_e32 v4, v8, v80
	v_mul_f32_e32 v0, v81, v0
	v_mul_f32_e32 v1, v81, v1
	v_mul_f32_e32 v3, v3, v4
	v_mul_f32_e32 v0, v44, v0
	v_mul_f32_e32 v1, v45, v1
	v_mul_f32_e32 v2, v81, v2
	v_mul_f32_e32 v3, v81, v3
	v_mul_f32_e32 v2, v46, v2
	v_mul_f32_e32 v3, v47, v3
	v_cvt_pk_bf16_f32 v0, v0, v1
	v_cvt_pk_bf16_f32 v1, v2, v3
	global_store_dwordx2 v[16:17], v[0:1], off offset:96
	s_add_i32 s34, s34, s74
	s_cmpk_lt_i32 s34, 0x800
	s_cbranch_scc1 .LBB0_502

.LBB0_706:
	ds_read_b128 v[196:199], v171 offset:32768
	ds_read_b128 v[200:203], v171 offset:33792
	ds_read_b128 v[204:207], v171 offset:34816
	ds_read_b128 v[208:211], v171 offset:35840
	ds_read_b128 v[212:215], v169
	global_load_dwordx4 v[172:175], v[172:173], off
	ds_read_b128 v[216:219], v169 offset:1024
	global_load_dwordx4 v[176:179], v[176:177], off
	ds_read_b128 v[222:225], v169 offset:2048
	global_load_dwordx4 v[180:183], v[180:181], off
	ds_read_b128 v[226:229], v169 offset:3072
	global_load_dwordx4 v[184:187], v[184:185], off
	ds_read_b128 v[230:233], v169 offset:4096
	global_load_dwordx4 v[188:191], v[188:189], off
	ds_read_b128 v[234:237], v169 offset:5120
	global_load_dwordx4 v[192:195], v[192:193], off
	ds_read_b128 v[238:241], v169 offset:6144
	ds_read_b128 v[242:245], v169 offset:7168
	s_setprio 1
	s_waitcnt lgkmcnt(7)
	v_mfma_f32_16x16x32_bf16 v[148:151], v[196:199], v[212:215], v[148:151]
	v_mfma_f32_16x16x32_bf16 v[144:147], v[200:203], v[212:215], v[144:147]
	v_mfma_f32_16x16x32_bf16 v[140:143], v[204:207], v[212:215], v[140:143]
	v_mfma_f32_16x16x32_bf16 v[136:139], v[208:211], v[212:215], v[136:139]
	s_waitcnt vmcnt(11)
	ds_write_b128 v152, v[112:115] offset:16384
	s_waitcnt lgkmcnt(7)
	v_mfma_f32_16x16x32_bf16 v[108:111], v[196:199], v[216:219], v[108:111]
	v_mfma_f32_16x16x32_bf16 v[104:107], v[200:203], v[216:219], v[104:107]
	v_mfma_f32_16x16x32_bf16 v[100:103], v[204:207], v[216:219], v[100:103]
	v_mfma_f32_16x16x32_bf16 v[96:99], v[208:211], v[216:219], v[96:99]
	s_waitcnt vmcnt(9)
	ds_write_b128 v152, v[120:123] offset:20480
	s_waitcnt lgkmcnt(7)
	v_mfma_f32_16x16x32_bf16 v[92:95], v[196:199], v[222:225], v[92:95]
	v_mfma_f32_16x16x32_bf16 v[88:91], v[200:203], v[222:225], v[88:91]
	v_mfma_f32_16x16x32_bf16 v[84:87], v[204:207], v[222:225], v[84:87]
	v_mfma_f32_16x16x32_bf16 v[80:83], v[208:211], v[222:225], v[80:83]
	s_waitcnt vmcnt(8)
	ds_write_b128 v152, v[124:127] offset:24576
	s_waitcnt lgkmcnt(7)
	v_mfma_f32_16x16x32_bf16 v[76:79], v[196:199], v[226:229], v[76:79]
	v_mfma_f32_16x16x32_bf16 v[72:75], v[200:203], v[226:229], v[72:75]
	v_mfma_f32_16x16x32_bf16 v[68:71], v[204:207], v[226:229], v[68:71]
	v_mfma_f32_16x16x32_bf16 v[64:67], v[208:211], v[226:229], v[64:67]
	s_waitcnt vmcnt(7)
	ds_write_b128 v152, v[128:131] offset:28672
	s_waitcnt lgkmcnt(7)
	v_mfma_f32_16x16x32_bf16 v[60:63], v[196:199], v[230:233], v[60:63]
	v_mfma_f32_16x16x32_bf16 v[56:59], v[200:203], v[230:233], v[56:59]
	v_mfma_f32_16x16x32_bf16 v[52:55], v[204:207], v[230:233], v[52:55]
	v_mfma_f32_16x16x32_bf16 v[48:51], v[208:211], v[230:233], v[48:51]
	s_waitcnt vmcnt(7)
	ds_write_b128 v152, v[116:119] offset:40960
	s_waitcnt lgkmcnt(7)
	v_mfma_f32_16x16x32_bf16 v[44:47], v[196:199], v[234:237], v[44:47]
	v_mfma_f32_16x16x32_bf16 v[40:43], v[200:203], v[234:237], v[40:43]
	v_mfma_f32_16x16x32_bf16 v[36:39], v[204:207], v[234:237], v[36:39]
	v_mfma_f32_16x16x32_bf16 v[32:35], v[208:211], v[234:237], v[32:35]
	s_waitcnt vmcnt(6)
	ds_write_b128 v152, v[132:135] offset:45056
	s_waitcnt lgkmcnt(7)
	v_mfma_f32_16x16x32_bf16 v[28:31], v[196:199], v[238:241], v[28:31]
	v_mfma_f32_16x16x32_bf16 v[24:27], v[200:203], v[238:241], v[24:27]
	v_mfma_f32_16x16x32_bf16 v[20:23], v[204:207], v[238:241], v[20:23]
	v_mfma_f32_16x16x32_bf16 v[16:19], v[208:211], v[238:241], v[16:19]
	s_waitcnt lgkmcnt(6)
	v_mfma_f32_16x16x32_bf16 v[12:15], v[196:199], v[242:245], v[12:15]
	v_mfma_f32_16x16x32_bf16 v[8:11], v[200:203], v[242:245], v[8:11]
	v_mfma_f32_16x16x32_bf16 v[4:7], v[204:207], v[242:245], v[4:7]
	v_mfma_f32_16x16x32_bf16 v[0:3], v[208:211], v[242:245], v[0:3]
	s_setprio 0
	s_min_u32 s10, s10, 0x380
	s_lshl_b32 s16, s10, 1
	s_mov_b32 s27, s17
	s_add_i32 s26, s16, 0xc0
	v_lshl_add_u64 v[112:113], v[154:155], 0, s[16:17]
	v_lshl_add_u64 v[116:117], v[156:157], 0, s[16:17]
	v_lshl_add_u64 v[120:121], v[158:159], 0, s[26:27]
	v_lshl_add_u64 v[124:125], v[160:161], 0, s[26:27]
	v_lshl_add_u64 v[128:129], v[162:163], 0, s[26:27]
	v_lshl_add_u64 v[132:133], v[164:165], 0, s[26:27]
	s_waitcnt lgkmcnt(0)
	s_barrier
	ds_read_b128 v[196:199], v168 offset:40960
	ds_read_b128 v[200:203], v168 offset:41984
	ds_read_b128 v[204:207], v168 offset:43008
	ds_read_b128 v[208:211], v168 offset:44032
	ds_read_b128 v[212:215], v170
	global_load_dwordx4 v[112:115], v[112:113], off offset:192
	ds_read_b128 v[216:219], v170 offset:1024
	global_load_dwordx4 v[116:119], v[116:117], off offset:192
	ds_read_b128 v[222:225], v170 offset:2048
	global_load_dwordx4 v[120:123], v[120:121], off
	ds_read_b128 v[226:229], v170 offset:3072
	global_load_dwordx4 v[124:127], v[124:125], off
	ds_read_b128 v[230:233], v170 offset:4096
	global_load_dwordx4 v[128:131], v[128:129], off
	ds_read_b128 v[234:237], v170 offset:5120
	global_load_dwordx4 v[132:135], v[132:133], off
	ds_read_b128 v[238:241], v170 offset:6144
	ds_read_b128 v[242:245], v170 offset:7168
	s_setprio 1
	s_waitcnt lgkmcnt(7)
	v_mfma_f32_16x16x32_bf16 v[148:151], v[196:199], v[212:215], v[148:151]
	v_mfma_f32_16x16x32_bf16 v[144:147], v[200:203], v[212:215], v[144:147]
	v_mfma_f32_16x16x32_bf16 v[140:143], v[204:207], v[212:215], v[140:143]
	v_mfma_f32_16x16x32_bf16 v[136:139], v[208:211], v[212:215], v[136:139]
	s_waitcnt vmcnt(11)
	ds_write_b128 v152, v[172:175]
	s_waitcnt lgkmcnt(7)
	v_mfma_f32_16x16x32_bf16 v[108:111], v[196:199], v[216:219], v[108:111]
	v_mfma_f32_16x16x32_bf16 v[104:107], v[200:203], v[216:219], v[104:107]
	v_mfma_f32_16x16x32_bf16 v[100:103], v[204:207], v[216:219], v[100:103]
	v_mfma_f32_16x16x32_bf16 v[96:99], v[208:211], v[216:219], v[96:99]
	s_waitcnt vmcnt(10)
	ds_write_b128 v152, v[176:179] offset:4096
	s_waitcnt lgkmcnt(7)
	v_mfma_f32_16x16x32_bf16 v[92:95], v[196:199], v[222:225], v[92:95]
	v_mfma_f32_16x16x32_bf16 v[88:91], v[200:203], v[222:225], v[88:91]
	v_mfma_f32_16x16x32_bf16 v[84:87], v[204:207], v[222:225], v[84:87]
	v_mfma_f32_16x16x32_bf16 v[80:83], v[208:211], v[222:225], v[80:83]
	s_waitcnt vmcnt(9)
	ds_write_b128 v152, v[180:183] offset:8192
	s_waitcnt lgkmcnt(7)
	v_mfma_f32_16x16x32_bf16 v[76:79], v[196:199], v[226:229], v[76:79]
	v_mfma_f32_16x16x32_bf16 v[72:75], v[200:203], v[226:229], v[72:75]
	v_mfma_f32_16x16x32_bf16 v[68:71], v[204:207], v[226:229], v[68:71]
	v_mfma_f32_16x16x32_bf16 v[64:67], v[208:211], v[226:229], v[64:67]
	s_waitcnt vmcnt(8)
	ds_write_b128 v152, v[184:187] offset:12288
	s_waitcnt lgkmcnt(7)
	v_mfma_f32_16x16x32_bf16 v[60:63], v[196:199], v[230:233], v[60:63]
	v_mfma_f32_16x16x32_bf16 v[56:59], v[200:203], v[230:233], v[56:59]
	v_mfma_f32_16x16x32_bf16 v[52:55], v[204:207], v[230:233], v[52:55]
	v_mfma_f32_16x16x32_bf16 v[48:51], v[208:211], v[230:233], v[48:51]
	s_waitcnt vmcnt(7)
	ds_write_b128 v152, v[188:191] offset:32768
	s_waitcnt lgkmcnt(7)
	v_mfma_f32_16x16x32_bf16 v[44:47], v[196:199], v[234:237], v[44:47]
	v_mfma_f32_16x16x32_bf16 v[40:43], v[200:203], v[234:237], v[40:43]
	v_mfma_f32_16x16x32_bf16 v[36:39], v[204:207], v[234:237], v[36:39]
	v_mfma_f32_16x16x32_bf16 v[32:35], v[208:211], v[234:237], v[32:35]
	s_waitcnt vmcnt(6)
	ds_write_b128 v152, v[192:195] offset:36864
	s_waitcnt lgkmcnt(7)
	v_mfma_f32_16x16x32_bf16 v[28:31], v[196:199], v[238:241], v[28:31]
	v_mfma_f32_16x16x32_bf16 v[24:27], v[200:203], v[238:241], v[24:27]
	v_mfma_f32_16x16x32_bf16 v[20:23], v[204:207], v[238:241], v[20:23]
	v_mfma_f32_16x16x32_bf16 v[16:19], v[208:211], v[238:241], v[16:19]
	s_waitcnt lgkmcnt(6)
	v_mfma_f32_16x16x32_bf16 v[12:15], v[196:199], v[242:245], v[12:15]
	v_mfma_f32_16x16x32_bf16 v[8:11], v[200:203], v[242:245], v[8:11]
	v_mfma_f32_16x16x32_bf16 v[4:7], v[204:207], v[242:245], v[4:7]
	v_mfma_f32_16x16x32_bf16 v[0:3], v[208:211], v[242:245], v[0:3]
	s_setprio 0
	s_add_i32 s1, s1, 2
	s_mov_b32 s10, s11
	s_add_i32 s11, s10, 64
	s_min_u32 s13, s11, 0x3e0
	s_lshl_b32 s16, s13, 1
	v_lshl_add_u64 v[172:173], v[154:155], 0, s[16:17]
	v_lshl_add_u64 v[176:177], v[158:159], 0, s[16:17]
	v_lshl_add_u64 v[180:181], v[160:161], 0, s[16:17]
	v_lshl_add_u64 v[184:185], v[162:163], 0, s[16:17]
	v_lshl_add_u64 v[188:189], v[156:157], 0, s[16:17]
	v_lshl_add_u64 v[192:193], v[164:165], 0, s[16:17]
	s_cmp_lt_u32 s1, 30
	s_waitcnt lgkmcnt(0)
	s_cbranch_scc1 .Lrot_3
	s_barrier
	s_waitcnt vmcnt(4)
	v_mov_b32_e32 v116, v220
	s_nop 0
	v_and_b32_e32 v112, 0xffffff80, v116
	v_add_u32_e32 v117, s0, v112
	v_and_or_b32 v114, v116, 15, v117
	v_ashrrev_i32_e32 v115, 31, v114
	v_lshl_add_u64 v[112:113], v[114:115], 2, s[14:15]
	global_load_dword v246, v[112:113], off offset:64
	global_load_dword v247, v[112:113], off offset:128
	global_load_dword v248, v[112:113], off offset:192
	global_load_dword v249, v[112:113], off offset:256
	global_load_dword v250, v[112:113], off offset:320
	global_load_dword v251, v[112:113], off offset:384
	global_load_dword v252, v[112:113], off offset:448
	global_load_dword v122, v[112:113], off
	v_and_b32_e32 v112, 64, v116
	v_lshrrev_b32_e32 v115, 1, v116
	v_ashrrev_i32_e32 v116, 14, v117
	v_ashrrev_i32_e32 v117, 31, v116
	v_lshlrev_b32_e32 v152, 1, v112
	v_or_b32_e32 v118, 16, v114
	v_lshlrev_b64 v[116:117], 16, v[116:117]
	v_lshl_add_u64 v[112:113], s[38:39], 0, v[152:153]
	v_and_b32_e32 v152, 24, v115
	v_ashrrev_i32_e32 v119, 31, v118
	v_lshl_or_b32 v115, s12, 14, v116
	s_waitcnt vmcnt(4)
	v_lshl_add_u64 v[120:121], v[118:119], 2, s[14:15]
	v_lshl_add_u64 v[112:113], v[112:113], 0, v[152:153]
	s_waitcnt vmcnt(0)
	v_fmamk_f32 v116, v122, 0x3a800000, v166
	v_mul_f32_e32 v119, 0x4b800000, v116
	v_cmp_gt_f32_e32 vcc, s40, v116
	s_nop 1
	v_cndmask_b32_e32 v116, v116, v119, vcc
	v_rsq_f32_e32 v119, v116
	v_and_or_b32 v116, v114, s41, v115
	v_lshlrev_b64 v[122:123], 8, v[116:117]
	v_lshl_add_u64 v[122:123], v[112:113], 0, v[122:123]
	v_mul_f32_e32 v116, 0x45800000, v119
	v_cndmask_b32_e32 v116, v119, v116, vcc
	v_mul_f32_e32 v124, v149, v116
	v_mul_f32_e32 v125, v150, v116
	v_mul_f32_e32 v119, v148, v116
	v_mul_f32_e32 v126, v151, v116
	v_mul_f32_e32 v127, v144, v116
	v_mul_f32_e32 v128, v145, v116
	v_mul_f32_e32 v129, v146, v116
	v_mul_f32_e32 v130, v147, v116
	v_mul_f32_e32 v131, v140, v116
	v_cvt_pk_bf16_f32 v124, v119, v124
	v_cvt_pk_bf16_f32 v125, v125, v126
	v_mul_f32_e32 v132, v141, v116
	v_mul_f32_e32 v133, v142, v116
	v_mul_f32_e32 v134, v143, v116
	v_mul_f32_e32 v135, v136, v116
	v_mul_f32_e32 v136, v137, v116
	v_mul_f32_e32 v137, v138, v116
	v_mul_f32_e32 v116, v139, v116
	v_cvt_pk_bf16_f32 v126, v127, v128
	v_cvt_pk_bf16_f32 v127, v129, v130
	v_cvt_pk_bf16_f32 v128, v131, v132
	v_cvt_pk_bf16_f32 v129, v133, v134
	v_cvt_pk_bf16_f32 v130, v135, v136
	v_cvt_pk_bf16_f32 v131, v137, v116
	global_store_dwordx2 v[122:123], v[124:125], off
	global_store_dwordx2 v[122:123], v[126:127], off offset:32
	global_store_dwordx2 v[122:123], v[128:129], off offset:64
	global_store_dwordx2 v[122:123], v[130:131], off offset:96
	v_mov_b32_e32 v116, v246
	v_or_b32_e32 v120, 32, v114
	v_ashrrev_i32_e32 v121, 31, v120
	v_lshl_add_u64 v[122:123], v[120:121], 2, s[14:15]
	v_fmamk_f32 v116, v116, 0x3a800000, v166
	v_mul_f32_e32 v119, 0x4b800000, v116
	v_cmp_gt_f32_e32 vcc, s40, v116
	s_nop 1
	v_cndmask_b32_e32 v116, v116, v119, vcc
	v_rsq_f32_e32 v121, v116
	v_and_or_b32 v116, v118, s42, v115
	v_lshlrev_b64 v[118:119], 8, v[116:117]
	v_lshl_add_u64 v[118:119], v[112:113], 0, v[118:119]
	v_mul_f32_e32 v116, 0x45800000, v121
	v_cndmask_b32_e32 v116, v121, v116, vcc
	v_mul_f32_e32 v108, v108, v116
	v_mul_f32_e32 v109, v109, v116
	v_mul_f32_e32 v110, v110, v116
	v_mul_f32_e32 v111, v111, v116
	v_mul_f32_e32 v100, v100, v116
	v_mul_f32_e32 v101, v101, v116
	v_mul_f32_e32 v102, v102, v116
	v_mul_f32_e32 v103, v103, v116
	v_mul_f32_e32 v121, v96, v116
	v_mul_f32_e32 v124, v97, v116
	v_cvt_pk_bf16_f32 v96, v108, v109
	v_cvt_pk_bf16_f32 v97, v110, v111
	v_mul_f32_e32 v104, v104, v116
	v_mul_f32_e32 v105, v105, v116
	v_mul_f32_e32 v106, v106, v116
	v_mul_f32_e32 v107, v107, v116
	v_mul_f32_e32 v125, v98, v116
	v_mul_f32_e32 v116, v99, v116
	v_cvt_pk_bf16_f32 v98, v104, v105
	v_cvt_pk_bf16_f32 v99, v106, v107
	v_cvt_pk_bf16_f32 v100, v100, v101
	v_cvt_pk_bf16_f32 v101, v102, v103
	v_cvt_pk_bf16_f32 v102, v121, v124
	v_cvt_pk_bf16_f32 v103, v125, v116
	global_store_dwordx2 v[118:119], v[96:97], off
	global_store_dwordx2 v[118:119], v[98:99], off offset:32
	global_store_dwordx2 v[118:119], v[100:101], off offset:64
	global_store_dwordx2 v[118:119], v[102:103], off offset:96
	v_mov_b32_e32 v100, v247
	v_or_b32_e32 v96, 48, v114
	v_ashrrev_i32_e32 v97, 31, v96
	v_lshl_add_u64 v[98:99], v[96:97], 2, s[14:15]
	v_and_or_b32 v116, v120, s43, v115
	v_fmamk_f32 v97, v100, 0x3a800000, v166
	v_mul_f32_e32 v100, 0x4b800000, v97
	v_cmp_gt_f32_e32 vcc, s40, v97
	s_nop 1
	v_cndmask_b32_e32 v97, v97, v100, vcc
	v_rsq_f32_e32 v97, v97
	v_lshlrev_b64 v[100:101], 8, v[116:117]
	v_lshl_add_u64 v[100:101], v[112:113], 0, v[100:101]
	v_and_or_b32 v116, v96, s44, v115
	v_mul_f32_e32 v102, 0x45800000, v97
	v_cndmask_b32_e32 v97, v97, v102, vcc
	v_mul_f32_e32 v92, v92, v97
	v_mul_f32_e32 v93, v93, v97
	v_mul_f32_e32 v94, v94, v97
	v_mul_f32_e32 v95, v95, v97
	v_mul_f32_e32 v84, v84, v97
	v_mul_f32_e32 v85, v85, v97
	v_mul_f32_e32 v86, v86, v97
	v_mul_f32_e32 v87, v87, v97
	v_mul_f32_e32 v102, v80, v97
	v_mul_f32_e32 v103, v81, v97
	v_cvt_pk_bf16_f32 v80, v92, v93
	v_cvt_pk_bf16_f32 v81, v94, v95
	v_mul_f32_e32 v88, v88, v97
	v_mul_f32_e32 v89, v89, v97
	v_mul_f32_e32 v90, v90, v97
	v_mul_f32_e32 v91, v91, v97
	v_mul_f32_e32 v104, v82, v97
	v_mul_f32_e32 v97, v83, v97
	v_cvt_pk_bf16_f32 v82, v88, v89
	v_cvt_pk_bf16_f32 v83, v90, v91
	v_cvt_pk_bf16_f32 v84, v84, v85
	v_cvt_pk_bf16_f32 v85, v86, v87
	v_cvt_pk_bf16_f32 v86, v102, v103
	v_cvt_pk_bf16_f32 v87, v104, v97
	global_store_dwordx2 v[100:101], v[80:81], off
	global_store_dwordx2 v[100:101], v[82:83], off offset:32
	global_store_dwordx2 v[100:101], v[84:85], off offset:64
	global_store_dwordx2 v[100:101], v[86:87], off offset:96
	v_mov_b32_e32 v84, v248
	v_or_b32_e32 v80, 64, v114
	v_ashrrev_i32_e32 v81, 31, v80
	v_lshl_add_u64 v[82:83], v[80:81], 2, s[14:15]
	v_fmamk_f32 v81, v84, 0x3a800000, v166
	v_mul_f32_e32 v84, 0x4b800000, v81
	v_cmp_gt_f32_e32 vcc, s40, v81
	s_nop 1
	v_cndmask_b32_e32 v81, v81, v84, vcc
	v_rsq_f32_e32 v81, v81
	v_lshlrev_b64 v[84:85], 8, v[116:117]
	v_lshl_add_u64 v[84:85], v[112:113], 0, v[84:85]
	v_and_or_b32 v116, v80, s45, v115
	v_mul_f32_e32 v86, 0x45800000, v81
	v_cndmask_b32_e32 v81, v81, v86, vcc
	v_mul_f32_e32 v76, v76, v81
	v_mul_f32_e32 v77, v77, v81
	v_mul_f32_e32 v78, v78, v81
	v_mul_f32_e32 v79, v79, v81
	v_mul_f32_e32 v68, v68, v81
	v_mul_f32_e32 v69, v69, v81
	v_mul_f32_e32 v70, v70, v81
	v_mul_f32_e32 v71, v71, v81
	v_mul_f32_e32 v86, v64, v81
	v_mul_f32_e32 v87, v65, v81
	v_cvt_pk_bf16_f32 v64, v76, v77
	v_cvt_pk_bf16_f32 v65, v78, v79
	v_mul_f32_e32 v72, v72, v81
	v_mul_f32_e32 v73, v73, v81
	v_mul_f32_e32 v74, v74, v81
	v_mul_f32_e32 v75, v75, v81
	v_mul_f32_e32 v88, v66, v81
	v_mul_f32_e32 v81, v67, v81
	v_cvt_pk_bf16_f32 v66, v72, v73
	v_cvt_pk_bf16_f32 v67, v74, v75
	v_cvt_pk_bf16_f32 v68, v68, v69
	v_cvt_pk_bf16_f32 v69, v70, v71
	v_cvt_pk_bf16_f32 v70, v86, v87
	v_cvt_pk_bf16_f32 v71, v88, v81
	global_store_dwordx2 v[84:85], v[64:65], off
	global_store_dwordx2 v[84:85], v[66:67], off offset:32
	global_store_dwordx2 v[84:85], v[68:69], off offset:64
	global_store_dwordx2 v[84:85], v[70:71], off offset:96
	v_mov_b32_e32 v68, v249
	v_or_b32_e32 v64, 0x50, v114
	v_ashrrev_i32_e32 v65, 31, v64
	v_lshl_add_u64 v[66:67], v[64:65], 2, s[14:15]
	v_fmamk_f32 v65, v68, 0x3a800000, v166
	v_mul_f32_e32 v68, 0x4b800000, v65
	v_cmp_gt_f32_e32 vcc, s40, v65
	s_nop 1
	v_cndmask_b32_e32 v65, v65, v68, vcc
	v_rsq_f32_e32 v65, v65
	v_lshlrev_b64 v[68:69], 8, v[116:117]
	v_lshl_add_u64 v[68:69], v[112:113], 0, v[68:69]
	v_and_or_b32 v116, v64, s46, v115
	v_mul_f32_e32 v70, 0x45800000, v65
	v_cndmask_b32_e32 v65, v65, v70, vcc
	v_mul_f32_e32 v60, v60, v65
	v_mul_f32_e32 v61, v61, v65
	v_mul_f32_e32 v62, v62, v65
	v_mul_f32_e32 v63, v63, v65
	v_mul_f32_e32 v52, v52, v65
	v_mul_f32_e32 v53, v53, v65
	v_mul_f32_e32 v54, v54, v65
	v_mul_f32_e32 v55, v55, v65
	v_mul_f32_e32 v70, v48, v65
	v_mul_f32_e32 v71, v49, v65
	v_cvt_pk_bf16_f32 v48, v60, v61
	v_cvt_pk_bf16_f32 v49, v62, v63
	v_mul_f32_e32 v56, v56, v65
	v_mul_f32_e32 v57, v57, v65
	v_mul_f32_e32 v58, v58, v65
	v_mul_f32_e32 v59, v59, v65
	v_mul_f32_e32 v72, v50, v65
	v_mul_f32_e32 v65, v51, v65
	v_cvt_pk_bf16_f32 v50, v56, v57
	v_cvt_pk_bf16_f32 v51, v58, v59
	v_cvt_pk_bf16_f32 v52, v52, v53
	v_cvt_pk_bf16_f32 v53, v54, v55
	v_cvt_pk_bf16_f32 v54, v70, v71
	v_cvt_pk_bf16_f32 v55, v72, v65
	global_store_dwordx2 v[68:69], v[48:49], off
	global_store_dwordx2 v[68:69], v[50:51], off offset:32
	global_store_dwordx2 v[68:69], v[52:53], off offset:64
	global_store_dwordx2 v[68:69], v[54:55], off offset:96
	v_mov_b32_e32 v52, v250
	v_or_b32_e32 v48, 0x60, v114
	v_ashrrev_i32_e32 v49, 31, v48
	v_lshl_add_u64 v[50:51], v[48:49], 2, s[14:15]
	v_fmamk_f32 v49, v52, 0x3a800000, v166
	v_mul_f32_e32 v52, 0x4b800000, v49
	v_cmp_gt_f32_e32 vcc, s40, v49
	s_nop 1
	v_cndmask_b32_e32 v49, v49, v52, vcc
	v_rsq_f32_e32 v49, v49
	v_lshlrev_b64 v[52:53], 8, v[116:117]
	v_lshl_add_u64 v[52:53], v[112:113], 0, v[52:53]
	v_and_or_b32 v116, v48, s47, v115
	v_mul_f32_e32 v54, 0x45800000, v49
	v_cndmask_b32_e32 v49, v49, v54, vcc
	v_mul_f32_e32 v44, v44, v49
	v_mul_f32_e32 v45, v45, v49
	v_mul_f32_e32 v46, v46, v49
	v_mul_f32_e32 v47, v47, v49
	v_mul_f32_e32 v36, v36, v49
	v_mul_f32_e32 v37, v37, v49
	v_mul_f32_e32 v38, v38, v49
	v_mul_f32_e32 v39, v39, v49
	v_mul_f32_e32 v54, v32, v49
	v_mul_f32_e32 v55, v33, v49
	v_cvt_pk_bf16_f32 v32, v44, v45
	v_cvt_pk_bf16_f32 v33, v46, v47
	v_mul_f32_e32 v40, v40, v49
	v_mul_f32_e32 v41, v41, v49
	v_mul_f32_e32 v42, v42, v49
	v_mul_f32_e32 v43, v43, v49
	v_mul_f32_e32 v56, v34, v49
	v_mul_f32_e32 v49, v35, v49
	v_cvt_pk_bf16_f32 v34, v40, v41
	v_cvt_pk_bf16_f32 v35, v42, v43
	v_cvt_pk_bf16_f32 v36, v36, v37
	v_cvt_pk_bf16_f32 v37, v38, v39
	v_cvt_pk_bf16_f32 v38, v54, v55
	v_cvt_pk_bf16_f32 v39, v56, v49
	global_store_dwordx2 v[52:53], v[32:33], off
	global_store_dwordx2 v[52:53], v[34:35], off offset:32
	global_store_dwordx2 v[52:53], v[36:37], off offset:64
	global_store_dwordx2 v[52:53], v[38:39], off offset:96
	v_mov_b32_e32 v36, v251
	v_or_b32_e32 v32, 0x70, v114
	v_ashrrev_i32_e32 v33, 31, v32
	v_lshl_add_u64 v[34:35], v[32:33], 2, s[14:15]
	v_fmamk_f32 v33, v36, 0x3a800000, v166
	v_mul_f32_e32 v36, 0x4b800000, v33
	v_cmp_gt_f32_e32 vcc, s40, v33
	s_nop 1
	v_cndmask_b32_e32 v33, v33, v36, vcc
	v_rsq_f32_e32 v33, v33
	v_lshlrev_b64 v[36:37], 8, v[116:117]
	v_lshl_add_u64 v[36:37], v[112:113], 0, v[36:37]
	v_and_or_b32 v116, v32, s48, v115
	v_mul_f32_e32 v38, 0x45800000, v33
	v_cndmask_b32_e32 v33, v33, v38, vcc
	v_mul_f32_e32 v28, v28, v33
	v_mul_f32_e32 v29, v29, v33
	v_mul_f32_e32 v30, v30, v33
	v_mul_f32_e32 v31, v31, v33
	v_mul_f32_e32 v20, v20, v33
	v_mul_f32_e32 v21, v21, v33
	v_mul_f32_e32 v22, v22, v33
	v_mul_f32_e32 v23, v23, v33
	v_mul_f32_e32 v38, v16, v33
	v_mul_f32_e32 v39, v17, v33
	v_cvt_pk_bf16_f32 v16, v28, v29
	v_cvt_pk_bf16_f32 v17, v30, v31
	v_mul_f32_e32 v24, v24, v33
	v_mul_f32_e32 v25, v25, v33
	v_mul_f32_e32 v26, v26, v33
	v_mul_f32_e32 v27, v27, v33
	v_mul_f32_e32 v40, v18, v33
	v_mul_f32_e32 v33, v19, v33
	v_cvt_pk_bf16_f32 v18, v24, v25
	v_cvt_pk_bf16_f32 v19, v26, v27
	v_cvt_pk_bf16_f32 v20, v20, v21
	v_cvt_pk_bf16_f32 v21, v22, v23
	v_cvt_pk_bf16_f32 v22, v38, v39
	v_cvt_pk_bf16_f32 v23, v40, v33
	global_store_dwordx2 v[36:37], v[16:17], off
	global_store_dwordx2 v[36:37], v[18:19], off offset:32
	global_store_dwordx2 v[36:37], v[20:21], off offset:64
	global_store_dwordx2 v[36:37], v[22:23], off offset:96
	v_mov_b32_e32 v16, v252
	v_fmamk_f32 v16, v16, 0x3a800000, v166
	v_mul_f32_e32 v17, 0x4b800000, v16
	v_cmp_gt_f32_e32 vcc, s40, v16
	s_nop 1
	v_cndmask_b32_e32 v16, v16, v17, vcc
	v_rsq_f32_e32 v18, v16
	v_lshlrev_b64 v[16:17], 8, v[116:117]
	v_lshl_add_u64 v[16:17], v[112:113], 0, v[16:17]
	v_mul_f32_e32 v19, 0x45800000, v18
	v_cndmask_b32_e32 v18, v18, v19, vcc
	v_mul_f32_e32 v12, v12, v18
	v_mul_f32_e32 v13, v13, v18
	v_mul_f32_e32 v14, v14, v18
	v_mul_f32_e32 v15, v15, v18
	v_mul_f32_e32 v4, v4, v18
	v_mul_f32_e32 v5, v5, v18
	v_mul_f32_e32 v6, v6, v18
	v_mul_f32_e32 v7, v7, v18
	v_mul_f32_e32 v19, v0, v18
	v_mul_f32_e32 v20, v1, v18
	v_cvt_pk_bf16_f32 v0, v12, v13
	v_cvt_pk_bf16_f32 v1, v14, v15
	v_mul_f32_e32 v8, v8, v18
	v_mul_f32_e32 v9, v9, v18
	v_mul_f32_e32 v10, v10, v18
	v_mul_f32_e32 v11, v11, v18
	v_mul_f32_e32 v21, v2, v18
	v_mul_f32_e32 v18, v3, v18
	v_cvt_pk_bf16_f32 v2, v8, v9
	v_cvt_pk_bf16_f32 v3, v10, v11
	v_cvt_pk_bf16_f32 v4, v4, v5
	v_cvt_pk_bf16_f32 v5, v6, v7
	v_cvt_pk_bf16_f32 v6, v19, v20
	v_cvt_pk_bf16_f32 v7, v21, v18
	global_store_dwordx2 v[16:17], v[0:1], off
	global_store_dwordx2 v[16:17], v[2:3], off offset:32
	global_store_dwordx2 v[16:17], v[4:5], off offset:64
	global_store_dwordx2 v[16:17], v[6:7], off offset:96
	s_branch .LBB0_699

.LBB0_710:
	ds_read_b128 v[196:199], v171 offset:32768
	ds_read_b128 v[200:203], v171 offset:33792
	ds_read_b128 v[204:207], v171 offset:34816
	ds_read_b128 v[208:211], v171 offset:35840
	ds_read_b128 v[212:215], v169
	global_load_dwordx4 v[172:175], v[172:173], off
	ds_read_b128 v[216:219], v169 offset:1024
	global_load_dwordx4 v[176:179], v[176:177], off
	ds_read_b128 v[222:225], v169 offset:2048
	global_load_dwordx4 v[180:183], v[180:181], off
	ds_read_b128 v[226:229], v169 offset:3072
	global_load_dwordx4 v[184:187], v[184:185], off
	ds_read_b128 v[230:233], v169 offset:4096
	global_load_dwordx4 v[188:191], v[188:189], off
	ds_read_b128 v[234:237], v169 offset:5120
	global_load_dwordx4 v[192:195], v[192:193], off
	ds_read_b128 v[238:241], v169 offset:6144
	ds_read_b128 v[242:245], v169 offset:7168
	s_setprio 1
	s_waitcnt lgkmcnt(7)
	v_mfma_f32_16x16x32_bf16 v[148:151], v[212:215], v[196:199], v[148:151]
	v_mfma_f32_16x16x32_bf16 v[144:147], v[212:215], v[200:203], v[144:147]
	v_mfma_f32_16x16x32_bf16 v[140:143], v[212:215], v[204:207], v[140:143]
	v_mfma_f32_16x16x32_bf16 v[128:131], v[212:215], v[208:211], v[128:131]
	s_waitcnt vmcnt(11)
	ds_write_b128 v152, v[112:115] offset:16384
	s_waitcnt lgkmcnt(7)
	v_mfma_f32_16x16x32_bf16 v[108:111], v[216:219], v[196:199], v[108:111]
	v_mfma_f32_16x16x32_bf16 v[104:107], v[216:219], v[200:203], v[104:107]
	v_mfma_f32_16x16x32_bf16 v[100:103], v[216:219], v[204:207], v[100:103]
	v_mfma_f32_16x16x32_bf16 v[96:99], v[216:219], v[208:211], v[96:99]
	s_waitcnt vmcnt(9)
	ds_write_b128 v152, v[120:123] offset:20480
	s_waitcnt lgkmcnt(7)
	v_mfma_f32_16x16x32_bf16 v[92:95], v[222:225], v[196:199], v[92:95]
	v_mfma_f32_16x16x32_bf16 v[88:91], v[222:225], v[200:203], v[88:91]
	v_mfma_f32_16x16x32_bf16 v[84:87], v[222:225], v[204:207], v[84:87]
	v_mfma_f32_16x16x32_bf16 v[80:83], v[222:225], v[208:211], v[80:83]
	s_waitcnt vmcnt(8)
	ds_write_b128 v152, v[124:127] offset:24576
	s_waitcnt lgkmcnt(7)
	v_mfma_f32_16x16x32_bf16 v[76:79], v[226:229], v[196:199], v[76:79]
	v_mfma_f32_16x16x32_bf16 v[72:75], v[226:229], v[200:203], v[72:75]
	v_mfma_f32_16x16x32_bf16 v[68:71], v[226:229], v[204:207], v[68:71]
	v_mfma_f32_16x16x32_bf16 v[64:67], v[226:229], v[208:211], v[64:67]
	s_waitcnt vmcnt(7)
	ds_write_b128 v152, v[132:135] offset:28672
	s_waitcnt lgkmcnt(7)
	v_mfma_f32_16x16x32_bf16 v[60:63], v[230:233], v[196:199], v[60:63]
	v_mfma_f32_16x16x32_bf16 v[56:59], v[230:233], v[200:203], v[56:59]
	v_mfma_f32_16x16x32_bf16 v[52:55], v[230:233], v[204:207], v[52:55]
	v_mfma_f32_16x16x32_bf16 v[48:51], v[230:233], v[208:211], v[48:51]
	s_waitcnt vmcnt(7)
	ds_write_b128 v152, v[116:119] offset:40960
	s_waitcnt lgkmcnt(7)
	v_mfma_f32_16x16x32_bf16 v[44:47], v[234:237], v[196:199], v[44:47]
	v_mfma_f32_16x16x32_bf16 v[40:43], v[234:237], v[200:203], v[40:43]
	v_mfma_f32_16x16x32_bf16 v[36:39], v[234:237], v[204:207], v[36:39]
	v_mfma_f32_16x16x32_bf16 v[32:35], v[234:237], v[208:211], v[32:35]
	s_waitcnt vmcnt(6)
	ds_write_b128 v152, v[136:139] offset:45056
	s_waitcnt lgkmcnt(7)
	v_mfma_f32_16x16x32_bf16 v[28:31], v[238:241], v[196:199], v[28:31]
	v_mfma_f32_16x16x32_bf16 v[24:27], v[238:241], v[200:203], v[24:27]
	v_mfma_f32_16x16x32_bf16 v[20:23], v[238:241], v[204:207], v[20:23]
	v_mfma_f32_16x16x32_bf16 v[16:19], v[238:241], v[208:211], v[16:19]
	s_waitcnt lgkmcnt(6)
	v_mfma_f32_16x16x32_bf16 v[12:15], v[242:245], v[196:199], v[12:15]
	v_mfma_f32_16x16x32_bf16 v[8:11], v[242:245], v[200:203], v[8:11]
	v_mfma_f32_16x16x32_bf16 v[4:7], v[242:245], v[204:207], v[4:7]
	v_mfma_f32_16x16x32_bf16 v[0:3], v[242:245], v[208:211], v[0:3]
	s_setprio 0
	s_min_u32 s10, s10, 0x380
	s_lshl_b32 s16, s10, 1
	s_mov_b32 s27, s17
	s_add_i32 s26, s16, 0xc0
	v_lshl_add_u64 v[112:113], v[154:155], 0, s[16:17]
	v_lshl_add_u64 v[116:117], v[156:157], 0, s[16:17]
	v_lshl_add_u64 v[120:121], v[158:159], 0, s[26:27]
	v_lshl_add_u64 v[124:125], v[160:161], 0, s[26:27]
	v_lshl_add_u64 v[132:133], v[162:163], 0, s[26:27]
	v_lshl_add_u64 v[136:137], v[164:165], 0, s[26:27]
	s_waitcnt lgkmcnt(0)
	s_barrier
	ds_read_b128 v[196:199], v168 offset:40960
	ds_read_b128 v[200:203], v168 offset:41984
	ds_read_b128 v[204:207], v168 offset:43008
	ds_read_b128 v[208:211], v168 offset:44032
	ds_read_b128 v[212:215], v170
	global_load_dwordx4 v[112:115], v[112:113], off offset:192
	ds_read_b128 v[216:219], v170 offset:1024
	global_load_dwordx4 v[116:119], v[116:117], off offset:192
	ds_read_b128 v[222:225], v170 offset:2048
	global_load_dwordx4 v[120:123], v[120:121], off
	ds_read_b128 v[226:229], v170 offset:3072
	global_load_dwordx4 v[124:127], v[124:125], off
	ds_read_b128 v[230:233], v170 offset:4096
	global_load_dwordx4 v[132:135], v[132:133], off
	ds_read_b128 v[234:237], v170 offset:5120
	global_load_dwordx4 v[136:139], v[136:137], off
	ds_read_b128 v[238:241], v170 offset:6144
	ds_read_b128 v[242:245], v170 offset:7168
	s_setprio 1
	s_waitcnt lgkmcnt(7)
	v_mfma_f32_16x16x32_bf16 v[148:151], v[212:215], v[196:199], v[148:151]
	v_mfma_f32_16x16x32_bf16 v[144:147], v[212:215], v[200:203], v[144:147]
	v_mfma_f32_16x16x32_bf16 v[140:143], v[212:215], v[204:207], v[140:143]
	v_mfma_f32_16x16x32_bf16 v[128:131], v[212:215], v[208:211], v[128:131]
	s_waitcnt vmcnt(11)
	ds_write_b128 v152, v[172:175]
	s_waitcnt lgkmcnt(7)
	v_mfma_f32_16x16x32_bf16 v[108:111], v[216:219], v[196:199], v[108:111]
	v_mfma_f32_16x16x32_bf16 v[104:107], v[216:219], v[200:203], v[104:107]
	v_mfma_f32_16x16x32_bf16 v[100:103], v[216:219], v[204:207], v[100:103]
	v_mfma_f32_16x16x32_bf16 v[96:99], v[216:219], v[208:211], v[96:99]
	s_waitcnt vmcnt(10)
	ds_write_b128 v152, v[176:179] offset:4096
	s_waitcnt lgkmcnt(7)
	v_mfma_f32_16x16x32_bf16 v[92:95], v[222:225], v[196:199], v[92:95]
	v_mfma_f32_16x16x32_bf16 v[88:91], v[222:225], v[200:203], v[88:91]
	v_mfma_f32_16x16x32_bf16 v[84:87], v[222:225], v[204:207], v[84:87]
	v_mfma_f32_16x16x32_bf16 v[80:83], v[222:225], v[208:211], v[80:83]
	s_waitcnt vmcnt(9)
	ds_write_b128 v152, v[180:183] offset:8192
	s_waitcnt lgkmcnt(7)
	v_mfma_f32_16x16x32_bf16 v[76:79], v[226:229], v[196:199], v[76:79]
	v_mfma_f32_16x16x32_bf16 v[72:75], v[226:229], v[200:203], v[72:75]
	v_mfma_f32_16x16x32_bf16 v[68:71], v[226:229], v[204:207], v[68:71]
	v_mfma_f32_16x16x32_bf16 v[64:67], v[226:229], v[208:211], v[64:67]
	s_waitcnt vmcnt(8)
	ds_write_b128 v152, v[184:187] offset:12288
	s_waitcnt lgkmcnt(7)
	v_mfma_f32_16x16x32_bf16 v[60:63], v[230:233], v[196:199], v[60:63]
	v_mfma_f32_16x16x32_bf16 v[56:59], v[230:233], v[200:203], v[56:59]
	v_mfma_f32_16x16x32_bf16 v[52:55], v[230:233], v[204:207], v[52:55]
	v_mfma_f32_16x16x32_bf16 v[48:51], v[230:233], v[208:211], v[48:51]
	s_waitcnt vmcnt(7)
	ds_write_b128 v152, v[188:191] offset:32768
	s_waitcnt lgkmcnt(7)
	v_mfma_f32_16x16x32_bf16 v[44:47], v[234:237], v[196:199], v[44:47]
	v_mfma_f32_16x16x32_bf16 v[40:43], v[234:237], v[200:203], v[40:43]
	v_mfma_f32_16x16x32_bf16 v[36:39], v[234:237], v[204:207], v[36:39]
	v_mfma_f32_16x16x32_bf16 v[32:35], v[234:237], v[208:211], v[32:35]
	s_waitcnt vmcnt(6)
	ds_write_b128 v152, v[192:195] offset:36864
	s_waitcnt lgkmcnt(7)
	v_mfma_f32_16x16x32_bf16 v[28:31], v[238:241], v[196:199], v[28:31]
	v_mfma_f32_16x16x32_bf16 v[24:27], v[238:241], v[200:203], v[24:27]
	v_mfma_f32_16x16x32_bf16 v[20:23], v[238:241], v[204:207], v[20:23]
	v_mfma_f32_16x16x32_bf16 v[16:19], v[238:241], v[208:211], v[16:19]
	s_waitcnt lgkmcnt(6)
	v_mfma_f32_16x16x32_bf16 v[12:15], v[242:245], v[196:199], v[12:15]
	v_mfma_f32_16x16x32_bf16 v[8:11], v[242:245], v[200:203], v[8:11]
	v_mfma_f32_16x16x32_bf16 v[4:7], v[242:245], v[204:207], v[4:7]
	v_mfma_f32_16x16x32_bf16 v[0:3], v[242:245], v[208:211], v[0:3]
	s_setprio 0
	s_add_i32 s1, s1, 2
	s_mov_b32 s10, s11
	s_add_i32 s11, s10, 64
	s_min_u32 s13, s11, 0x3e0
	s_lshl_b32 s16, s13, 1
	v_lshl_add_u64 v[172:173], v[154:155], 0, s[16:17]
	v_lshl_add_u64 v[176:177], v[158:159], 0, s[16:17]
	v_lshl_add_u64 v[180:181], v[160:161], 0, s[16:17]
	v_lshl_add_u64 v[184:185], v[162:163], 0, s[16:17]
	v_lshl_add_u64 v[188:189], v[156:157], 0, s[16:17]
	v_lshl_add_u64 v[192:193], v[164:165], 0, s[16:17]
	s_cmp_lt_u32 s1, 30
	s_waitcnt lgkmcnt(0)
	s_cbranch_scc1 .Lrot_2
	s_barrier
	s_waitcnt vmcnt(5)
	v_mov_b32_e32 v114, v220
	v_mov_b32_e32 v115, v153
	v_and_b32_e32 v112, 0xffffff80, v114
	s_waitcnt vmcnt(4)
	v_add_u32_e32 v116, s0, v112
	v_lshrrev_b32_e32 v112, 2, v114
	v_and_b32_e32 v118, 12, v112
	s_waitcnt vmcnt(3)
	v_or_b32_e32 v120, v118, v116
	v_ashrrev_i32_e32 v121, 31, v120
	v_lshl_add_u64 v[112:113], v[120:121], 2, s[14:15]
	global_load_dwordx4 v[132:135], v[112:113], off
	v_ashrrev_i32_e32 v122, 14, v116
	v_ashrrev_i32_e32 v123, 31, v122
	v_lshlrev_b64 v[122:123], 10, v[122:123]
	v_mov_b64_e32 v[112:113], s[34:35]
	s_waitcnt vmcnt(3)
	v_lshrrev_b32_e32 v126, 6, v116
	v_or_b32_e32 v124, 16, v120
	v_lshl_or_b32 v121, s12, 8, v122
	v_ashrrev_i32_e32 v125, 31, v124
	v_and_or_b32 v122, v126, s49, v121
	s_waitcnt vmcnt(1)
	v_lshl_add_u64 v[136:137], v[124:125], 2, s[14:15]
	global_load_dwordx4 v[246:249], v[136:137], off
	v_lshlrev_b64 v[124:125], 14, v[122:123]
	v_lshlrev_b32_e32 v114, 7, v114
	v_lshlrev_b32_e32 v152, 1, v118
	v_lshl_add_u64 v[124:125], s[38:39], 0, v[124:125]
	v_and_b32_e32 v114, 0x2780, v114
	v_lshl_add_u64 v[126:127], v[124:125], 0, v[152:153]
	v_mov_b32_e32 v117, v153
	v_mov_b32_e32 v119, v153
	v_or_b32_e32 v116, 0x1000, v114
	v_or_b32_e32 v118, 0x1800, v114
	v_lshl_add_u64 v[124:125], v[126:127], 0, v[114:115]
	v_lshl_add_u64 v[138:139], v[126:127], 0, v[116:117]
	v_lshl_add_u64 v[154:155], v[126:127], 0, v[118:119]
	s_waitcnt vmcnt(1)
	v_pk_fma_f32 v[132:133], v[132:133], s[30:31], v[112:113] op_sel_hi:[1,0,0]
	v_pk_fma_f32 v[134:135], v[134:135], s[30:31], v[112:113] op_sel_hi:[1,0,0]
	v_mul_f32_e32 v122, 0x4b800000, v132
	v_mul_f32_e32 v156, 0x4b800000, v133
	v_mul_f32_e32 v157, 0x4b800000, v134
	v_mul_f32_e32 v158, 0x4b800000, v135
	v_cmp_gt_f32_e32 vcc, s40, v132
	v_cmp_gt_f32_e64 s[0:1], s40, v133
	v_cmp_gt_f32_e64 s[10:11], s40, v134
	v_cmp_gt_f32_e64 s[12:13], s40, v135
	v_cndmask_b32_e32 v122, v132, v122, vcc
	v_cndmask_b32_e64 v132, v133, v156, s[0:1]
	v_cndmask_b32_e64 v133, v134, v157, s[10:11]
	v_cndmask_b32_e64 v134, v135, v158, s[12:13]
	v_rsq_f32_e32 v122, v122
	v_rsq_f32_e32 v132, v132
	v_rsq_f32_e32 v133, v133
	v_rsq_f32_e32 v134, v134
	v_mul_f32_e32 v135, 0x45800000, v122
	v_mul_f32_e32 v156, 0x45800000, v132
	v_mul_f32_e32 v157, 0x45800000, v133
	v_mul_f32_e32 v158, 0x45800000, v134
	v_cndmask_b32_e32 v122, v122, v135, vcc
	v_cndmask_b32_e64 v132, v132, v156, s[0:1]
	v_cndmask_b32_e64 v133, v133, v157, s[10:11]
	v_cndmask_b32_e64 v134, v134, v158, s[12:13]
	v_mul_f32_e32 v135, v148, v122
	v_mul_f32_e32 v148, v149, v132
	v_mul_f32_e32 v149, v150, v133
	v_mul_f32_e32 v150, v151, v134
	v_mul_f32_e32 v144, v144, v122
	v_mul_f32_e32 v140, v140, v122
	v_mul_f32_e32 v122, v128, v122
	v_mul_f32_e32 v151, v129, v132
	v_cvt_pk_bf16_f32 v128, v135, v148
	v_cvt_pk_bf16_f32 v129, v149, v150
	v_mul_f32_e32 v145, v145, v132
	v_mul_f32_e32 v146, v146, v133
	v_mul_f32_e32 v147, v147, v134
	v_mul_f32_e32 v141, v141, v132
	v_mul_f32_e32 v142, v142, v133
	v_mul_f32_e32 v143, v143, v134
	v_mul_f32_e32 v156, v130, v133
	v_mul_f32_e32 v157, v131, v134
	v_cvt_pk_bf16_f32 v130, v144, v145
	v_cvt_pk_bf16_f32 v131, v146, v147
	v_cvt_pk_bf16_f32 v132, v140, v141
	v_cvt_pk_bf16_f32 v133, v142, v143
	v_cvt_pk_bf16_f32 v134, v122, v151
	v_cvt_pk_bf16_f32 v135, v156, v157
	global_store_dwordx2 v[124:125], v[128:129], off
	global_store_dwordx2 v[124:125], v[130:131], off offset:2048
	global_store_dwordx2 v[138:139], v[132:133], off
	global_store_dwordx2 v[154:155], v[134:135], off
	v_or_b32_e32 v132, 32, v120
	v_ashrrev_i32_e32 v133, 31, v132
	v_lshl_add_u64 v[134:135], v[126:127], 0, 32
	v_lshl_add_u64 v[132:133], v[132:133], 2, s[14:15]
	global_load_dwordx4 v[250:253], v[132:133], off
	v_lshl_add_u64 v[136:137], v[134:135], 0, v[116:117]
	v_lshl_add_u64 v[134:135], v[134:135], 0, v[118:119]
	s_waitcnt vmcnt(5)
	v_mov_b32_e32 v128, v246
	v_mov_b32_e32 v129, v247
	v_mov_b32_e32 v130, v248
	v_mov_b32_e32 v131, v249
	v_pk_fma_f32 v[128:129], v[128:129], s[30:31], v[112:113] op_sel_hi:[1,0,0]
	v_pk_fma_f32 v[130:131], v[130:131], s[30:31], v[112:113] op_sel_hi:[1,0,0]
	v_mul_f32_e32 v122, 0x4b800000, v128
	v_mul_f32_e32 v138, 0x4b800000, v129
	v_mul_f32_e32 v139, 0x4b800000, v130
	v_mul_f32_e32 v140, 0x4b800000, v131
	v_cmp_gt_f32_e32 vcc, s40, v128
	v_cmp_gt_f32_e64 s[0:1], s40, v129
	v_cmp_gt_f32_e64 s[10:11], s40, v130
	v_cmp_gt_f32_e64 s[12:13], s40, v131
	v_cndmask_b32_e32 v122, v128, v122, vcc
	v_cndmask_b32_e64 v128, v129, v138, s[0:1]
	v_cndmask_b32_e64 v129, v130, v139, s[10:11]
	v_cndmask_b32_e64 v130, v131, v140, s[12:13]
	v_rsq_f32_e32 v122, v122
	v_rsq_f32_e32 v128, v128
	v_rsq_f32_e32 v129, v129
	v_rsq_f32_e32 v130, v130
	v_mul_f32_e32 v131, 0x45800000, v122
	v_mul_f32_e32 v138, 0x45800000, v128
	v_mul_f32_e32 v139, 0x45800000, v129
	v_mul_f32_e32 v140, 0x45800000, v130
	v_cndmask_b32_e32 v122, v122, v131, vcc
	v_cndmask_b32_e64 v128, v128, v138, s[0:1]
	v_cndmask_b32_e64 v129, v129, v139, s[10:11]
	v_cndmask_b32_e64 v130, v130, v140, s[12:13]
	v_mul_f32_e32 v108, v108, v122
	v_mul_f32_e32 v109, v109, v128
	v_mul_f32_e32 v110, v110, v129
	v_mul_f32_e32 v111, v111, v130
	v_mul_f32_e32 v104, v104, v122
	v_mul_f32_e32 v105, v105, v128
	v_mul_f32_e32 v100, v100, v122
	v_mul_f32_e32 v101, v101, v128
	v_mul_f32_e32 v102, v102, v129
	v_mul_f32_e32 v103, v103, v130
	v_mul_f32_e32 v122, v96, v122
	v_mul_f32_e32 v128, v97, v128
	v_cvt_pk_bf16_f32 v96, v108, v109
	v_cvt_pk_bf16_f32 v97, v110, v111
	v_mul_f32_e32 v106, v106, v129
	v_mul_f32_e32 v107, v107, v130
	v_mul_f32_e32 v129, v98, v129
	v_mul_f32_e32 v130, v99, v130
	v_cvt_pk_bf16_f32 v98, v104, v105
	v_cvt_pk_bf16_f32 v99, v106, v107
	v_cvt_pk_bf16_f32 v100, v100, v101
	v_cvt_pk_bf16_f32 v101, v102, v103
	v_cvt_pk_bf16_f32 v102, v122, v128
	v_cvt_pk_bf16_f32 v103, v129, v130
	global_store_dwordx2 v[124:125], v[96:97], off offset:32
	global_store_dwordx2 v[124:125], v[98:99], off offset:2080
	global_store_dwordx2 v[136:137], v[100:101], off
	global_store_dwordx2 v[134:135], v[102:103], off
	v_or_b32_e32 v100, 48, v120
	v_ashrrev_i32_e32 v101, 31, v100
	v_lshl_add_u64 v[102:103], v[126:127], 0, 64
	v_lshl_add_u64 v[100:101], v[100:101], 2, s[14:15]
	global_load_dwordx4 v[246:249], v[100:101], off
	v_lshl_add_u64 v[104:105], v[102:103], 0, v[116:117]
	v_lshl_add_u64 v[102:103], v[102:103], 0, v[118:119]
	s_waitcnt vmcnt(5)
	v_mov_b32_e32 v96, v250
	v_mov_b32_e32 v97, v251
	v_mov_b32_e32 v98, v252
	v_mov_b32_e32 v99, v253
	v_pk_fma_f32 v[96:97], v[96:97], s[30:31], v[112:113] op_sel_hi:[1,0,0]
	v_pk_fma_f32 v[98:99], v[98:99], s[30:31], v[112:113] op_sel_hi:[1,0,0]
	v_mul_f32_e32 v106, 0x4b800000, v96
	v_mul_f32_e32 v107, 0x4b800000, v97
	v_mul_f32_e32 v108, 0x4b800000, v98
	v_mul_f32_e32 v109, 0x4b800000, v99
	v_cmp_gt_f32_e32 vcc, s40, v96
	v_cmp_gt_f32_e64 s[0:1], s40, v97
	v_cmp_gt_f32_e64 s[10:11], s40, v98
	v_cmp_gt_f32_e64 s[12:13], s40, v99
	v_cndmask_b32_e32 v96, v96, v106, vcc
	v_cndmask_b32_e64 v97, v97, v107, s[0:1]
	v_cndmask_b32_e64 v98, v98, v108, s[10:11]
	v_cndmask_b32_e64 v99, v99, v109, s[12:13]
	v_rsq_f32_e32 v96, v96
	v_rsq_f32_e32 v97, v97
	v_rsq_f32_e32 v98, v98
	v_rsq_f32_e32 v99, v99
	v_mul_f32_e32 v106, 0x45800000, v96
	v_mul_f32_e32 v107, 0x45800000, v97
	v_mul_f32_e32 v108, 0x45800000, v98
	v_mul_f32_e32 v109, 0x45800000, v99
	v_cndmask_b32_e32 v96, v96, v106, vcc
	v_cndmask_b32_e64 v97, v97, v107, s[0:1]
	v_cndmask_b32_e64 v98, v98, v108, s[10:11]
	v_cndmask_b32_e64 v99, v99, v109, s[12:13]
	v_mul_f32_e32 v92, v92, v96
	v_mul_f32_e32 v93, v93, v97
	v_mul_f32_e32 v94, v94, v98
	v_mul_f32_e32 v95, v95, v99
	v_mul_f32_e32 v88, v88, v96
	v_mul_f32_e32 v89, v89, v97
	v_mul_f32_e32 v84, v84, v96
	v_mul_f32_e32 v85, v85, v97
	v_mul_f32_e32 v86, v86, v98
	v_mul_f32_e32 v87, v87, v99
	v_mul_f32_e32 v96, v80, v96
	v_mul_f32_e32 v97, v81, v97
	v_cvt_pk_bf16_f32 v80, v92, v93
	v_cvt_pk_bf16_f32 v81, v94, v95
	v_mul_f32_e32 v90, v90, v98
	v_mul_f32_e32 v91, v91, v99
	v_mul_f32_e32 v98, v82, v98
	v_mul_f32_e32 v99, v83, v99
	v_cvt_pk_bf16_f32 v82, v88, v89
	v_cvt_pk_bf16_f32 v83, v90, v91
	v_cvt_pk_bf16_f32 v84, v84, v85
	v_cvt_pk_bf16_f32 v85, v86, v87
	v_cvt_pk_bf16_f32 v86, v96, v97
	v_cvt_pk_bf16_f32 v87, v98, v99
	global_store_dwordx2 v[124:125], v[80:81], off offset:64
	global_store_dwordx2 v[124:125], v[82:83], off offset:2112
	global_store_dwordx2 v[104:105], v[84:85], off
	global_store_dwordx2 v[102:103], v[86:87], off
	v_or_b32_e32 v84, 64, v120
	v_ashrrev_i32_e32 v85, 31, v84
	v_lshl_add_u64 v[86:87], v[84:85], 2, s[14:15]
	global_load_dwordx4 v[250:253], v[86:87], off
	v_lshl_add_u64 v[88:89], v[126:127], 0, s[36:37]
	v_lshl_add_u64 v[90:91], v[88:89], 0, v[116:117]
	v_lshl_add_u64 v[88:89], v[88:89], 0, v[118:119]
	s_waitcnt vmcnt(5)
	v_mov_b32_e32 v80, v246
	v_mov_b32_e32 v81, v247
	v_mov_b32_e32 v82, v248
	v_mov_b32_e32 v83, v249
	v_pk_fma_f32 v[80:81], v[80:81], s[30:31], v[112:113] op_sel_hi:[1,0,0]
	v_pk_fma_f32 v[82:83], v[82:83], s[30:31], v[112:113] op_sel_hi:[1,0,0]
	v_mul_f32_e32 v85, 0x4b800000, v80
	v_mul_f32_e32 v92, 0x4b800000, v81
	v_mul_f32_e32 v93, 0x4b800000, v82
	v_mul_f32_e32 v94, 0x4b800000, v83
	v_cmp_gt_f32_e32 vcc, s40, v80
	v_cmp_gt_f32_e64 s[0:1], s40, v81
	v_cmp_gt_f32_e64 s[10:11], s40, v82
	v_cmp_gt_f32_e64 s[12:13], s40, v83
	v_cndmask_b32_e32 v80, v80, v85, vcc
	v_cndmask_b32_e64 v81, v81, v92, s[0:1]
	v_cndmask_b32_e64 v82, v82, v93, s[10:11]
	v_cndmask_b32_e64 v83, v83, v94, s[12:13]
	v_rsq_f32_e32 v80, v80
	v_rsq_f32_e32 v81, v81
	v_rsq_f32_e32 v82, v82
	v_rsq_f32_e32 v83, v83
	v_mul_f32_e32 v85, 0x45800000, v80
	v_mul_f32_e32 v92, 0x45800000, v81
	v_mul_f32_e32 v93, 0x45800000, v82
	v_mul_f32_e32 v94, 0x45800000, v83
	v_cndmask_b32_e32 v80, v80, v85, vcc
	v_cndmask_b32_e64 v81, v81, v92, s[0:1]
	v_cndmask_b32_e64 v82, v82, v93, s[10:11]
	v_cndmask_b32_e64 v83, v83, v94, s[12:13]
	v_mul_f32_e32 v76, v76, v80
	v_mul_f32_e32 v77, v77, v81
	v_mul_f32_e32 v78, v78, v82
	v_mul_f32_e32 v79, v79, v83
	v_mul_f32_e32 v72, v72, v80
	v_mul_f32_e32 v73, v73, v81
	v_mul_f32_e32 v68, v68, v80
	v_mul_f32_e32 v69, v69, v81
	v_mul_f32_e32 v70, v70, v82
	v_mul_f32_e32 v71, v71, v83
	v_mul_f32_e32 v80, v64, v80
	v_mul_f32_e32 v81, v65, v81
	v_cvt_pk_bf16_f32 v64, v76, v77
	v_cvt_pk_bf16_f32 v65, v78, v79
	v_mul_f32_e32 v74, v74, v82
	v_mul_f32_e32 v75, v75, v83
	v_mul_f32_e32 v82, v66, v82
	v_mul_f32_e32 v83, v67, v83
	v_cvt_pk_bf16_f32 v66, v72, v73
	v_cvt_pk_bf16_f32 v67, v74, v75
	v_cvt_pk_bf16_f32 v68, v68, v69
	v_cvt_pk_bf16_f32 v69, v70, v71
	v_cvt_pk_bf16_f32 v70, v80, v81
	v_cvt_pk_bf16_f32 v71, v82, v83
	global_store_dwordx2 v[124:125], v[64:65], off offset:96
	global_store_dwordx2 v[124:125], v[66:67], off offset:2144
	global_store_dwordx2 v[90:91], v[68:69], off
	global_store_dwordx2 v[88:89], v[70:71], off
	v_or_b32_e32 v68, 0x50, v120
	v_ashrrev_i32_e32 v69, 31, v68
	v_lshl_add_u64 v[70:71], v[68:69], 2, s[14:15]
	global_load_dwordx4 v[246:249], v[70:71], off
	v_lshrrev_b32_e32 v72, 6, v84
	v_and_or_b32 v122, v72, s50, v121
	v_lshlrev_b64 v[72:73], 14, v[122:123]
	v_lshl_add_u64 v[72:73], s[38:39], 0, v[72:73]
	v_lshl_add_u64 v[72:73], v[72:73], 0, v[152:153]
	v_lshl_add_u64 v[74:75], v[72:73], 0, v[114:115]
	v_lshl_add_u64 v[76:77], v[72:73], 0, v[116:117]
	v_lshl_add_u64 v[72:73], v[72:73], 0, v[118:119]
	s_waitcnt vmcnt(5)
	v_mov_b32_e32 v64, v250
	v_mov_b32_e32 v65, v251
	v_mov_b32_e32 v66, v252
	v_mov_b32_e32 v67, v253
	v_pk_fma_f32 v[64:65], v[64:65], s[30:31], v[112:113] op_sel_hi:[1,0,0]
	v_pk_fma_f32 v[66:67], v[66:67], s[30:31], v[112:113] op_sel_hi:[1,0,0]
	v_mul_f32_e32 v69, 0x4b800000, v64
	v_mul_f32_e32 v78, 0x4b800000, v65
	v_mul_f32_e32 v79, 0x4b800000, v66
	v_mul_f32_e32 v80, 0x4b800000, v67
	v_cmp_gt_f32_e32 vcc, s40, v64
	v_cmp_gt_f32_e64 s[0:1], s40, v65
	v_cmp_gt_f32_e64 s[10:11], s40, v66
	v_cmp_gt_f32_e64 s[12:13], s40, v67
	v_cndmask_b32_e32 v64, v64, v69, vcc
	v_cndmask_b32_e64 v65, v65, v78, s[0:1]
	v_cndmask_b32_e64 v66, v66, v79, s[10:11]
	v_cndmask_b32_e64 v67, v67, v80, s[12:13]
	v_rsq_f32_e32 v64, v64
	v_rsq_f32_e32 v65, v65
	v_rsq_f32_e32 v66, v66
	v_rsq_f32_e32 v67, v67
	v_mul_f32_e32 v69, 0x45800000, v64
	v_mul_f32_e32 v78, 0x45800000, v65
	v_mul_f32_e32 v79, 0x45800000, v66
	v_mul_f32_e32 v80, 0x45800000, v67
	v_cndmask_b32_e32 v64, v64, v69, vcc
	v_cndmask_b32_e64 v65, v65, v78, s[0:1]
	v_cndmask_b32_e64 v66, v66, v79, s[10:11]
	v_cndmask_b32_e64 v67, v67, v80, s[12:13]
	v_mul_f32_e32 v60, v60, v64
	v_mul_f32_e32 v61, v61, v65
	v_mul_f32_e32 v62, v62, v66
	v_mul_f32_e32 v63, v63, v67
	v_mul_f32_e32 v56, v56, v64
	v_mul_f32_e32 v57, v57, v65
	v_mul_f32_e32 v52, v52, v64
	v_mul_f32_e32 v53, v53, v65
	v_mul_f32_e32 v54, v54, v66
	v_mul_f32_e32 v55, v55, v67
	v_mul_f32_e32 v64, v48, v64
	v_mul_f32_e32 v65, v49, v65
	v_cvt_pk_bf16_f32 v48, v60, v61
	v_cvt_pk_bf16_f32 v49, v62, v63
	v_mul_f32_e32 v58, v58, v66
	v_mul_f32_e32 v59, v59, v67
	v_mul_f32_e32 v66, v50, v66
	v_mul_f32_e32 v67, v51, v67
	v_cvt_pk_bf16_f32 v50, v56, v57
	v_cvt_pk_bf16_f32 v51, v58, v59
	v_cvt_pk_bf16_f32 v52, v52, v53
	v_cvt_pk_bf16_f32 v53, v54, v55
	v_cvt_pk_bf16_f32 v54, v64, v65
	v_cvt_pk_bf16_f32 v55, v66, v67
	global_store_dwordx2 v[74:75], v[48:49], off
	global_store_dwordx2 v[74:75], v[50:51], off offset:2048
	global_store_dwordx2 v[76:77], v[52:53], off
	global_store_dwordx2 v[72:73], v[54:55], off
	v_or_b32_e32 v52, 0x60, v120
	v_ashrrev_i32_e32 v53, 31, v52
	v_lshl_add_u64 v[54:55], v[52:53], 2, s[14:15]
	global_load_dwordx4 v[250:253], v[54:55], off
	v_lshrrev_b32_e32 v56, 6, v68
	v_and_or_b32 v122, v56, s50, v121
	v_lshlrev_b64 v[56:57], 14, v[122:123]
	v_lshl_add_u64 v[56:57], s[38:39], 0, v[56:57]
	v_lshl_add_u64 v[56:57], v[56:57], 0, v[152:153]
	v_lshl_add_u64 v[58:59], v[56:57], 0, 32
	v_lshl_add_u64 v[56:57], v[56:57], 0, v[114:115]
	v_lshl_add_u64 v[60:61], v[58:59], 0, v[116:117]
	v_lshl_add_u64 v[58:59], v[58:59], 0, v[118:119]
	s_waitcnt vmcnt(5)
	v_mov_b32_e32 v48, v246
	v_mov_b32_e32 v49, v247
	v_mov_b32_e32 v50, v248
	v_mov_b32_e32 v51, v249
	v_pk_fma_f32 v[48:49], v[48:49], s[30:31], v[112:113] op_sel_hi:[1,0,0]
	v_pk_fma_f32 v[50:51], v[50:51], s[30:31], v[112:113] op_sel_hi:[1,0,0]
	v_mul_f32_e32 v53, 0x4b800000, v48
	v_mul_f32_e32 v62, 0x4b800000, v49
	v_mul_f32_e32 v63, 0x4b800000, v50
	v_mul_f32_e32 v64, 0x4b800000, v51
	v_cmp_gt_f32_e32 vcc, s40, v48
	v_cmp_gt_f32_e64 s[0:1], s40, v49
	v_cmp_gt_f32_e64 s[10:11], s40, v50
	v_cmp_gt_f32_e64 s[12:13], s40, v51
	v_cndmask_b32_e32 v48, v48, v53, vcc
	v_cndmask_b32_e64 v49, v49, v62, s[0:1]
	v_cndmask_b32_e64 v50, v50, v63, s[10:11]
	v_cndmask_b32_e64 v51, v51, v64, s[12:13]
	v_rsq_f32_e32 v48, v48
	v_rsq_f32_e32 v49, v49
	v_rsq_f32_e32 v50, v50
	v_rsq_f32_e32 v51, v51
	v_mul_f32_e32 v53, 0x45800000, v48
	v_mul_f32_e32 v62, 0x45800000, v49
	v_mul_f32_e32 v63, 0x45800000, v50
	v_mul_f32_e32 v64, 0x45800000, v51
	v_cndmask_b32_e32 v48, v48, v53, vcc
	v_cndmask_b32_e64 v49, v49, v62, s[0:1]
	v_cndmask_b32_e64 v50, v50, v63, s[10:11]
	v_cndmask_b32_e64 v51, v51, v64, s[12:13]
	v_mul_f32_e32 v44, v44, v48
	v_mul_f32_e32 v45, v45, v49
	v_mul_f32_e32 v46, v46, v50
	v_mul_f32_e32 v47, v47, v51
	v_mul_f32_e32 v40, v40, v48
	v_mul_f32_e32 v41, v41, v49
	v_mul_f32_e32 v36, v36, v48
	v_mul_f32_e32 v37, v37, v49
	v_mul_f32_e32 v38, v38, v50
	v_mul_f32_e32 v39, v39, v51
	v_mul_f32_e32 v48, v32, v48
	v_mul_f32_e32 v49, v33, v49
	v_cvt_pk_bf16_f32 v32, v44, v45
	v_cvt_pk_bf16_f32 v33, v46, v47
	v_mul_f32_e32 v42, v42, v50
	v_mul_f32_e32 v43, v43, v51
	v_mul_f32_e32 v50, v34, v50
	v_mul_f32_e32 v51, v35, v51
	v_cvt_pk_bf16_f32 v34, v40, v41
	v_cvt_pk_bf16_f32 v35, v42, v43
	v_cvt_pk_bf16_f32 v36, v36, v37
	v_cvt_pk_bf16_f32 v37, v38, v39
	v_cvt_pk_bf16_f32 v38, v48, v49
	v_cvt_pk_bf16_f32 v39, v50, v51
	global_store_dwordx2 v[56:57], v[32:33], off offset:32
	global_store_dwordx2 v[56:57], v[34:35], off offset:2080
	global_store_dwordx2 v[60:61], v[36:37], off
	global_store_dwordx2 v[58:59], v[38:39], off
	v_or_b32_e32 v36, 0x70, v120
	v_ashrrev_i32_e32 v37, 31, v36
	v_lshl_add_u64 v[38:39], v[36:37], 2, s[14:15]
	global_load_dwordx4 v[246:249], v[38:39], off
	v_lshrrev_b32_e32 v40, 6, v52
	v_and_or_b32 v122, v40, s50, v121
	v_lshlrev_b64 v[40:41], 14, v[122:123]
	v_lshl_add_u64 v[40:41], s[38:39], 0, v[40:41]
	v_lshl_add_u64 v[40:41], v[40:41], 0, v[152:153]
	v_lshl_add_u64 v[42:43], v[40:41], 0, 64
	v_lshl_add_u64 v[40:41], v[40:41], 0, v[114:115]
	v_lshl_add_u64 v[44:45], v[42:43], 0, v[116:117]
	v_lshl_add_u64 v[42:43], v[42:43], 0, v[118:119]
	s_waitcnt vmcnt(5)
	v_mov_b32_e32 v32, v250
	v_mov_b32_e32 v33, v251
	v_mov_b32_e32 v34, v252
	v_mov_b32_e32 v35, v253
	v_pk_fma_f32 v[32:33], v[32:33], s[30:31], v[112:113] op_sel_hi:[1,0,0]
	v_pk_fma_f32 v[34:35], v[34:35], s[30:31], v[112:113] op_sel_hi:[1,0,0]
	v_mul_f32_e32 v37, 0x4b800000, v32
	v_mul_f32_e32 v46, 0x4b800000, v33
	v_mul_f32_e32 v47, 0x4b800000, v34
	v_mul_f32_e32 v48, 0x4b800000, v35
	v_cmp_gt_f32_e32 vcc, s40, v32
	v_cmp_gt_f32_e64 s[0:1], s40, v33
	v_cmp_gt_f32_e64 s[10:11], s40, v34
	v_cmp_gt_f32_e64 s[12:13], s40, v35
	v_cndmask_b32_e32 v32, v32, v37, vcc
	v_cndmask_b32_e64 v33, v33, v46, s[0:1]
	v_cndmask_b32_e64 v34, v34, v47, s[10:11]
	v_cndmask_b32_e64 v35, v35, v48, s[12:13]
	v_rsq_f32_e32 v32, v32
	v_rsq_f32_e32 v33, v33
	v_rsq_f32_e32 v34, v34
	v_rsq_f32_e32 v35, v35
	v_mul_f32_e32 v37, 0x45800000, v32
	v_mul_f32_e32 v46, 0x45800000, v33
	v_mul_f32_e32 v47, 0x45800000, v34
	v_mul_f32_e32 v48, 0x45800000, v35
	v_cndmask_b32_e32 v32, v32, v37, vcc
	v_cndmask_b32_e64 v33, v33, v46, s[0:1]
	v_cndmask_b32_e64 v34, v34, v47, s[10:11]
	v_cndmask_b32_e64 v35, v35, v48, s[12:13]
	v_mul_f32_e32 v28, v28, v32
	v_mul_f32_e32 v29, v29, v33
	v_mul_f32_e32 v30, v30, v34
	v_mul_f32_e32 v31, v31, v35
	v_mul_f32_e32 v24, v24, v32
	v_mul_f32_e32 v25, v25, v33
	v_mul_f32_e32 v20, v20, v32
	v_mul_f32_e32 v21, v21, v33
	v_mul_f32_e32 v22, v22, v34
	v_mul_f32_e32 v23, v23, v35
	v_mul_f32_e32 v32, v16, v32
	v_mul_f32_e32 v33, v17, v33
	v_cvt_pk_bf16_f32 v16, v28, v29
	v_cvt_pk_bf16_f32 v17, v30, v31
	v_mul_f32_e32 v26, v26, v34
	v_mul_f32_e32 v27, v27, v35
	v_mul_f32_e32 v34, v18, v34
	v_mul_f32_e32 v35, v19, v35
	v_cvt_pk_bf16_f32 v18, v24, v25
	v_cvt_pk_bf16_f32 v19, v26, v27
	v_cvt_pk_bf16_f32 v20, v20, v21
	v_cvt_pk_bf16_f32 v21, v22, v23
	v_cvt_pk_bf16_f32 v22, v32, v33
	v_cvt_pk_bf16_f32 v23, v34, v35
	global_store_dwordx2 v[40:41], v[16:17], off offset:64
	global_store_dwordx2 v[40:41], v[18:19], off offset:2112
	global_store_dwordx2 v[44:45], v[20:21], off
	global_store_dwordx2 v[42:43], v[22:23], off
	v_lshrrev_b32_e32 v20, 6, v36
	v_and_or_b32 v122, v20, s50, v121
	v_lshlrev_b64 v[20:21], 14, v[122:123]
	v_lshl_add_u64 v[20:21], s[38:39], 0, v[20:21]
	v_lshl_add_u64 v[20:21], v[20:21], 0, v[152:153]
	v_lshl_add_u64 v[22:23], v[20:21], 0, s[36:37]
	v_lshl_add_u64 v[20:21], v[20:21], 0, v[114:115]
	v_lshl_add_u64 v[24:25], v[22:23], 0, v[116:117]
	v_lshl_add_u64 v[22:23], v[22:23], 0, v[118:119]
	s_waitcnt vmcnt(4)
	v_mov_b32_e32 v16, v246
	v_mov_b32_e32 v17, v247
	v_mov_b32_e32 v18, v248
	v_mov_b32_e32 v19, v249
	v_pk_fma_f32 v[16:17], v[16:17], s[30:31], v[112:113] op_sel_hi:[1,0,0]
	v_pk_fma_f32 v[18:19], v[18:19], s[30:31], v[112:113] op_sel_hi:[1,0,0]
	v_mul_f32_e32 v26, 0x4b800000, v16
	v_mul_f32_e32 v27, 0x4b800000, v17
	v_mul_f32_e32 v28, 0x4b800000, v18
	v_mul_f32_e32 v29, 0x4b800000, v19
	v_cmp_gt_f32_e32 vcc, s40, v16
	v_cmp_gt_f32_e64 s[0:1], s40, v17
	v_cmp_gt_f32_e64 s[10:11], s40, v18
	v_cmp_gt_f32_e64 s[12:13], s40, v19
	v_cndmask_b32_e32 v16, v16, v26, vcc
	v_cndmask_b32_e64 v17, v17, v27, s[0:1]
	v_cndmask_b32_e64 v18, v18, v28, s[10:11]
	v_cndmask_b32_e64 v19, v19, v29, s[12:13]
	v_rsq_f32_e32 v16, v16
	v_rsq_f32_e32 v17, v17
	v_rsq_f32_e32 v18, v18
	v_rsq_f32_e32 v19, v19
	v_mul_f32_e32 v26, 0x45800000, v16
	v_mul_f32_e32 v27, 0x45800000, v17
	v_mul_f32_e32 v28, 0x45800000, v18
	v_mul_f32_e32 v29, 0x45800000, v19
	v_cndmask_b32_e32 v16, v16, v26, vcc
	v_cndmask_b32_e64 v17, v17, v27, s[0:1]
	v_cndmask_b32_e64 v18, v18, v28, s[10:11]
	v_cndmask_b32_e64 v19, v19, v29, s[12:13]
	v_mul_f32_e32 v12, v12, v16
	v_mul_f32_e32 v13, v13, v17
	v_mul_f32_e32 v14, v14, v18
	v_mul_f32_e32 v15, v15, v19
	v_mul_f32_e32 v8, v8, v16
	v_mul_f32_e32 v9, v9, v17
	v_mul_f32_e32 v4, v4, v16
	v_mul_f32_e32 v5, v5, v17
	v_mul_f32_e32 v6, v6, v18
	v_mul_f32_e32 v7, v7, v19
	v_mul_f32_e32 v16, v0, v16
	v_mul_f32_e32 v17, v1, v17
	v_cvt_pk_bf16_f32 v0, v12, v13
	v_cvt_pk_bf16_f32 v1, v14, v15
	v_mul_f32_e32 v10, v10, v18
	v_mul_f32_e32 v11, v11, v19
	v_mul_f32_e32 v18, v2, v18
	v_mul_f32_e32 v19, v3, v19
	v_cvt_pk_bf16_f32 v2, v8, v9
	v_cvt_pk_bf16_f32 v3, v10, v11
	v_cvt_pk_bf16_f32 v4, v4, v5
	v_cvt_pk_bf16_f32 v5, v6, v7
	v_cvt_pk_bf16_f32 v6, v16, v17
	v_cvt_pk_bf16_f32 v7, v18, v19
	global_store_dwordx2 v[20:21], v[0:1], off offset:96
	global_store_dwordx2 v[20:21], v[2:3], off offset:2144
	global_store_dwordx2 v[24:25], v[4:5], off
	global_store_dwordx2 v[22:23], v[6:7], off
	s_branch .LBB0_699

.LBB0_769:
	ds_read_b128 v[196:199], v171 offset:32768
	ds_read_b128 v[200:203], v171 offset:33792
	ds_read_b128 v[204:207], v171 offset:34816
	ds_read_b128 v[208:211], v171 offset:35840
	ds_read_b128 v[212:215], v169
	global_load_dwordx4 v[172:175], v[172:173], off
	ds_read_b128 v[216:219], v169 offset:1024
	global_load_dwordx4 v[176:179], v[176:177], off
	ds_read_b128 v[222:225], v169 offset:2048
	global_load_dwordx4 v[180:183], v[180:181], off
	ds_read_b128 v[226:229], v169 offset:3072
	global_load_dwordx4 v[184:187], v[184:185], off
	ds_read_b128 v[230:233], v169 offset:4096
	global_load_dwordx4 v[188:191], v[188:189], off
	ds_read_b128 v[234:237], v169 offset:5120
	global_load_dwordx4 v[192:195], v[192:193], off
	ds_read_b128 v[238:241], v169 offset:6144
	ds_read_b128 v[242:245], v169 offset:7168
	s_setprio 1
	s_waitcnt lgkmcnt(7)
	v_mfma_f32_16x16x32_bf16 v[148:151], v[196:199], v[212:215], v[148:151]
	v_mfma_f32_16x16x32_bf16 v[144:147], v[200:203], v[212:215], v[144:147]
	v_mfma_f32_16x16x32_bf16 v[116:119], v[204:207], v[212:215], v[116:119]
	v_mfma_f32_16x16x32_bf16 v[112:115], v[208:211], v[212:215], v[112:115]
	s_waitcnt vmcnt(11)
	ds_write_b128 v152, v[120:123] offset:16384
	s_waitcnt lgkmcnt(7)
	v_mfma_f32_16x16x32_bf16 v[108:111], v[196:199], v[216:219], v[108:111]
	v_mfma_f32_16x16x32_bf16 v[104:107], v[200:203], v[216:219], v[104:107]
	v_mfma_f32_16x16x32_bf16 v[100:103], v[204:207], v[216:219], v[100:103]
	v_mfma_f32_16x16x32_bf16 v[96:99], v[208:211], v[216:219], v[96:99]
	s_waitcnt vmcnt(9)
	ds_write_b128 v152, v[128:131] offset:20480
	s_waitcnt lgkmcnt(7)
	v_mfma_f32_16x16x32_bf16 v[92:95], v[196:199], v[222:225], v[92:95]
	v_mfma_f32_16x16x32_bf16 v[88:91], v[200:203], v[222:225], v[88:91]
	v_mfma_f32_16x16x32_bf16 v[84:87], v[204:207], v[222:225], v[84:87]
	v_mfma_f32_16x16x32_bf16 v[80:83], v[208:211], v[222:225], v[80:83]
	s_waitcnt vmcnt(8)
	ds_write_b128 v152, v[132:135] offset:24576
	s_waitcnt lgkmcnt(7)
	v_mfma_f32_16x16x32_bf16 v[76:79], v[196:199], v[226:229], v[76:79]
	v_mfma_f32_16x16x32_bf16 v[72:75], v[200:203], v[226:229], v[72:75]
	v_mfma_f32_16x16x32_bf16 v[68:71], v[204:207], v[226:229], v[68:71]
	v_mfma_f32_16x16x32_bf16 v[64:67], v[208:211], v[226:229], v[64:67]
	s_waitcnt vmcnt(7)
	ds_write_b128 v152, v[136:139] offset:28672
	s_waitcnt lgkmcnt(7)
	v_mfma_f32_16x16x32_bf16 v[60:63], v[196:199], v[230:233], v[60:63]
	v_mfma_f32_16x16x32_bf16 v[56:59], v[200:203], v[230:233], v[56:59]
	v_mfma_f32_16x16x32_bf16 v[52:55], v[204:207], v[230:233], v[52:55]
	v_mfma_f32_16x16x32_bf16 v[48:51], v[208:211], v[230:233], v[48:51]
	s_waitcnt vmcnt(7)
	ds_write_b128 v152, v[124:127] offset:40960
	s_waitcnt lgkmcnt(7)
	v_mfma_f32_16x16x32_bf16 v[44:47], v[196:199], v[234:237], v[44:47]
	v_mfma_f32_16x16x32_bf16 v[40:43], v[200:203], v[234:237], v[40:43]
	v_mfma_f32_16x16x32_bf16 v[36:39], v[204:207], v[234:237], v[36:39]
	v_mfma_f32_16x16x32_bf16 v[32:35], v[208:211], v[234:237], v[32:35]
	s_waitcnt vmcnt(6)
	ds_write_b128 v152, v[140:143] offset:45056
	s_waitcnt lgkmcnt(7)
	v_mfma_f32_16x16x32_bf16 v[28:31], v[196:199], v[238:241], v[28:31]
	v_mfma_f32_16x16x32_bf16 v[24:27], v[200:203], v[238:241], v[24:27]
	v_mfma_f32_16x16x32_bf16 v[20:23], v[204:207], v[238:241], v[20:23]
	v_mfma_f32_16x16x32_bf16 v[16:19], v[208:211], v[238:241], v[16:19]
	s_waitcnt lgkmcnt(6)
	v_mfma_f32_16x16x32_bf16 v[12:15], v[196:199], v[242:245], v[12:15]
	v_mfma_f32_16x16x32_bf16 v[8:11], v[200:203], v[242:245], v[8:11]
	v_mfma_f32_16x16x32_bf16 v[4:7], v[204:207], v[242:245], v[4:7]
	v_mfma_f32_16x16x32_bf16 v[0:3], v[208:211], v[242:245], v[0:3]
	s_setprio 0
	s_min_u32 s13, s13, 0x380
	s_lshl_b32 s34, s13, 1
	s_mov_b32 s17, s35
	s_add_i32 s16, s34, 0xc0
	v_lshl_add_u64 v[120:121], v[154:155], 0, s[34:35]
	v_lshl_add_u64 v[124:125], v[156:157], 0, s[34:35]
	v_lshl_add_u64 v[128:129], v[158:159], 0, s[16:17]
	v_lshl_add_u64 v[132:133], v[160:161], 0, s[16:17]
	v_lshl_add_u64 v[136:137], v[162:163], 0, s[16:17]
	v_lshl_add_u64 v[140:141], v[164:165], 0, s[16:17]
	s_waitcnt lgkmcnt(0)
	s_barrier
	ds_read_b128 v[196:199], v168 offset:40960
	ds_read_b128 v[200:203], v168 offset:41984
	ds_read_b128 v[204:207], v168 offset:43008
	ds_read_b128 v[208:211], v168 offset:44032
	ds_read_b128 v[212:215], v170
	global_load_dwordx4 v[120:123], v[120:121], off offset:192
	ds_read_b128 v[216:219], v170 offset:1024
	global_load_dwordx4 v[124:127], v[124:125], off offset:192
	ds_read_b128 v[222:225], v170 offset:2048
	global_load_dwordx4 v[128:131], v[128:129], off
	ds_read_b128 v[226:229], v170 offset:3072
	global_load_dwordx4 v[132:135], v[132:133], off
	ds_read_b128 v[230:233], v170 offset:4096
	global_load_dwordx4 v[136:139], v[136:137], off
	ds_read_b128 v[234:237], v170 offset:5120
	global_load_dwordx4 v[140:143], v[140:141], off
	ds_read_b128 v[238:241], v170 offset:6144
	ds_read_b128 v[242:245], v170 offset:7168
	s_setprio 1
	s_waitcnt lgkmcnt(7)
	v_mfma_f32_16x16x32_bf16 v[148:151], v[196:199], v[212:215], v[148:151]
	v_mfma_f32_16x16x32_bf16 v[144:147], v[200:203], v[212:215], v[144:147]
	v_mfma_f32_16x16x32_bf16 v[116:119], v[204:207], v[212:215], v[116:119]
	v_mfma_f32_16x16x32_bf16 v[112:115], v[208:211], v[212:215], v[112:115]
	s_waitcnt vmcnt(11)
	ds_write_b128 v152, v[172:175]
	s_waitcnt lgkmcnt(7)
	v_mfma_f32_16x16x32_bf16 v[108:111], v[196:199], v[216:219], v[108:111]
	v_mfma_f32_16x16x32_bf16 v[104:107], v[200:203], v[216:219], v[104:107]
	v_mfma_f32_16x16x32_bf16 v[100:103], v[204:207], v[216:219], v[100:103]
	v_mfma_f32_16x16x32_bf16 v[96:99], v[208:211], v[216:219], v[96:99]
	s_waitcnt vmcnt(10)
	ds_write_b128 v152, v[176:179] offset:4096
	s_waitcnt lgkmcnt(7)
	v_mfma_f32_16x16x32_bf16 v[92:95], v[196:199], v[222:225], v[92:95]
	v_mfma_f32_16x16x32_bf16 v[88:91], v[200:203], v[222:225], v[88:91]
	v_mfma_f32_16x16x32_bf16 v[84:87], v[204:207], v[222:225], v[84:87]
	v_mfma_f32_16x16x32_bf16 v[80:83], v[208:211], v[222:225], v[80:83]
	s_waitcnt vmcnt(9)
	ds_write_b128 v152, v[180:183] offset:8192
	s_waitcnt lgkmcnt(7)
	v_mfma_f32_16x16x32_bf16 v[76:79], v[196:199], v[226:229], v[76:79]
	v_mfma_f32_16x16x32_bf16 v[72:75], v[200:203], v[226:229], v[72:75]
	v_mfma_f32_16x16x32_bf16 v[68:71], v[204:207], v[226:229], v[68:71]
	v_mfma_f32_16x16x32_bf16 v[64:67], v[208:211], v[226:229], v[64:67]
	s_waitcnt vmcnt(8)
	ds_write_b128 v152, v[184:187] offset:12288
	s_waitcnt lgkmcnt(7)
	v_mfma_f32_16x16x32_bf16 v[60:63], v[196:199], v[230:233], v[60:63]
	v_mfma_f32_16x16x32_bf16 v[56:59], v[200:203], v[230:233], v[56:59]
	v_mfma_f32_16x16x32_bf16 v[52:55], v[204:207], v[230:233], v[52:55]
	v_mfma_f32_16x16x32_bf16 v[48:51], v[208:211], v[230:233], v[48:51]
	s_waitcnt vmcnt(7)
	ds_write_b128 v152, v[188:191] offset:32768
	s_waitcnt lgkmcnt(7)
	v_mfma_f32_16x16x32_bf16 v[44:47], v[196:199], v[234:237], v[44:47]
	v_mfma_f32_16x16x32_bf16 v[40:43], v[200:203], v[234:237], v[40:43]
	v_mfma_f32_16x16x32_bf16 v[36:39], v[204:207], v[234:237], v[36:39]
	v_mfma_f32_16x16x32_bf16 v[32:35], v[208:211], v[234:237], v[32:35]
	s_waitcnt vmcnt(6)
	ds_write_b128 v152, v[192:195] offset:36864
	s_waitcnt lgkmcnt(7)
	v_mfma_f32_16x16x32_bf16 v[28:31], v[196:199], v[238:241], v[28:31]
	v_mfma_f32_16x16x32_bf16 v[24:27], v[200:203], v[238:241], v[24:27]
	v_mfma_f32_16x16x32_bf16 v[20:23], v[204:207], v[238:241], v[20:23]
	v_mfma_f32_16x16x32_bf16 v[16:19], v[208:211], v[238:241], v[16:19]
	s_waitcnt lgkmcnt(6)
	v_mfma_f32_16x16x32_bf16 v[12:15], v[196:199], v[242:245], v[12:15]
	v_mfma_f32_16x16x32_bf16 v[8:11], v[200:203], v[242:245], v[8:11]
	v_mfma_f32_16x16x32_bf16 v[4:7], v[204:207], v[242:245], v[4:7]
	v_mfma_f32_16x16x32_bf16 v[0:3], v[208:211], v[242:245], v[0:3]
	s_setprio 0
	s_add_i32 s11, s11, 2
	s_mov_b32 s13, s14
	s_add_i32 s14, s13, 64
	s_min_u32 s15, s14, 0x3e0
	s_lshl_b32 s34, s15, 1
	v_lshl_add_u64 v[172:173], v[154:155], 0, s[34:35]
	v_lshl_add_u64 v[176:177], v[158:159], 0, s[34:35]
	v_lshl_add_u64 v[180:181], v[160:161], 0, s[34:35]
	v_lshl_add_u64 v[184:185], v[162:163], 0, s[34:35]
	v_lshl_add_u64 v[188:189], v[156:157], 0, s[34:35]
	v_lshl_add_u64 v[192:193], v[164:165], 0, s[34:35]
	s_cmp_lt_u32 s11, 30
	s_waitcnt lgkmcnt(0)
	s_cbranch_scc1 .Lrot_1
	s_barrier
	s_waitcnt vmcnt(4)
	v_mov_b32_e32 v126, v220
	v_mov_b64_e32 v[124:125], s[72:73]
	v_and_b32_e32 v120, 0xffffff80, v126
	v_add_u32_e32 v120, s12, v120
	v_and_or_b32 v122, v126, 15, v120
	v_ashrrev_i32_e32 v123, 31, v122
	v_lshl_add_u64 v[120:121], v[122:123], 2, s[0:1]
	global_load_dword v246, v[120:121], off offset:64
	global_load_dword v247, v[120:121], off offset:128
	global_load_dword v248, v[120:121], off offset:192
	global_load_dword v249, v[120:121], off offset:256
	global_load_dword v250, v[120:121], off offset:320
	global_load_dword v251, v[120:121], off offset:384
	global_load_dword v252, v[120:121], off offset:448
	global_load_dword v120, v[120:121], off
	v_and_b32_e32 v121, 64, v126
	v_lshrrev_b32_e32 v126, 2, v126
	v_and_b32_e32 v126, 12, v126
	s_waitcnt vmcnt(0)
	v_fmamk_f32 v120, v120, 0x3a800000, v167
	v_mul_f32_e32 v127, 0x4b800000, v120
	v_cmp_gt_f32_e32 vcc, s42, v120
	s_nop 1
	v_cndmask_b32_e32 v120, v120, v127, vcc
	v_rsq_f32_e32 v127, v120
	v_or3_b32 v120, v121, v126, s10
	v_mad_i64_i32 v[124:125], s[10:11], v122, s41, v[124:125]
	v_mul_f32_e32 v121, 0x45800000, v127
	v_cndmask_b32_e32 v129, v127, v121, vcc
	v_mul_f32_e32 v132, v148, v129
	v_mul_f32_e32 v131, v149, v129
	v_mul_f32_e32 v130, v150, v129
	v_mul_f32_e32 v128, v151, v129
	v_cmp_lt_i32_e64 s[10:11], s43, v120
	s_and_saveexec_b64 s[12:13], s[10:11]
	s_xor_b64 s[12:13], exec, s[12:13]
	s_cbranch_execz .LBB0_774
	v_cmp_gt_u32_e32 vcc, s44, v120
	s_and_saveexec_b64 s[14:15], vcc
	s_cbranch_execz .LBB0_773
	v_mul_f32_e32 v121, 0xbfb8aa3b, v132
	v_exp_f32_e32 v121, v121
	v_mul_f32_e32 v126, 0xbfb8aa3b, v131
	v_mul_f32_e32 v127, 0xbfb8aa3b, v128
	v_exp_f32_e32 v126, v126
	v_add_f32_e32 v121, 1.0, v121
	v_rcp_f32_e32 v132, v121
	v_mul_f32_e32 v121, 0xbfb8aa3b, v130
	v_exp_f32_e32 v121, v121
	v_exp_f32_e32 v127, v127
	v_add_f32_e32 v126, 1.0, v126
	v_rcp_f32_e32 v133, v126
	v_add_f32_e32 v121, 1.0, v121
	v_rcp_f32_e32 v134, v121
	v_add_f32_e32 v121, 1.0, v127
	v_rcp_f32_e32 v135, v121
	v_mov_b32_e32 v121, v153
	v_lshl_add_u64 v[126:127], v[120:121], 2, v[124:125]
	v_add_co_u32_e32 v126, vcc, 0x2ffe000, v126
	s_nop 1
	v_addc_co_u32_e32 v127, vcc, 0, v127, vcc
	global_store_dwordx4 v[126:127], v[132:135], off

.LBB0_1737:
	ds_read_b128 v[196:199], v171 offset:32768
	ds_read_b128 v[200:203], v171 offset:33792
	ds_read_b128 v[204:207], v171 offset:34816
	ds_read_b128 v[208:211], v171 offset:35840
	ds_read_b128 v[212:215], v169
	global_load_dwordx4 v[172:175], v[172:173], off
	ds_read_b128 v[216:219], v169 offset:1024
	global_load_dwordx4 v[176:179], v[176:177], off
	ds_read_b128 v[222:225], v169 offset:2048
	global_load_dwordx4 v[180:183], v[180:181], off
	ds_read_b128 v[226:229], v169 offset:3072
	global_load_dwordx4 v[184:187], v[184:185], off
	ds_read_b128 v[230:233], v169 offset:4096
	global_load_dwordx4 v[188:191], v[188:189], off
	ds_read_b128 v[234:237], v169 offset:5120
	global_load_dwordx4 v[192:195], v[192:193], off
	ds_read_b128 v[238:241], v169 offset:6144
	ds_read_b128 v[242:245], v169 offset:7168
	s_setprio 1
	s_waitcnt lgkmcnt(7)
	v_mfma_f32_16x16x32_bf16 v[148:151], v[196:199], v[212:215], v[148:151]
	v_mfma_f32_16x16x32_bf16 v[144:147], v[200:203], v[212:215], v[144:147]
	v_mfma_f32_16x16x32_bf16 v[116:119], v[204:207], v[212:215], v[116:119]
	v_mfma_f32_16x16x32_bf16 v[112:115], v[208:211], v[212:215], v[112:115]
	s_waitcnt vmcnt(11)
	ds_write_b128 v152, v[120:123] offset:16384
	s_waitcnt lgkmcnt(7)
	v_mfma_f32_16x16x32_bf16 v[108:111], v[196:199], v[216:219], v[108:111]
	v_mfma_f32_16x16x32_bf16 v[104:107], v[200:203], v[216:219], v[104:107]
	v_mfma_f32_16x16x32_bf16 v[100:103], v[204:207], v[216:219], v[100:103]
	v_mfma_f32_16x16x32_bf16 v[96:99], v[208:211], v[216:219], v[96:99]
	s_waitcnt vmcnt(9)
	ds_write_b128 v152, v[124:127] offset:20480
	s_waitcnt lgkmcnt(7)
	v_mfma_f32_16x16x32_bf16 v[92:95], v[196:199], v[222:225], v[92:95]
	v_mfma_f32_16x16x32_bf16 v[88:91], v[200:203], v[222:225], v[88:91]
	v_mfma_f32_16x16x32_bf16 v[84:87], v[204:207], v[222:225], v[84:87]
	v_mfma_f32_16x16x32_bf16 v[80:83], v[208:211], v[222:225], v[80:83]
	s_waitcnt vmcnt(8)
	ds_write_b128 v152, v[128:131] offset:24576
	s_waitcnt lgkmcnt(7)
	v_mfma_f32_16x16x32_bf16 v[76:79], v[196:199], v[226:229], v[76:79]
	v_mfma_f32_16x16x32_bf16 v[72:75], v[200:203], v[226:229], v[72:75]
	v_mfma_f32_16x16x32_bf16 v[68:71], v[204:207], v[226:229], v[68:71]
	v_mfma_f32_16x16x32_bf16 v[64:67], v[208:211], v[226:229], v[64:67]
	s_waitcnt vmcnt(7)
	ds_write_b128 v152, v[136:139] offset:28672
	s_waitcnt lgkmcnt(7)
	v_mfma_f32_16x16x32_bf16 v[60:63], v[196:199], v[230:233], v[60:63]
	v_mfma_f32_16x16x32_bf16 v[56:59], v[200:203], v[230:233], v[56:59]
	v_mfma_f32_16x16x32_bf16 v[52:55], v[204:207], v[230:233], v[52:55]
	v_mfma_f32_16x16x32_bf16 v[48:51], v[208:211], v[230:233], v[48:51]
	s_waitcnt vmcnt(6)
	ds_write_b128 v152, v[140:143] offset:45056
	s_waitcnt lgkmcnt(7)
	v_mfma_f32_16x16x32_bf16 v[44:47], v[196:199], v[234:237], v[44:47]
	v_mfma_f32_16x16x32_bf16 v[40:43], v[200:203], v[234:237], v[40:43]
	v_mfma_f32_16x16x32_bf16 v[36:39], v[204:207], v[234:237], v[36:39]
	v_mfma_f32_16x16x32_bf16 v[32:35], v[208:211], v[234:237], v[32:35]
	ds_write_b128 v152, v[132:135] offset:40960
	s_waitcnt lgkmcnt(7)
	v_mfma_f32_16x16x32_bf16 v[28:31], v[196:199], v[238:241], v[28:31]
	v_mfma_f32_16x16x32_bf16 v[24:27], v[200:203], v[238:241], v[24:27]
	v_mfma_f32_16x16x32_bf16 v[20:23], v[204:207], v[238:241], v[20:23]
	v_mfma_f32_16x16x32_bf16 v[16:19], v[208:211], v[238:241], v[16:19]
	s_waitcnt lgkmcnt(6)
	v_mfma_f32_16x16x32_bf16 v[12:15], v[196:199], v[242:245], v[12:15]
	v_mfma_f32_16x16x32_bf16 v[8:11], v[200:203], v[242:245], v[8:11]
	v_mfma_f32_16x16x32_bf16 v[4:7], v[204:207], v[242:245], v[4:7]
	v_mfma_f32_16x16x32_bf16 v[0:3], v[208:211], v[242:245], v[0:3]
	s_setprio 0
	s_min_u32 s12, s25, 0x380
	s_lshl_b32 s12, s12, 1
	s_mov_b32 s29, s13
	s_add_i32 s28, s12, 0xc0
	v_lshl_add_u64 v[120:121], v[154:155], 0, s[12:13]
	v_lshl_add_u64 v[124:125], v[156:157], 0, s[12:13]
	v_lshl_add_u64 v[126:127], v[158:159], 0, s[28:29]
	v_lshl_add_u64 v[128:129], v[160:161], 0, s[28:29]
	v_lshl_add_u64 v[136:137], v[162:163], 0, s[28:29]
	v_lshl_add_u64 v[140:141], v[164:165], 0, s[28:29]
	s_waitcnt lgkmcnt(0)
	s_barrier
	ds_read_b128 v[196:199], v168 offset:40960
	ds_read_b128 v[200:203], v168 offset:41984
	ds_read_b128 v[204:207], v168 offset:43008
	ds_read_b128 v[208:211], v168 offset:44032
	ds_read_b128 v[212:215], v170
	global_load_dwordx4 v[120:123], v[120:121], off offset:192
	ds_read_b128 v[216:219], v170 offset:1024
	global_load_dwordx4 v[132:135], v[124:125], off offset:192
	ds_read_b128 v[222:225], v170 offset:2048
	global_load_dwordx4 v[124:127], v[126:127], off
	ds_read_b128 v[226:229], v170 offset:3072
	global_load_dwordx4 v[128:131], v[128:129], off
	ds_read_b128 v[230:233], v170 offset:4096
	global_load_dwordx4 v[136:139], v[136:137], off
	ds_read_b128 v[234:237], v170 offset:5120
	global_load_dwordx4 v[140:143], v[140:141], off
	ds_read_b128 v[238:241], v170 offset:6144
	ds_read_b128 v[242:245], v170 offset:7168
	s_setprio 1
	s_waitcnt lgkmcnt(7)
	v_mfma_f32_16x16x32_bf16 v[148:151], v[196:199], v[212:215], v[148:151]
	v_mfma_f32_16x16x32_bf16 v[144:147], v[200:203], v[212:215], v[144:147]
	v_mfma_f32_16x16x32_bf16 v[116:119], v[204:207], v[212:215], v[116:119]
	v_mfma_f32_16x16x32_bf16 v[112:115], v[208:211], v[212:215], v[112:115]
	s_waitcnt vmcnt(11)
	ds_write_b128 v152, v[172:175]
	s_waitcnt lgkmcnt(7)
	v_mfma_f32_16x16x32_bf16 v[108:111], v[196:199], v[216:219], v[108:111]
	v_mfma_f32_16x16x32_bf16 v[104:107], v[200:203], v[216:219], v[104:107]
	v_mfma_f32_16x16x32_bf16 v[100:103], v[204:207], v[216:219], v[100:103]
	v_mfma_f32_16x16x32_bf16 v[96:99], v[208:211], v[216:219], v[96:99]
	s_waitcnt vmcnt(10)
	ds_write_b128 v152, v[176:179] offset:4096
	s_waitcnt lgkmcnt(7)
	v_mfma_f32_16x16x32_bf16 v[92:95], v[196:199], v[222:225], v[92:95]
	v_mfma_f32_16x16x32_bf16 v[88:91], v[200:203], v[222:225], v[88:91]
	v_mfma_f32_16x16x32_bf16 v[84:87], v[204:207], v[222:225], v[84:87]
	v_mfma_f32_16x16x32_bf16 v[80:83], v[208:211], v[222:225], v[80:83]
	s_waitcnt vmcnt(9)
	ds_write_b128 v152, v[180:183] offset:8192
	s_waitcnt lgkmcnt(7)
	v_mfma_f32_16x16x32_bf16 v[76:79], v[196:199], v[226:229], v[76:79]
	v_mfma_f32_16x16x32_bf16 v[72:75], v[200:203], v[226:229], v[72:75]
	v_mfma_f32_16x16x32_bf16 v[68:71], v[204:207], v[226:229], v[68:71]
	v_mfma_f32_16x16x32_bf16 v[64:67], v[208:211], v[226:229], v[64:67]
	s_waitcnt vmcnt(8)
	ds_write_b128 v152, v[184:187] offset:12288
	s_waitcnt lgkmcnt(7)
	v_mfma_f32_16x16x32_bf16 v[60:63], v[196:199], v[230:233], v[60:63]
	v_mfma_f32_16x16x32_bf16 v[56:59], v[200:203], v[230:233], v[56:59]
	v_mfma_f32_16x16x32_bf16 v[52:55], v[204:207], v[230:233], v[52:55]
	v_mfma_f32_16x16x32_bf16 v[48:51], v[208:211], v[230:233], v[48:51]
	s_waitcnt vmcnt(7)
	ds_write_b128 v152, v[188:191] offset:32768
	s_waitcnt lgkmcnt(7)
	v_mfma_f32_16x16x32_bf16 v[44:47], v[196:199], v[234:237], v[44:47]
	v_mfma_f32_16x16x32_bf16 v[40:43], v[200:203], v[234:237], v[40:43]
	v_mfma_f32_16x16x32_bf16 v[36:39], v[204:207], v[234:237], v[36:39]
	v_mfma_f32_16x16x32_bf16 v[32:35], v[208:211], v[234:237], v[32:35]
	s_waitcnt vmcnt(6)
	ds_write_b128 v152, v[192:195] offset:36864
	s_waitcnt lgkmcnt(7)
	v_mfma_f32_16x16x32_bf16 v[28:31], v[196:199], v[238:241], v[28:31]
	v_mfma_f32_16x16x32_bf16 v[24:27], v[200:203], v[238:241], v[24:27]
	v_mfma_f32_16x16x32_bf16 v[20:23], v[204:207], v[238:241], v[20:23]
	v_mfma_f32_16x16x32_bf16 v[16:19], v[208:211], v[238:241], v[16:19]
	s_waitcnt lgkmcnt(6)
	v_mfma_f32_16x16x32_bf16 v[12:15], v[196:199], v[242:245], v[12:15]
	v_mfma_f32_16x16x32_bf16 v[8:11], v[200:203], v[242:245], v[8:11]
	v_mfma_f32_16x16x32_bf16 v[4:7], v[204:207], v[242:245], v[4:7]
	v_mfma_f32_16x16x32_bf16 v[0:3], v[208:211], v[242:245], v[0:3]
	s_setprio 0
	s_add_i32 s21, s21, 2
	s_mov_b32 s25, s26
	s_add_i32 s26, s25, 64
	s_min_u32 s12, s26, 0x3e0
	s_lshl_b32 s12, s12, 1
	v_lshl_add_u64 v[172:173], v[154:155], 0, s[12:13]
	v_lshl_add_u64 v[176:177], v[158:159], 0, s[12:13]
	v_lshl_add_u64 v[180:181], v[160:161], 0, s[12:13]
	v_lshl_add_u64 v[184:185], v[162:163], 0, s[12:13]
	v_lshl_add_u64 v[188:189], v[156:157], 0, s[12:13]
	v_lshl_add_u64 v[192:193], v[164:165], 0, s[12:13]
	s_cmp_lt_u32 s21, 30
	s_waitcnt lgkmcnt(0)
	s_cbranch_scc1 .Lrot_0
	s_barrier
	s_waitcnt vmcnt(5)
	v_mov_b32_e32 v120, v220
	s_nop 0
	v_and_b32_e32 v122, 0xffffff80, v120
	v_add_u32_e32 v122, s20, v122
	v_and_b32_e32 v121, 64, v120
	v_and_or_b32 v122, v120, 15, v122
	v_lshrrev_b32_e32 v120, 2, v120
	v_and_b32_e32 v120, 12, v120
	v_or3_b32 v120, v121, v120, s24
	v_ashrrev_i32_e32 v121, 31, v120
	v_ashrrev_i32_e32 v123, 31, v122
	v_lshl_add_u64 v[120:121], v[120:121], 1, s[10:11]
	s_waitcnt vmcnt(3)
	v_lshl_add_u64 v[124:125], v[122:123], 2, s[0:1]
	v_lshlrev_b64 v[126:127], 12, v[122:123]
	v_lshl_add_u64 v[162:163], v[120:121], 0, v[126:127]
	global_load_dword v152, v[124:125], off
	global_load_dwordx2 v[168:169], v[162:163], off
	global_load_dwordx2 v[170:171], v[162:163], off offset:32
	global_load_dwordx2 v[172:173], v[162:163], off offset:64
	v_or_b32_e32 v124, 16, v122
	v_ashrrev_i32_e32 v125, 31, v124
	v_lshl_add_u64 v[126:127], v[124:125], 2, s[0:1]
	v_lshlrev_b64 v[124:125], 12, v[124:125]
	s_waitcnt vmcnt(4)
	v_lshl_add_u64 v[142:143], v[120:121], 0, v[124:125]
	v_or_b32_e32 v124, 32, v122
	v_ashrrev_i32_e32 v125, 31, v124
	global_load_dwordx2 v[174:175], v[162:163], off offset:96
	global_load_dword v176, v[126:127], off
	global_load_dwordx2 v[164:165], v[142:143], off
	global_load_dwordx2 v[160:161], v[142:143], off offset:32
	v_lshl_add_u64 v[126:127], v[124:125], 2, s[0:1]
	v_lshlrev_b64 v[124:125], 12, v[124:125]
	v_lshl_add_u64 v[132:133], v[120:121], 0, v[124:125]
	v_or_b32_e32 v124, 48, v122
	v_ashrrev_i32_e32 v125, 31, v124
	global_load_dwordx2 v[158:159], v[142:143], off offset:64
	global_load_dwordx2 v[156:157], v[142:143], off offset:96
	global_load_dword v177, v[126:127], off
	global_load_dwordx2 v[154:155], v[132:133], off
	v_lshl_add_u64 v[126:127], v[124:125], 2, s[0:1]
	v_lshlrev_b64 v[124:125], 12, v[124:125]
	v_lshl_add_u64 v[124:125], v[120:121], 0, v[124:125]
	global_load_dwordx2 v[140:141], v[132:133], off offset:32
	global_load_dwordx2 v[138:139], v[132:133], off offset:64
	global_load_dwordx2 v[136:137], v[132:133], off offset:96
	global_load_dword v123, v[126:127], off
	global_load_dwordx2 v[134:135], v[124:125], off
	global_load_dwordx2 v[130:131], v[124:125], off offset:32
	global_load_dwordx2 v[128:129], v[124:125], off offset:64
	s_nop 0
	global_load_dwordx2 v[126:127], v[124:125], off offset:96
	s_waitcnt vmcnt(19)
	v_fmamk_f32 v152, v152, 0x3a800000, v167
	v_mul_f32_e32 v178, 0x4b800000, v152
	v_cmp_gt_f32_e32 vcc, s22, v152
	s_nop 1
	v_cndmask_b32_e32 v152, v152, v178, vcc
	v_rsq_f32_e32 v152, v152
	s_waitcnt vmcnt(18)
	v_lshlrev_b32_e32 v178, 16, v168
	v_and_b32_e32 v168, 0xffff0000, v168
	v_mul_f32_e32 v179, 0x45800000, v152
	v_cndmask_b32_e32 v152, v152, v179, vcc
	v_mul_f32_e32 v148, v148, v152
	v_mul_f32_e32 v180, 0xbfb8aa3b, v148
	v_exp_f32_e32 v180, v180
	v_mul_f32_e32 v149, v149, v152
	v_mul_f32_e32 v181, 0xbfb8aa3b, v149
	v_exp_f32_e32 v181, v181
	v_add_f32_e32 v180, 1.0, v180
	v_rcp_f32_e32 v180, v180
	v_mul_f32_e32 v150, v150, v152
	v_mul_f32_e32 v151, v151, v152
	v_lshlrev_b32_e32 v179, 16, v169
	v_mul_f32_e32 v148, v148, v180
	v_mul_f32_e32 v148, v148, v178
	v_add_f32_e32 v178, 1.0, v181
	v_mul_f32_e32 v180, 0xbfb8aa3b, v150
	v_mul_f32_e32 v181, 0xbfb8aa3b, v151
	v_rcp_f32_e32 v178, v178
	v_exp_f32_e32 v180, v180
	v_exp_f32_e32 v181, v181
	v_and_b32_e32 v169, 0xffff0000, v169
	v_mul_f32_e32 v149, v149, v178
	v_add_f32_e32 v178, 1.0, v180
	v_add_f32_e32 v180, 1.0, v181
	v_rcp_f32_e32 v180, v180
	v_rcp_f32_e32 v178, v178
	v_mul_f32_e32 v149, v149, v168
	v_mul_f32_e32 v144, v144, v152
	v_mul_f32_e32 v151, v151, v180
	v_mul_f32_e32 v150, v150, v178
	v_mul_f32_e32 v151, v151, v169
	v_mul_f32_e32 v150, v150, v179
	v_cvt_pk_bf16_f32 v148, v148, v149
	v_cvt_pk_bf16_f32 v149, v150, v151
	v_mul_f32_e32 v151, 0xbfb8aa3b, v144
	v_exp_f32_e32 v151, v151
	v_mul_f32_e32 v145, v145, v152
	v_mul_f32_e32 v169, 0xbfb8aa3b, v145
	v_exp_f32_e32 v169, v169
	v_add_f32_e32 v151, 1.0, v151
	v_rcp_f32_e32 v151, v151
	global_store_dwordx2 v[162:163], v[148:149], off
	s_waitcnt vmcnt(18)
	v_lshlrev_b32_e32 v148, 16, v170
	v_mul_f32_e32 v146, v146, v152
	v_mul_f32_e32 v147, v147, v152
	v_mul_f32_e32 v144, v144, v151
	v_mul_f32_e32 v144, v144, v148
	v_add_f32_e32 v148, 1.0, v169
	v_mul_f32_e32 v151, 0xbfb8aa3b, v146
	v_mul_f32_e32 v169, 0xbfb8aa3b, v147
	v_rcp_f32_e32 v148, v148
	v_exp_f32_e32 v151, v151
	v_exp_f32_e32 v169, v169
	v_and_b32_e32 v149, 0xffff0000, v170
	v_mul_f32_e32 v145, v145, v148
	v_add_f32_e32 v148, 1.0, v151
	v_add_f32_e32 v151, 1.0, v169
	v_rcp_f32_e32 v151, v151
	v_rcp_f32_e32 v148, v148
	v_and_b32_e32 v168, 0xffff0000, v171
	v_lshlrev_b32_e32 v150, 16, v171
	v_mul_f32_e32 v147, v147, v151
	v_mul_f32_e32 v145, v145, v149
	v_mul_f32_e32 v146, v146, v148
	v_mul_f32_e32 v147, v147, v168
	v_mul_f32_e32 v116, v116, v152
	v_mul_f32_e32 v146, v146, v150
	v_cvt_pk_bf16_f32 v144, v144, v145
	v_cvt_pk_bf16_f32 v145, v146, v147
	v_mul_f32_e32 v147, 0xbfb8aa3b, v116
	v_exp_f32_e32 v147, v147
	v_mul_f32_e32 v117, v117, v152
	v_mul_f32_e32 v149, 0xbfb8aa3b, v117
	v_exp_f32_e32 v149, v149
	v_add_f32_e32 v147, 1.0, v147
	v_rcp_f32_e32 v147, v147
	global_store_dwordx2 v[162:163], v[144:145], off offset:32
	s_waitcnt vmcnt(18)
	v_lshlrev_b32_e32 v144, 16, v172
	v_mul_f32_e32 v118, v118, v152
	v_mul_f32_e32 v119, v119, v152
	v_mul_f32_e32 v116, v116, v147
	v_mul_f32_e32 v116, v116, v144
	v_add_f32_e32 v144, 1.0, v149
	v_mul_f32_e32 v147, 0xbfb8aa3b, v118
	v_mul_f32_e32 v149, 0xbfb8aa3b, v119
	v_rcp_f32_e32 v144, v144
	v_exp_f32_e32 v147, v147
	v_exp_f32_e32 v149, v149
	v_and_b32_e32 v145, 0xffff0000, v172
	v_mul_f32_e32 v117, v117, v144
	v_add_f32_e32 v144, 1.0, v147
	v_add_f32_e32 v147, 1.0, v149
	v_rcp_f32_e32 v147, v147
	v_rcp_f32_e32 v144, v144
	v_and_b32_e32 v148, 0xffff0000, v173
	v_lshlrev_b32_e32 v146, 16, v173
	v_mul_f32_e32 v119, v119, v147
	v_mul_f32_e32 v117, v117, v145
	v_mul_f32_e32 v118, v118, v144
	v_mul_f32_e32 v119, v119, v148
	v_mul_f32_e32 v112, v112, v152
	v_mul_f32_e32 v118, v118, v146
	v_cvt_pk_bf16_f32 v116, v116, v117
	v_cvt_pk_bf16_f32 v117, v118, v119
	v_mul_f32_e32 v119, 0xbfb8aa3b, v112
	v_exp_f32_e32 v119, v119
	v_mul_f32_e32 v113, v113, v152
	v_mul_f32_e32 v145, 0xbfb8aa3b, v113
	v_exp_f32_e32 v145, v145
	v_add_f32_e32 v119, 1.0, v119
	v_rcp_f32_e32 v119, v119
	global_store_dwordx2 v[162:163], v[116:117], off offset:64
	s_waitcnt vmcnt(18)
	v_lshlrev_b32_e32 v116, 16, v174
	v_mul_f32_e32 v114, v114, v152
	v_mul_f32_e32 v112, v112, v119
	v_mul_f32_e32 v112, v112, v116
	v_add_f32_e32 v116, 1.0, v145
	v_mul_f32_e32 v119, 0xbfb8aa3b, v114
	v_rcp_f32_e32 v116, v116
	v_exp_f32_e32 v119, v119
	v_mul_f32_e32 v115, v115, v152
	v_mul_f32_e32 v145, 0xbfb8aa3b, v115
	v_mul_f32_e32 v113, v113, v116
	v_add_f32_e32 v116, 1.0, v119
	v_rcp_f32_e32 v116, v116
	v_exp_f32_e32 v145, v145
	v_and_b32_e32 v117, 0xffff0000, v174
	v_mul_f32_e32 v113, v113, v117
	v_mul_f32_e32 v114, v114, v116
	s_waitcnt vmcnt(17)
	v_fmamk_f32 v116, v176, 0x3a800000, v167
	v_add_f32_e32 v119, 1.0, v145
	v_mul_f32_e32 v117, 0x4b800000, v116
	v_cmp_gt_f32_e32 vcc, s22, v116
	v_rcp_f32_e32 v119, v119
	v_lshlrev_b32_e32 v118, 16, v175
	v_cndmask_b32_e32 v116, v116, v117, vcc
	v_rsq_f32_e32 v116, v116
	v_and_b32_e32 v144, 0xffff0000, v175
	v_mul_f32_e32 v115, v115, v119
	v_cvt_pk_bf16_f32 v112, v112, v113
	v_mul_f32_e32 v114, v114, v118
	v_mul_f32_e32 v115, v115, v144
	v_cvt_pk_bf16_f32 v113, v114, v115
	global_store_dwordx2 v[162:163], v[112:113], off offset:96
	v_mul_f32_e32 v112, 0x45800000, v116
	v_cndmask_b32_e32 v112, v116, v112, vcc
	v_mul_f32_e32 v108, v108, v112
	v_mul_f32_e32 v116, 0xbfb8aa3b, v108
	v_exp_f32_e32 v116, v116
	v_mul_f32_e32 v109, v109, v112
	v_mul_f32_e32 v118, 0xbfb8aa3b, v109
	v_exp_f32_e32 v118, v118
	v_add_f32_e32 v116, 1.0, v116
	v_rcp_f32_e32 v116, v116
	s_waitcnt vmcnt(17)
	v_lshlrev_b32_e32 v113, 16, v164
	v_mul_f32_e32 v110, v110, v112
	v_mul_f32_e32 v111, v111, v112
	v_mul_f32_e32 v108, v108, v116
	v_mul_f32_e32 v108, v108, v113
	v_add_f32_e32 v113, 1.0, v118
	v_mul_f32_e32 v116, 0xbfb8aa3b, v110
	v_mul_f32_e32 v118, 0xbfb8aa3b, v111
	v_rcp_f32_e32 v113, v113
	v_exp_f32_e32 v116, v116
	v_exp_f32_e32 v118, v118
	v_and_b32_e32 v114, 0xffff0000, v164
	v_mul_f32_e32 v109, v109, v113
	v_add_f32_e32 v113, 1.0, v116
	v_add_f32_e32 v116, 1.0, v118
	v_rcp_f32_e32 v116, v116
	v_rcp_f32_e32 v113, v113
	v_and_b32_e32 v117, 0xffff0000, v165
	v_lshlrev_b32_e32 v115, 16, v165
	v_mul_f32_e32 v111, v111, v116
	v_mul_f32_e32 v109, v109, v114
	v_mul_f32_e32 v110, v110, v113
	v_mul_f32_e32 v111, v111, v117
	v_mul_f32_e32 v104, v104, v112
	v_mul_f32_e32 v110, v110, v115
	v_cvt_pk_bf16_f32 v108, v108, v109
	v_cvt_pk_bf16_f32 v109, v110, v111
	v_mul_f32_e32 v111, 0xbfb8aa3b, v104
	v_exp_f32_e32 v111, v111
	v_mul_f32_e32 v105, v105, v112
	v_mul_f32_e32 v114, 0xbfb8aa3b, v105
	v_exp_f32_e32 v114, v114
	v_add_f32_e32 v111, 1.0, v111
	v_rcp_f32_e32 v111, v111
	global_store_dwordx2 v[142:143], v[108:109], off
	s_waitcnt vmcnt(17)
	v_lshlrev_b32_e32 v108, 16, v160
	v_mul_f32_e32 v106, v106, v112
	v_mul_f32_e32 v107, v107, v112
	v_mul_f32_e32 v104, v104, v111
	v_mul_f32_e32 v104, v104, v108
	v_add_f32_e32 v108, 1.0, v114
	v_mul_f32_e32 v111, 0xbfb8aa3b, v106
	v_mul_f32_e32 v114, 0xbfb8aa3b, v107
	v_rcp_f32_e32 v108, v108
	v_exp_f32_e32 v111, v111
	v_exp_f32_e32 v114, v114
	v_and_b32_e32 v109, 0xffff0000, v160
	v_mul_f32_e32 v105, v105, v108
	v_add_f32_e32 v108, 1.0, v111
	v_add_f32_e32 v111, 1.0, v114
	v_rcp_f32_e32 v111, v111
	v_rcp_f32_e32 v108, v108
	v_and_b32_e32 v113, 0xffff0000, v161
	v_lshlrev_b32_e32 v110, 16, v161
	v_mul_f32_e32 v107, v107, v111
	v_mul_f32_e32 v105, v105, v109
	v_mul_f32_e32 v106, v106, v108
	v_mul_f32_e32 v107, v107, v113
	v_mul_f32_e32 v100, v100, v112
	v_mul_f32_e32 v106, v106, v110
	v_cvt_pk_bf16_f32 v104, v104, v105
	v_cvt_pk_bf16_f32 v105, v106, v107
	v_mul_f32_e32 v107, 0xbfb8aa3b, v100
	v_exp_f32_e32 v107, v107
	v_mul_f32_e32 v101, v101, v112
	v_mul_f32_e32 v109, 0xbfb8aa3b, v101
	v_exp_f32_e32 v109, v109
	v_add_f32_e32 v107, 1.0, v107
	v_rcp_f32_e32 v107, v107
	global_store_dwordx2 v[142:143], v[104:105], off offset:32
	s_waitcnt vmcnt(17)
	v_lshlrev_b32_e32 v104, 16, v158
	v_mul_f32_e32 v102, v102, v112
	v_mul_f32_e32 v103, v103, v112
	v_mul_f32_e32 v100, v100, v107
	v_mul_f32_e32 v100, v100, v104
	v_add_f32_e32 v104, 1.0, v109
	v_mul_f32_e32 v107, 0xbfb8aa3b, v102
	v_mul_f32_e32 v109, 0xbfb8aa3b, v103
	v_rcp_f32_e32 v104, v104
	v_exp_f32_e32 v107, v107
	v_exp_f32_e32 v109, v109
	v_and_b32_e32 v105, 0xffff0000, v158
	v_mul_f32_e32 v101, v101, v104
	v_add_f32_e32 v104, 1.0, v107
	v_add_f32_e32 v107, 1.0, v109
	v_rcp_f32_e32 v107, v107
	v_rcp_f32_e32 v104, v104
	v_and_b32_e32 v108, 0xffff0000, v159
	v_lshlrev_b32_e32 v106, 16, v159
	v_mul_f32_e32 v103, v103, v107
	v_mul_f32_e32 v101, v101, v105
	v_mul_f32_e32 v102, v102, v104
	v_mul_f32_e32 v103, v103, v108
	v_mul_f32_e32 v96, v96, v112
	v_mul_f32_e32 v102, v102, v106
	v_cvt_pk_bf16_f32 v100, v100, v101
	v_cvt_pk_bf16_f32 v101, v102, v103
	v_mul_f32_e32 v103, 0xbfb8aa3b, v96
	v_exp_f32_e32 v103, v103
	v_mul_f32_e32 v97, v97, v112
	v_mul_f32_e32 v105, 0xbfb8aa3b, v97
	v_exp_f32_e32 v105, v105
	v_add_f32_e32 v103, 1.0, v103
	v_rcp_f32_e32 v103, v103
	global_store_dwordx2 v[142:143], v[100:101], off offset:64
	s_waitcnt vmcnt(17)
	v_lshlrev_b32_e32 v100, 16, v156
	v_mul_f32_e32 v98, v98, v112
	v_mul_f32_e32 v96, v96, v103
	v_mul_f32_e32 v96, v96, v100
	v_add_f32_e32 v100, 1.0, v105
	v_mul_f32_e32 v103, 0xbfb8aa3b, v98
	v_rcp_f32_e32 v100, v100
	v_exp_f32_e32 v103, v103
	v_mul_f32_e32 v99, v99, v112
	v_mul_f32_e32 v105, 0xbfb8aa3b, v99
	v_mul_f32_e32 v97, v97, v100
	v_add_f32_e32 v100, 1.0, v103
	v_rcp_f32_e32 v100, v100
	v_exp_f32_e32 v105, v105
	v_and_b32_e32 v101, 0xffff0000, v156
	v_mul_f32_e32 v97, v97, v101
	v_mul_f32_e32 v98, v98, v100
	s_waitcnt vmcnt(16)
	v_fmamk_f32 v100, v177, 0x3a800000, v167
	v_add_f32_e32 v103, 1.0, v105
	v_mul_f32_e32 v101, 0x4b800000, v100
	v_cmp_gt_f32_e32 vcc, s22, v100
	v_rcp_f32_e32 v103, v103
	v_lshlrev_b32_e32 v102, 16, v157
	v_cndmask_b32_e32 v100, v100, v101, vcc
	v_rsq_f32_e32 v100, v100
	v_and_b32_e32 v104, 0xffff0000, v157
	v_mul_f32_e32 v99, v99, v103
	v_cvt_pk_bf16_f32 v96, v96, v97
	v_mul_f32_e32 v98, v98, v102
	v_mul_f32_e32 v99, v99, v104
	v_cvt_pk_bf16_f32 v97, v98, v99
	global_store_dwordx2 v[142:143], v[96:97], off offset:96
	v_mul_f32_e32 v96, 0x45800000, v100
	v_cndmask_b32_e32 v96, v100, v96, vcc
	v_mul_f32_e32 v92, v92, v96
	v_mul_f32_e32 v100, 0xbfb8aa3b, v92
	v_exp_f32_e32 v100, v100
	v_mul_f32_e32 v93, v93, v96
	v_mul_f32_e32 v102, 0xbfb8aa3b, v93
	v_exp_f32_e32 v102, v102
	v_add_f32_e32 v100, 1.0, v100
	v_rcp_f32_e32 v100, v100
	s_waitcnt vmcnt(16)
	v_lshlrev_b32_e32 v97, 16, v154
	v_mul_f32_e32 v94, v94, v96
	v_mul_f32_e32 v95, v95, v96
	v_mul_f32_e32 v92, v92, v100
	v_mul_f32_e32 v92, v92, v97
	v_add_f32_e32 v97, 1.0, v102
	v_mul_f32_e32 v100, 0xbfb8aa3b, v94
	v_mul_f32_e32 v102, 0xbfb8aa3b, v95
	v_rcp_f32_e32 v97, v97
	v_exp_f32_e32 v100, v100
	v_exp_f32_e32 v102, v102
	v_and_b32_e32 v98, 0xffff0000, v154
	v_mul_f32_e32 v93, v93, v97
	v_add_f32_e32 v97, 1.0, v100
	v_add_f32_e32 v100, 1.0, v102
	v_rcp_f32_e32 v100, v100
	v_rcp_f32_e32 v97, v97
	v_and_b32_e32 v101, 0xffff0000, v155
	v_lshlrev_b32_e32 v99, 16, v155
	v_mul_f32_e32 v95, v95, v100
	v_mul_f32_e32 v93, v93, v98
	v_mul_f32_e32 v94, v94, v97
	v_mul_f32_e32 v95, v95, v101
	v_mul_f32_e32 v88, v88, v96
	v_mul_f32_e32 v94, v94, v99
	v_cvt_pk_bf16_f32 v92, v92, v93
	v_cvt_pk_bf16_f32 v93, v94, v95
	v_mul_f32_e32 v95, 0xbfb8aa3b, v88
	v_exp_f32_e32 v95, v95
	v_mul_f32_e32 v89, v89, v96
	v_mul_f32_e32 v98, 0xbfb8aa3b, v89
	v_exp_f32_e32 v98, v98
	v_add_f32_e32 v95, 1.0, v95
	v_rcp_f32_e32 v95, v95
	global_store_dwordx2 v[132:133], v[92:93], off
	s_waitcnt vmcnt(16)
	v_lshlrev_b32_e32 v92, 16, v140
	v_mul_f32_e32 v90, v90, v96
	v_mul_f32_e32 v91, v91, v96
	v_mul_f32_e32 v88, v88, v95
	v_mul_f32_e32 v88, v88, v92
	v_add_f32_e32 v92, 1.0, v98
	v_mul_f32_e32 v95, 0xbfb8aa3b, v90
	v_mul_f32_e32 v98, 0xbfb8aa3b, v91
	v_rcp_f32_e32 v92, v92
	v_exp_f32_e32 v95, v95
	v_exp_f32_e32 v98, v98
	v_and_b32_e32 v93, 0xffff0000, v140
	v_mul_f32_e32 v89, v89, v92
	v_add_f32_e32 v92, 1.0, v95
	v_add_f32_e32 v95, 1.0, v98
	v_rcp_f32_e32 v95, v95
	v_rcp_f32_e32 v92, v92
	v_and_b32_e32 v97, 0xffff0000, v141
	v_lshlrev_b32_e32 v94, 16, v141
	v_mul_f32_e32 v91, v91, v95
	v_mul_f32_e32 v89, v89, v93
	v_mul_f32_e32 v90, v90, v92
	v_mul_f32_e32 v91, v91, v97
	v_mul_f32_e32 v84, v84, v96
	v_mul_f32_e32 v90, v90, v94
	v_cvt_pk_bf16_f32 v88, v88, v89
	v_cvt_pk_bf16_f32 v89, v90, v91
	v_mul_f32_e32 v91, 0xbfb8aa3b, v84
	v_exp_f32_e32 v91, v91
	v_mul_f32_e32 v85, v85, v96
	v_mul_f32_e32 v93, 0xbfb8aa3b, v85
	v_exp_f32_e32 v93, v93
	v_add_f32_e32 v91, 1.0, v91
	v_rcp_f32_e32 v91, v91
	global_store_dwordx2 v[132:133], v[88:89], off offset:32
	s_waitcnt vmcnt(16)
	v_lshlrev_b32_e32 v88, 16, v138
	v_mul_f32_e32 v86, v86, v96
	v_mul_f32_e32 v87, v87, v96
	v_mul_f32_e32 v84, v84, v91
	v_mul_f32_e32 v84, v84, v88
	v_add_f32_e32 v88, 1.0, v93
	v_mul_f32_e32 v91, 0xbfb8aa3b, v86
	v_mul_f32_e32 v93, 0xbfb8aa3b, v87
	v_rcp_f32_e32 v88, v88
	v_exp_f32_e32 v91, v91
	v_exp_f32_e32 v93, v93
	v_and_b32_e32 v89, 0xffff0000, v138
	v_mul_f32_e32 v85, v85, v88
	v_add_f32_e32 v88, 1.0, v91
	v_add_f32_e32 v91, 1.0, v93
	v_rcp_f32_e32 v91, v91
	v_rcp_f32_e32 v88, v88
	v_and_b32_e32 v92, 0xffff0000, v139
	v_lshlrev_b32_e32 v90, 16, v139
	v_mul_f32_e32 v87, v87, v91
	v_mul_f32_e32 v85, v85, v89
	v_mul_f32_e32 v86, v86, v88
	v_mul_f32_e32 v87, v87, v92
	v_mul_f32_e32 v80, v80, v96
	v_mul_f32_e32 v86, v86, v90
	v_cvt_pk_bf16_f32 v84, v84, v85
	v_cvt_pk_bf16_f32 v85, v86, v87
	v_mul_f32_e32 v87, 0xbfb8aa3b, v80
	v_exp_f32_e32 v87, v87
	v_mul_f32_e32 v81, v81, v96
	v_mul_f32_e32 v89, 0xbfb8aa3b, v81
	v_exp_f32_e32 v89, v89
	v_add_f32_e32 v87, 1.0, v87
	v_rcp_f32_e32 v87, v87
	global_store_dwordx2 v[132:133], v[84:85], off offset:64
	s_waitcnt vmcnt(16)
	v_lshlrev_b32_e32 v84, 16, v136
	v_mul_f32_e32 v82, v82, v96
	v_mul_f32_e32 v80, v80, v87
	v_mul_f32_e32 v80, v80, v84
	v_add_f32_e32 v84, 1.0, v89
	v_mul_f32_e32 v87, 0xbfb8aa3b, v82
	v_rcp_f32_e32 v84, v84
	v_exp_f32_e32 v87, v87
	v_mul_f32_e32 v83, v83, v96
	v_mul_f32_e32 v89, 0xbfb8aa3b, v83
	v_mul_f32_e32 v81, v81, v84
	v_add_f32_e32 v84, 1.0, v87
	v_rcp_f32_e32 v84, v84
	v_exp_f32_e32 v89, v89
	v_and_b32_e32 v85, 0xffff0000, v136
	v_mul_f32_e32 v81, v81, v85
	v_mul_f32_e32 v82, v82, v84
	s_waitcnt vmcnt(15)
	v_fmamk_f32 v84, v123, 0x3a800000, v167
	v_add_f32_e32 v87, 1.0, v89
	v_mul_f32_e32 v85, 0x4b800000, v84
	v_cmp_gt_f32_e32 vcc, s22, v84
	v_rcp_f32_e32 v87, v87
	v_lshlrev_b32_e32 v86, 16, v137
	v_cndmask_b32_e32 v84, v84, v85, vcc
	v_rsq_f32_e32 v84, v84
	v_and_b32_e32 v88, 0xffff0000, v137
	v_mul_f32_e32 v83, v83, v87
	v_cvt_pk_bf16_f32 v80, v80, v81
	v_mul_f32_e32 v82, v82, v86
	v_mul_f32_e32 v83, v83, v88
	v_cvt_pk_bf16_f32 v81, v82, v83
	global_store_dwordx2 v[132:133], v[80:81], off offset:96
	v_mul_f32_e32 v80, 0x45800000, v84
	v_cndmask_b32_e32 v80, v84, v80, vcc
	v_mul_f32_e32 v76, v76, v80
	v_mul_f32_e32 v84, 0xbfb8aa3b, v76
	v_exp_f32_e32 v84, v84
	v_mul_f32_e32 v77, v77, v80
	v_mul_f32_e32 v86, 0xbfb8aa3b, v77
	v_exp_f32_e32 v86, v86
	v_add_f32_e32 v84, 1.0, v84
	v_rcp_f32_e32 v84, v84
	s_waitcnt vmcnt(15)
	v_lshlrev_b32_e32 v81, 16, v134
	v_mul_f32_e32 v78, v78, v80
	v_mul_f32_e32 v79, v79, v80
	v_mul_f32_e32 v76, v76, v84
	v_mul_f32_e32 v76, v76, v81
	v_add_f32_e32 v81, 1.0, v86
	v_mul_f32_e32 v84, 0xbfb8aa3b, v78
	v_mul_f32_e32 v86, 0xbfb8aa3b, v79
	v_rcp_f32_e32 v81, v81
	v_exp_f32_e32 v84, v84
	v_exp_f32_e32 v86, v86
	v_and_b32_e32 v82, 0xffff0000, v134
	v_mul_f32_e32 v77, v77, v81
	v_add_f32_e32 v81, 1.0, v84
	v_add_f32_e32 v84, 1.0, v86
	v_rcp_f32_e32 v84, v84
	v_rcp_f32_e32 v81, v81
	v_and_b32_e32 v85, 0xffff0000, v135
	v_lshlrev_b32_e32 v83, 16, v135
	v_mul_f32_e32 v79, v79, v84
	v_mul_f32_e32 v77, v77, v82
	v_mul_f32_e32 v78, v78, v81
	v_mul_f32_e32 v79, v79, v85
	v_mul_f32_e32 v72, v72, v80
	v_mul_f32_e32 v78, v78, v83
	v_cvt_pk_bf16_f32 v76, v76, v77
	v_cvt_pk_bf16_f32 v77, v78, v79
	v_mul_f32_e32 v79, 0xbfb8aa3b, v72
	v_exp_f32_e32 v79, v79
	v_mul_f32_e32 v73, v73, v80
	v_mul_f32_e32 v82, 0xbfb8aa3b, v73
	v_exp_f32_e32 v82, v82
	v_add_f32_e32 v79, 1.0, v79
	v_rcp_f32_e32 v79, v79
	global_store_dwordx2 v[124:125], v[76:77], off
	s_waitcnt vmcnt(15)
	v_lshlrev_b32_e32 v76, 16, v130
	v_mul_f32_e32 v74, v74, v80
	v_mul_f32_e32 v75, v75, v80
	v_mul_f32_e32 v72, v72, v79
	v_mul_f32_e32 v72, v72, v76
	v_add_f32_e32 v76, 1.0, v82
	v_mul_f32_e32 v79, 0xbfb8aa3b, v74
	v_mul_f32_e32 v82, 0xbfb8aa3b, v75
	v_rcp_f32_e32 v76, v76
	v_exp_f32_e32 v79, v79
	v_exp_f32_e32 v82, v82
	v_and_b32_e32 v77, 0xffff0000, v130
	v_mul_f32_e32 v73, v73, v76
	v_add_f32_e32 v76, 1.0, v79
	v_add_f32_e32 v79, 1.0, v82
	v_rcp_f32_e32 v79, v79
	v_rcp_f32_e32 v76, v76
	v_and_b32_e32 v81, 0xffff0000, v131
	v_lshlrev_b32_e32 v78, 16, v131
	v_mul_f32_e32 v75, v75, v79
	v_mul_f32_e32 v73, v73, v77
	v_mul_f32_e32 v74, v74, v76
	v_mul_f32_e32 v75, v75, v81
	v_mul_f32_e32 v68, v68, v80
	v_mul_f32_e32 v74, v74, v78
	v_cvt_pk_bf16_f32 v72, v72, v73
	v_cvt_pk_bf16_f32 v73, v74, v75
	v_mul_f32_e32 v75, 0xbfb8aa3b, v68
	v_exp_f32_e32 v75, v75
	v_mul_f32_e32 v69, v69, v80
	v_mul_f32_e32 v77, 0xbfb8aa3b, v69
	v_exp_f32_e32 v77, v77
	v_add_f32_e32 v75, 1.0, v75
	v_rcp_f32_e32 v75, v75
	global_store_dwordx2 v[124:125], v[72:73], off offset:32
	s_waitcnt vmcnt(15)
	v_lshlrev_b32_e32 v72, 16, v128
	v_mul_f32_e32 v70, v70, v80
	v_mul_f32_e32 v71, v71, v80
	v_mul_f32_e32 v68, v68, v75
	v_mul_f32_e32 v68, v68, v72
	v_add_f32_e32 v72, 1.0, v77
	v_mul_f32_e32 v75, 0xbfb8aa3b, v70
	v_mul_f32_e32 v77, 0xbfb8aa3b, v71
	v_rcp_f32_e32 v72, v72
	v_exp_f32_e32 v75, v75
	v_exp_f32_e32 v77, v77
	v_and_b32_e32 v73, 0xffff0000, v128
	v_mul_f32_e32 v69, v69, v72
	v_add_f32_e32 v72, 1.0, v75
	v_add_f32_e32 v75, 1.0, v77
	v_rcp_f32_e32 v75, v75
	v_rcp_f32_e32 v72, v72
	v_and_b32_e32 v76, 0xffff0000, v129
	v_lshlrev_b32_e32 v74, 16, v129
	v_mul_f32_e32 v71, v71, v75
	v_mul_f32_e32 v69, v69, v73
	v_mul_f32_e32 v70, v70, v72
	v_mul_f32_e32 v71, v71, v76
	v_mul_f32_e32 v64, v64, v80
	v_mul_f32_e32 v70, v70, v74
	v_cvt_pk_bf16_f32 v68, v68, v69
	v_cvt_pk_bf16_f32 v69, v70, v71
	v_mul_f32_e32 v71, 0xbfb8aa3b, v64
	v_exp_f32_e32 v71, v71
	v_mul_f32_e32 v65, v65, v80
	v_mul_f32_e32 v73, 0xbfb8aa3b, v65
	v_exp_f32_e32 v73, v73
	v_add_f32_e32 v71, 1.0, v71
	v_rcp_f32_e32 v71, v71
	global_store_dwordx2 v[124:125], v[68:69], off offset:64
	s_waitcnt vmcnt(15)
	v_lshlrev_b32_e32 v68, 16, v126
	v_mul_f32_e32 v66, v66, v80
	v_mul_f32_e32 v67, v67, v80
	v_mul_f32_e32 v64, v64, v71
	v_mul_f32_e32 v64, v64, v68
	v_add_f32_e32 v68, 1.0, v73
	v_mul_f32_e32 v71, 0xbfb8aa3b, v66
	v_mul_f32_e32 v73, 0xbfb8aa3b, v67
	v_rcp_f32_e32 v68, v68
	v_exp_f32_e32 v71, v71
	v_exp_f32_e32 v73, v73
	v_and_b32_e32 v69, 0xffff0000, v126
	v_mul_f32_e32 v65, v65, v68
	v_add_f32_e32 v68, 1.0, v71
	v_add_f32_e32 v71, 1.0, v73
	v_rcp_f32_e32 v68, v68
	v_rcp_f32_e32 v71, v71
	v_lshlrev_b32_e32 v70, 16, v127
	v_and_b32_e32 v72, 0xffff0000, v127
	v_mul_f32_e32 v65, v65, v69
	v_mul_f32_e32 v66, v66, v68
	v_mul_f32_e32 v67, v67, v71
	v_mul_f32_e32 v66, v66, v70
	v_mul_f32_e32 v67, v67, v72
	v_cvt_pk_bf16_f32 v64, v64, v65
	v_cvt_pk_bf16_f32 v65, v66, v67
	global_store_dwordx2 v[124:125], v[64:65], off offset:96
	v_or_b32_e32 v64, 64, v122
	v_ashrrev_i32_e32 v65, 31, v64
	v_lshl_add_u64 v[66:67], v[64:65], 2, s[0:1]
	v_lshlrev_b64 v[64:65], 12, v[64:65]
	v_lshl_add_u64 v[92:93], v[120:121], 0, v[64:65]
	v_or_b32_e32 v64, 0x50, v122
	v_ashrrev_i32_e32 v65, 31, v64
	global_load_dword v97, v[66:67], off
	global_load_dwordx2 v[98:99], v[92:93], off
	global_load_dwordx2 v[100:101], v[92:93], off offset:32
	global_load_dwordx2 v[102:103], v[92:93], off offset:64
	v_lshl_add_u64 v[66:67], v[64:65], 2, s[0:1]
	v_lshlrev_b64 v[64:65], 12, v[64:65]
	v_lshl_add_u64 v[82:83], v[120:121], 0, v[64:65]
	v_or_b32_e32 v64, 0x60, v122
	v_ashrrev_i32_e32 v65, 31, v64
	global_load_dwordx2 v[104:105], v[92:93], off offset:96
	global_load_dword v106, v[66:67], off
	global_load_dwordx2 v[94:95], v[82:83], off
	global_load_dwordx2 v[90:91], v[82:83], off offset:32
	v_lshl_add_u64 v[66:67], v[64:65], 2, s[0:1]
	v_lshlrev_b64 v[64:65], 12, v[64:65]
	v_lshl_add_u64 v[72:73], v[120:121], 0, v[64:65]
	v_or_b32_e32 v64, 0x70, v122
	v_ashrrev_i32_e32 v65, 31, v64
	global_load_dwordx2 v[88:89], v[82:83], off offset:64
	global_load_dwordx2 v[86:87], v[82:83], off offset:96
	global_load_dword v107, v[66:67], off
	global_load_dwordx2 v[84:85], v[72:73], off
	v_lshl_add_u64 v[66:67], v[64:65], 2, s[0:1]
	v_lshlrev_b64 v[64:65], 12, v[64:65]
	v_lshl_add_u64 v[64:65], v[120:121], 0, v[64:65]
	global_load_dwordx2 v[80:81], v[72:73], off offset:32
	global_load_dwordx2 v[78:79], v[72:73], off offset:64
	global_load_dwordx2 v[76:77], v[72:73], off offset:96
	global_load_dword v96, v[66:67], off
	global_load_dwordx2 v[74:75], v[64:65], off
	global_load_dwordx2 v[70:71], v[64:65], off offset:32
	global_load_dwordx2 v[68:69], v[64:65], off offset:64
	s_nop 0
	global_load_dwordx2 v[66:67], v[64:65], off offset:96
	s_waitcnt vmcnt(19)
	v_fmamk_f32 v97, v97, 0x3a800000, v167
	v_mul_f32_e32 v108, 0x4b800000, v97
	v_cmp_gt_f32_e32 vcc, s22, v97
	s_nop 1
	v_cndmask_b32_e32 v97, v97, v108, vcc
	v_rsq_f32_e32 v97, v97
	s_waitcnt vmcnt(18)
	v_lshlrev_b32_e32 v108, 16, v98
	v_and_b32_e32 v98, 0xffff0000, v98
	v_mul_f32_e32 v109, 0x45800000, v97
	v_cndmask_b32_e32 v97, v97, v109, vcc
	v_mul_f32_e32 v60, v60, v97
	v_mul_f32_e32 v110, 0xbfb8aa3b, v60
	v_exp_f32_e32 v110, v110
	v_mul_f32_e32 v61, v61, v97
	v_mul_f32_e32 v111, 0xbfb8aa3b, v61
	v_exp_f32_e32 v111, v111
	v_add_f32_e32 v110, 1.0, v110
	v_rcp_f32_e32 v110, v110
	v_mul_f32_e32 v62, v62, v97
	v_mul_f32_e32 v63, v63, v97
	v_lshlrev_b32_e32 v109, 16, v99
	v_mul_f32_e32 v60, v60, v110
	v_mul_f32_e32 v60, v60, v108
	v_add_f32_e32 v108, 1.0, v111
	v_mul_f32_e32 v110, 0xbfb8aa3b, v62
	v_mul_f32_e32 v111, 0xbfb8aa3b, v63
	v_rcp_f32_e32 v108, v108
	v_exp_f32_e32 v110, v110
	v_exp_f32_e32 v111, v111
	v_and_b32_e32 v99, 0xffff0000, v99
	v_mul_f32_e32 v61, v61, v108
	v_add_f32_e32 v108, 1.0, v110
	v_add_f32_e32 v110, 1.0, v111
	v_rcp_f32_e32 v110, v110
	v_rcp_f32_e32 v108, v108
	v_mul_f32_e32 v61, v61, v98
	v_mul_f32_e32 v56, v56, v97
	v_mul_f32_e32 v63, v63, v110
	v_mul_f32_e32 v62, v62, v108
	v_mul_f32_e32 v63, v63, v99
	v_mul_f32_e32 v62, v62, v109
	v_cvt_pk_bf16_f32 v60, v60, v61
	v_cvt_pk_bf16_f32 v61, v62, v63
	v_mul_f32_e32 v63, 0xbfb8aa3b, v56
	v_exp_f32_e32 v63, v63
	v_mul_f32_e32 v57, v57, v97
	v_mul_f32_e32 v99, 0xbfb8aa3b, v57
	v_exp_f32_e32 v99, v99
	v_add_f32_e32 v63, 1.0, v63
	v_rcp_f32_e32 v63, v63
	global_store_dwordx2 v[92:93], v[60:61], off
	s_waitcnt vmcnt(18)
	v_lshlrev_b32_e32 v60, 16, v100
	v_mul_f32_e32 v58, v58, v97
	v_mul_f32_e32 v59, v59, v97
	v_mul_f32_e32 v56, v56, v63
	v_mul_f32_e32 v56, v56, v60
	v_add_f32_e32 v60, 1.0, v99
	v_mul_f32_e32 v63, 0xbfb8aa3b, v58
	v_mul_f32_e32 v99, 0xbfb8aa3b, v59
	v_rcp_f32_e32 v60, v60
	v_exp_f32_e32 v63, v63
	v_exp_f32_e32 v99, v99
	v_and_b32_e32 v61, 0xffff0000, v100
	v_mul_f32_e32 v57, v57, v60
	v_add_f32_e32 v60, 1.0, v63
	v_add_f32_e32 v63, 1.0, v99
	v_rcp_f32_e32 v63, v63
	v_rcp_f32_e32 v60, v60
	v_and_b32_e32 v98, 0xffff0000, v101
	v_lshlrev_b32_e32 v62, 16, v101
	v_mul_f32_e32 v59, v59, v63
	v_mul_f32_e32 v57, v57, v61
	v_mul_f32_e32 v58, v58, v60
	v_mul_f32_e32 v59, v59, v98
	v_mul_f32_e32 v52, v52, v97
	v_mul_f32_e32 v58, v58, v62
	v_cvt_pk_bf16_f32 v56, v56, v57
	v_cvt_pk_bf16_f32 v57, v58, v59
	v_mul_f32_e32 v59, 0xbfb8aa3b, v52
	v_exp_f32_e32 v59, v59
	v_mul_f32_e32 v53, v53, v97
	v_mul_f32_e32 v61, 0xbfb8aa3b, v53
	v_exp_f32_e32 v61, v61
	v_add_f32_e32 v59, 1.0, v59
	v_rcp_f32_e32 v59, v59
	global_store_dwordx2 v[92:93], v[56:57], off offset:32
	s_waitcnt vmcnt(18)
	v_lshlrev_b32_e32 v56, 16, v102
	v_mul_f32_e32 v54, v54, v97
	v_mul_f32_e32 v55, v55, v97
	v_mul_f32_e32 v52, v52, v59
	v_mul_f32_e32 v52, v52, v56
	v_add_f32_e32 v56, 1.0, v61
	v_mul_f32_e32 v59, 0xbfb8aa3b, v54
	v_mul_f32_e32 v61, 0xbfb8aa3b, v55
	v_rcp_f32_e32 v56, v56
	v_exp_f32_e32 v59, v59
	v_exp_f32_e32 v61, v61
	v_and_b32_e32 v57, 0xffff0000, v102
	v_mul_f32_e32 v53, v53, v56
	v_add_f32_e32 v56, 1.0, v59
	v_add_f32_e32 v59, 1.0, v61
	v_rcp_f32_e32 v59, v59
	v_rcp_f32_e32 v56, v56
	v_and_b32_e32 v60, 0xffff0000, v103
	v_lshlrev_b32_e32 v58, 16, v103
	v_mul_f32_e32 v55, v55, v59
	v_mul_f32_e32 v53, v53, v57
	v_mul_f32_e32 v54, v54, v56
	v_mul_f32_e32 v55, v55, v60
	v_mul_f32_e32 v48, v48, v97
	v_mul_f32_e32 v54, v54, v58
	v_cvt_pk_bf16_f32 v52, v52, v53
	v_cvt_pk_bf16_f32 v53, v54, v55
	v_mul_f32_e32 v55, 0xbfb8aa3b, v48
	v_exp_f32_e32 v55, v55
	v_mul_f32_e32 v49, v49, v97
	v_mul_f32_e32 v57, 0xbfb8aa3b, v49
	v_exp_f32_e32 v57, v57
	v_add_f32_e32 v55, 1.0, v55
	v_rcp_f32_e32 v55, v55
	global_store_dwordx2 v[92:93], v[52:53], off offset:64
	s_waitcnt vmcnt(18)
	v_lshlrev_b32_e32 v52, 16, v104
	v_mul_f32_e32 v50, v50, v97
	v_mul_f32_e32 v48, v48, v55
	v_mul_f32_e32 v48, v48, v52
	v_add_f32_e32 v52, 1.0, v57
	v_mul_f32_e32 v55, 0xbfb8aa3b, v50
	v_rcp_f32_e32 v52, v52
	v_exp_f32_e32 v55, v55
	v_mul_f32_e32 v51, v51, v97
	v_mul_f32_e32 v57, 0xbfb8aa3b, v51
	v_mul_f32_e32 v49, v49, v52
	v_add_f32_e32 v52, 1.0, v55
	v_rcp_f32_e32 v52, v52
	v_exp_f32_e32 v57, v57
	v_and_b32_e32 v53, 0xffff0000, v104
	v_mul_f32_e32 v49, v49, v53
	v_mul_f32_e32 v50, v50, v52
	s_waitcnt vmcnt(17)
	v_fmamk_f32 v52, v106, 0x3a800000, v167
	v_add_f32_e32 v55, 1.0, v57
	v_mul_f32_e32 v53, 0x4b800000, v52
	v_cmp_gt_f32_e32 vcc, s22, v52
	v_rcp_f32_e32 v55, v55
	v_lshlrev_b32_e32 v54, 16, v105
	v_cndmask_b32_e32 v52, v52, v53, vcc
	v_rsq_f32_e32 v52, v52
	v_and_b32_e32 v56, 0xffff0000, v105
	v_mul_f32_e32 v51, v51, v55
	v_cvt_pk_bf16_f32 v48, v48, v49
	v_mul_f32_e32 v50, v50, v54
	v_mul_f32_e32 v51, v51, v56
	v_cvt_pk_bf16_f32 v49, v50, v51
	global_store_dwordx2 v[92:93], v[48:49], off offset:96
	v_mul_f32_e32 v48, 0x45800000, v52
	v_cndmask_b32_e32 v48, v52, v48, vcc
	v_mul_f32_e32 v44, v44, v48
	v_mul_f32_e32 v52, 0xbfb8aa3b, v44
	v_exp_f32_e32 v52, v52
	v_mul_f32_e32 v45, v45, v48
	v_mul_f32_e32 v54, 0xbfb8aa3b, v45
	v_exp_f32_e32 v54, v54
	v_add_f32_e32 v52, 1.0, v52
	v_rcp_f32_e32 v52, v52
	s_waitcnt vmcnt(17)
	v_lshlrev_b32_e32 v49, 16, v94
	v_mul_f32_e32 v46, v46, v48
	v_mul_f32_e32 v47, v47, v48
	v_mul_f32_e32 v44, v44, v52
	v_mul_f32_e32 v44, v44, v49
	v_add_f32_e32 v49, 1.0, v54
	v_mul_f32_e32 v52, 0xbfb8aa3b, v46
	v_mul_f32_e32 v54, 0xbfb8aa3b, v47
	v_rcp_f32_e32 v49, v49
	v_exp_f32_e32 v52, v52
	v_exp_f32_e32 v54, v54
	v_and_b32_e32 v50, 0xffff0000, v94
	v_mul_f32_e32 v45, v45, v49
	v_add_f32_e32 v49, 1.0, v52
	v_add_f32_e32 v52, 1.0, v54
	v_rcp_f32_e32 v52, v52
	v_rcp_f32_e32 v49, v49
	v_and_b32_e32 v53, 0xffff0000, v95
	v_lshlrev_b32_e32 v51, 16, v95
	v_mul_f32_e32 v47, v47, v52
	v_mul_f32_e32 v45, v45, v50
	v_mul_f32_e32 v46, v46, v49
	v_mul_f32_e32 v47, v47, v53
	v_mul_f32_e32 v40, v40, v48
	v_mul_f32_e32 v46, v46, v51
	v_cvt_pk_bf16_f32 v44, v44, v45
	v_cvt_pk_bf16_f32 v45, v46, v47
	v_mul_f32_e32 v47, 0xbfb8aa3b, v40
	v_exp_f32_e32 v47, v47
	v_mul_f32_e32 v41, v41, v48
	v_mul_f32_e32 v50, 0xbfb8aa3b, v41
	v_exp_f32_e32 v50, v50
	v_add_f32_e32 v47, 1.0, v47
	v_rcp_f32_e32 v47, v47
	global_store_dwordx2 v[82:83], v[44:45], off
	s_waitcnt vmcnt(17)
	v_lshlrev_b32_e32 v44, 16, v90
	v_mul_f32_e32 v42, v42, v48
	v_mul_f32_e32 v43, v43, v48
	v_mul_f32_e32 v40, v40, v47
	v_mul_f32_e32 v40, v40, v44
	v_add_f32_e32 v44, 1.0, v50
	v_mul_f32_e32 v47, 0xbfb8aa3b, v42
	v_mul_f32_e32 v50, 0xbfb8aa3b, v43
	v_rcp_f32_e32 v44, v44
	v_exp_f32_e32 v47, v47
	v_exp_f32_e32 v50, v50
	v_and_b32_e32 v45, 0xffff0000, v90
	v_mul_f32_e32 v41, v41, v44
	v_add_f32_e32 v44, 1.0, v47
	v_add_f32_e32 v47, 1.0, v50
	v_rcp_f32_e32 v47, v47
	v_rcp_f32_e32 v44, v44
	v_and_b32_e32 v49, 0xffff0000, v91
	v_lshlrev_b32_e32 v46, 16, v91
	v_mul_f32_e32 v43, v43, v47
	v_mul_f32_e32 v41, v41, v45
	v_mul_f32_e32 v42, v42, v44
	v_mul_f32_e32 v43, v43, v49
	v_mul_f32_e32 v36, v36, v48
	v_mul_f32_e32 v42, v42, v46
	v_cvt_pk_bf16_f32 v40, v40, v41
	v_cvt_pk_bf16_f32 v41, v42, v43
	v_mul_f32_e32 v43, 0xbfb8aa3b, v36
	v_exp_f32_e32 v43, v43
	v_mul_f32_e32 v37, v37, v48
	v_mul_f32_e32 v45, 0xbfb8aa3b, v37
	v_exp_f32_e32 v45, v45
	v_add_f32_e32 v43, 1.0, v43
	v_rcp_f32_e32 v43, v43
	global_store_dwordx2 v[82:83], v[40:41], off offset:32
	s_waitcnt vmcnt(17)
	v_lshlrev_b32_e32 v40, 16, v88
	v_mul_f32_e32 v38, v38, v48
	v_mul_f32_e32 v39, v39, v48
	v_mul_f32_e32 v36, v36, v43
	v_mul_f32_e32 v36, v36, v40
	v_add_f32_e32 v40, 1.0, v45
	v_mul_f32_e32 v43, 0xbfb8aa3b, v38
	v_mul_f32_e32 v45, 0xbfb8aa3b, v39
	v_rcp_f32_e32 v40, v40
	v_exp_f32_e32 v43, v43
	v_exp_f32_e32 v45, v45
	v_and_b32_e32 v41, 0xffff0000, v88
	v_mul_f32_e32 v37, v37, v40
	v_add_f32_e32 v40, 1.0, v43
	v_add_f32_e32 v43, 1.0, v45
	v_rcp_f32_e32 v43, v43
	v_rcp_f32_e32 v40, v40
	v_and_b32_e32 v44, 0xffff0000, v89
	v_lshlrev_b32_e32 v42, 16, v89
	v_mul_f32_e32 v39, v39, v43
	v_mul_f32_e32 v37, v37, v41
	v_mul_f32_e32 v38, v38, v40
	v_mul_f32_e32 v39, v39, v44
	v_mul_f32_e32 v32, v32, v48
	v_mul_f32_e32 v38, v38, v42
	v_cvt_pk_bf16_f32 v36, v36, v37
	v_cvt_pk_bf16_f32 v37, v38, v39
	v_mul_f32_e32 v39, 0xbfb8aa3b, v32
	v_exp_f32_e32 v39, v39
	v_mul_f32_e32 v33, v33, v48
	v_mul_f32_e32 v41, 0xbfb8aa3b, v33
	v_exp_f32_e32 v41, v41
	v_add_f32_e32 v39, 1.0, v39
	v_rcp_f32_e32 v39, v39
	global_store_dwordx2 v[82:83], v[36:37], off offset:64
	s_waitcnt vmcnt(17)
	v_lshlrev_b32_e32 v36, 16, v86
	v_mul_f32_e32 v34, v34, v48
	v_mul_f32_e32 v32, v32, v39
	v_mul_f32_e32 v32, v32, v36
	v_add_f32_e32 v36, 1.0, v41
	v_mul_f32_e32 v39, 0xbfb8aa3b, v34
	v_rcp_f32_e32 v36, v36
	v_exp_f32_e32 v39, v39
	v_mul_f32_e32 v35, v35, v48
	v_mul_f32_e32 v41, 0xbfb8aa3b, v35
	v_mul_f32_e32 v33, v33, v36
	v_add_f32_e32 v36, 1.0, v39
	v_rcp_f32_e32 v36, v36
	v_exp_f32_e32 v41, v41
	v_and_b32_e32 v37, 0xffff0000, v86
	v_mul_f32_e32 v33, v33, v37
	v_mul_f32_e32 v34, v34, v36
	s_waitcnt vmcnt(16)
	v_fmamk_f32 v36, v107, 0x3a800000, v167
	v_add_f32_e32 v39, 1.0, v41
	v_mul_f32_e32 v37, 0x4b800000, v36
	v_cmp_gt_f32_e32 vcc, s22, v36
	v_rcp_f32_e32 v39, v39
	v_lshlrev_b32_e32 v38, 16, v87
	v_cndmask_b32_e32 v36, v36, v37, vcc
	v_rsq_f32_e32 v36, v36
	v_and_b32_e32 v40, 0xffff0000, v87
	v_mul_f32_e32 v35, v35, v39
	v_cvt_pk_bf16_f32 v32, v32, v33
	v_mul_f32_e32 v34, v34, v38
	v_mul_f32_e32 v35, v35, v40
	v_cvt_pk_bf16_f32 v33, v34, v35
	global_store_dwordx2 v[82:83], v[32:33], off offset:96
	v_mul_f32_e32 v32, 0x45800000, v36
	v_cndmask_b32_e32 v32, v36, v32, vcc
	v_mul_f32_e32 v28, v28, v32
	v_mul_f32_e32 v36, 0xbfb8aa3b, v28
	v_exp_f32_e32 v36, v36
	v_mul_f32_e32 v29, v29, v32
	v_mul_f32_e32 v38, 0xbfb8aa3b, v29
	v_exp_f32_e32 v38, v38
	v_add_f32_e32 v36, 1.0, v36
	v_rcp_f32_e32 v36, v36
	s_waitcnt vmcnt(16)
	v_lshlrev_b32_e32 v33, 16, v84
	v_mul_f32_e32 v30, v30, v32
	v_mul_f32_e32 v31, v31, v32
	v_mul_f32_e32 v28, v28, v36
	v_mul_f32_e32 v28, v28, v33
	v_add_f32_e32 v33, 1.0, v38
	v_mul_f32_e32 v36, 0xbfb8aa3b, v30
	v_mul_f32_e32 v38, 0xbfb8aa3b, v31
	v_rcp_f32_e32 v33, v33
	v_exp_f32_e32 v36, v36
	v_exp_f32_e32 v38, v38
	v_and_b32_e32 v34, 0xffff0000, v84
	v_mul_f32_e32 v29, v29, v33
	v_add_f32_e32 v33, 1.0, v36
	v_add_f32_e32 v36, 1.0, v38
	v_rcp_f32_e32 v36, v36
	v_rcp_f32_e32 v33, v33
	v_and_b32_e32 v37, 0xffff0000, v85
	v_lshlrev_b32_e32 v35, 16, v85
	v_mul_f32_e32 v31, v31, v36
	v_mul_f32_e32 v29, v29, v34
	v_mul_f32_e32 v30, v30, v33
	v_mul_f32_e32 v31, v31, v37
	v_mul_f32_e32 v24, v24, v32
	v_mul_f32_e32 v30, v30, v35
	v_cvt_pk_bf16_f32 v28, v28, v29
	v_cvt_pk_bf16_f32 v29, v30, v31
	v_mul_f32_e32 v31, 0xbfb8aa3b, v24
	v_exp_f32_e32 v31, v31
	v_mul_f32_e32 v25, v25, v32
	v_mul_f32_e32 v34, 0xbfb8aa3b, v25
	v_exp_f32_e32 v34, v34
	v_add_f32_e32 v31, 1.0, v31
	v_rcp_f32_e32 v31, v31
	global_store_dwordx2 v[72:73], v[28:29], off
	s_waitcnt vmcnt(16)
	v_lshlrev_b32_e32 v28, 16, v80
	v_mul_f32_e32 v26, v26, v32
	v_mul_f32_e32 v27, v27, v32
	v_mul_f32_e32 v24, v24, v31
	v_mul_f32_e32 v24, v24, v28
	v_add_f32_e32 v28, 1.0, v34
	v_mul_f32_e32 v31, 0xbfb8aa3b, v26
	v_mul_f32_e32 v34, 0xbfb8aa3b, v27
	v_rcp_f32_e32 v28, v28
	v_exp_f32_e32 v31, v31
	v_exp_f32_e32 v34, v34
	v_and_b32_e32 v29, 0xffff0000, v80
	v_mul_f32_e32 v25, v25, v28
	v_add_f32_e32 v28, 1.0, v31
	v_add_f32_e32 v31, 1.0, v34
	v_rcp_f32_e32 v31, v31
	v_rcp_f32_e32 v28, v28
	v_and_b32_e32 v33, 0xffff0000, v81
	v_lshlrev_b32_e32 v30, 16, v81
	v_mul_f32_e32 v27, v27, v31
	v_mul_f32_e32 v25, v25, v29
	v_mul_f32_e32 v26, v26, v28
	v_mul_f32_e32 v27, v27, v33
	v_mul_f32_e32 v20, v20, v32
	v_mul_f32_e32 v26, v26, v30
	v_cvt_pk_bf16_f32 v24, v24, v25
	v_cvt_pk_bf16_f32 v25, v26, v27
	v_mul_f32_e32 v27, 0xbfb8aa3b, v20
	v_exp_f32_e32 v27, v27
	v_mul_f32_e32 v21, v21, v32
	v_mul_f32_e32 v29, 0xbfb8aa3b, v21
	v_exp_f32_e32 v29, v29
	v_add_f32_e32 v27, 1.0, v27
	v_rcp_f32_e32 v27, v27
	global_store_dwordx2 v[72:73], v[24:25], off offset:32
	s_waitcnt vmcnt(16)
	v_lshlrev_b32_e32 v24, 16, v78
	v_mul_f32_e32 v22, v22, v32
	v_mul_f32_e32 v23, v23, v32
	v_mul_f32_e32 v20, v20, v27
	v_mul_f32_e32 v20, v20, v24
	v_add_f32_e32 v24, 1.0, v29
	v_mul_f32_e32 v27, 0xbfb8aa3b, v22
	v_mul_f32_e32 v29, 0xbfb8aa3b, v23
	v_rcp_f32_e32 v24, v24
	v_exp_f32_e32 v27, v27
	v_exp_f32_e32 v29, v29
	v_and_b32_e32 v25, 0xffff0000, v78
	v_mul_f32_e32 v21, v21, v24
	v_add_f32_e32 v24, 1.0, v27
	v_add_f32_e32 v27, 1.0, v29
	v_rcp_f32_e32 v27, v27
	v_rcp_f32_e32 v24, v24
	v_and_b32_e32 v28, 0xffff0000, v79
	v_lshlrev_b32_e32 v26, 16, v79
	v_mul_f32_e32 v23, v23, v27
	v_mul_f32_e32 v21, v21, v25
	v_mul_f32_e32 v22, v22, v24
	v_mul_f32_e32 v23, v23, v28
	v_mul_f32_e32 v16, v16, v32
	v_mul_f32_e32 v22, v22, v26
	v_cvt_pk_bf16_f32 v20, v20, v21
	v_cvt_pk_bf16_f32 v21, v22, v23
	v_mul_f32_e32 v23, 0xbfb8aa3b, v16
	v_exp_f32_e32 v23, v23
	v_mul_f32_e32 v17, v17, v32
	v_mul_f32_e32 v25, 0xbfb8aa3b, v17
	v_exp_f32_e32 v25, v25
	v_add_f32_e32 v23, 1.0, v23
	v_rcp_f32_e32 v23, v23
	global_store_dwordx2 v[72:73], v[20:21], off offset:64
	s_waitcnt vmcnt(16)
	v_lshlrev_b32_e32 v20, 16, v76
	v_mul_f32_e32 v18, v18, v32
	v_mul_f32_e32 v16, v16, v23
	v_mul_f32_e32 v16, v16, v20
	v_add_f32_e32 v20, 1.0, v25
	v_mul_f32_e32 v23, 0xbfb8aa3b, v18
	v_rcp_f32_e32 v20, v20
	v_exp_f32_e32 v23, v23
	v_mul_f32_e32 v19, v19, v32
	v_mul_f32_e32 v25, 0xbfb8aa3b, v19
	v_mul_f32_e32 v17, v17, v20
	v_add_f32_e32 v20, 1.0, v23
	v_rcp_f32_e32 v20, v20
	v_exp_f32_e32 v25, v25
	v_and_b32_e32 v21, 0xffff0000, v76
	v_mul_f32_e32 v17, v17, v21
	v_mul_f32_e32 v18, v18, v20
	s_waitcnt vmcnt(15)
	v_fmamk_f32 v20, v96, 0x3a800000, v167
	v_add_f32_e32 v23, 1.0, v25
	v_mul_f32_e32 v21, 0x4b800000, v20
	v_cmp_gt_f32_e32 vcc, s22, v20
	v_rcp_f32_e32 v23, v23
	v_lshlrev_b32_e32 v22, 16, v77
	v_cndmask_b32_e32 v20, v20, v21, vcc
	v_rsq_f32_e32 v20, v20
	v_and_b32_e32 v24, 0xffff0000, v77
	v_mul_f32_e32 v19, v19, v23
	v_cvt_pk_bf16_f32 v16, v16, v17
	v_mul_f32_e32 v18, v18, v22
	v_mul_f32_e32 v19, v19, v24
	v_cvt_pk_bf16_f32 v17, v18, v19
	global_store_dwordx2 v[72:73], v[16:17], off offset:96
	v_mul_f32_e32 v16, 0x45800000, v20
	v_cndmask_b32_e32 v16, v20, v16, vcc
	v_mul_f32_e32 v12, v12, v16
	v_mul_f32_e32 v20, 0xbfb8aa3b, v12
	v_exp_f32_e32 v20, v20
	v_mul_f32_e32 v13, v13, v16
	v_mul_f32_e32 v22, 0xbfb8aa3b, v13
	v_exp_f32_e32 v22, v22
	v_add_f32_e32 v20, 1.0, v20
	v_rcp_f32_e32 v20, v20
	s_waitcnt vmcnt(15)
	v_lshlrev_b32_e32 v17, 16, v74
	v_mul_f32_e32 v14, v14, v16
	v_mul_f32_e32 v15, v15, v16
	v_mul_f32_e32 v12, v12, v20
	v_mul_f32_e32 v12, v12, v17
	v_add_f32_e32 v17, 1.0, v22
	v_mul_f32_e32 v20, 0xbfb8aa3b, v14
	v_mul_f32_e32 v22, 0xbfb8aa3b, v15
	v_rcp_f32_e32 v17, v17
	v_exp_f32_e32 v20, v20
	v_exp_f32_e32 v22, v22
	v_and_b32_e32 v18, 0xffff0000, v74
	v_mul_f32_e32 v13, v13, v17
	v_add_f32_e32 v17, 1.0, v20
	v_add_f32_e32 v20, 1.0, v22
	v_rcp_f32_e32 v20, v20
	v_rcp_f32_e32 v17, v17
	v_and_b32_e32 v21, 0xffff0000, v75
	v_lshlrev_b32_e32 v19, 16, v75
	v_mul_f32_e32 v15, v15, v20
	v_mul_f32_e32 v13, v13, v18
	v_mul_f32_e32 v14, v14, v17
	v_mul_f32_e32 v15, v15, v21
	v_mul_f32_e32 v8, v8, v16
	v_mul_f32_e32 v14, v14, v19
	v_cvt_pk_bf16_f32 v12, v12, v13
	v_cvt_pk_bf16_f32 v13, v14, v15
	v_mul_f32_e32 v15, 0xbfb8aa3b, v8
	v_exp_f32_e32 v15, v15
	v_mul_f32_e32 v9, v9, v16
	v_mul_f32_e32 v18, 0xbfb8aa3b, v9
	v_exp_f32_e32 v18, v18
	v_add_f32_e32 v15, 1.0, v15
	v_rcp_f32_e32 v15, v15
	global_store_dwordx2 v[64:65], v[12:13], off
	s_waitcnt vmcnt(15)
	v_lshlrev_b32_e32 v12, 16, v70
	v_mul_f32_e32 v10, v10, v16
	v_mul_f32_e32 v11, v11, v16
	v_mul_f32_e32 v8, v8, v15
	v_mul_f32_e32 v8, v8, v12
	v_add_f32_e32 v12, 1.0, v18
	v_mul_f32_e32 v15, 0xbfb8aa3b, v10
	v_mul_f32_e32 v18, 0xbfb8aa3b, v11
	v_rcp_f32_e32 v12, v12
	v_exp_f32_e32 v15, v15
	v_exp_f32_e32 v18, v18
	v_and_b32_e32 v13, 0xffff0000, v70
	v_mul_f32_e32 v9, v9, v12
	v_add_f32_e32 v12, 1.0, v15
	v_add_f32_e32 v15, 1.0, v18
	v_rcp_f32_e32 v15, v15
	v_rcp_f32_e32 v12, v12
	v_and_b32_e32 v17, 0xffff0000, v71
	v_lshlrev_b32_e32 v14, 16, v71
	v_mul_f32_e32 v11, v11, v15
	v_mul_f32_e32 v9, v9, v13
	v_mul_f32_e32 v10, v10, v12
	v_mul_f32_e32 v11, v11, v17
	v_mul_f32_e32 v4, v4, v16
	v_mul_f32_e32 v10, v10, v14
	v_cvt_pk_bf16_f32 v8, v8, v9
	v_cvt_pk_bf16_f32 v9, v10, v11
	v_mul_f32_e32 v11, 0xbfb8aa3b, v4
	v_exp_f32_e32 v11, v11
	v_mul_f32_e32 v5, v5, v16
	v_mul_f32_e32 v13, 0xbfb8aa3b, v5
	v_exp_f32_e32 v13, v13
	v_add_f32_e32 v11, 1.0, v11
	v_rcp_f32_e32 v11, v11
	global_store_dwordx2 v[64:65], v[8:9], off offset:32
	s_waitcnt vmcnt(15)
	v_lshlrev_b32_e32 v8, 16, v68
	v_mul_f32_e32 v6, v6, v16
	v_mul_f32_e32 v7, v7, v16
	v_mul_f32_e32 v4, v4, v11
	v_mul_f32_e32 v4, v4, v8
	v_add_f32_e32 v8, 1.0, v13
	v_mul_f32_e32 v11, 0xbfb8aa3b, v6
	v_mul_f32_e32 v13, 0xbfb8aa3b, v7
	v_rcp_f32_e32 v8, v8
	v_exp_f32_e32 v11, v11
	v_exp_f32_e32 v13, v13
	v_and_b32_e32 v9, 0xffff0000, v68
	v_mul_f32_e32 v5, v5, v8
	v_add_f32_e32 v8, 1.0, v11
	v_add_f32_e32 v11, 1.0, v13
	v_rcp_f32_e32 v11, v11
	v_rcp_f32_e32 v8, v8
	v_and_b32_e32 v12, 0xffff0000, v69
	v_lshlrev_b32_e32 v10, 16, v69
	v_mul_f32_e32 v7, v7, v11
	v_mul_f32_e32 v5, v5, v9
	v_mul_f32_e32 v6, v6, v8
	v_mul_f32_e32 v7, v7, v12
	v_mul_f32_e32 v0, v0, v16
	v_mul_f32_e32 v6, v6, v10
	v_cvt_pk_bf16_f32 v4, v4, v5
	v_cvt_pk_bf16_f32 v5, v6, v7
	v_mul_f32_e32 v7, 0xbfb8aa3b, v0
	v_exp_f32_e32 v7, v7
	v_mul_f32_e32 v1, v1, v16
	v_mul_f32_e32 v9, 0xbfb8aa3b, v1
	v_exp_f32_e32 v9, v9
	v_add_f32_e32 v7, 1.0, v7
	v_rcp_f32_e32 v7, v7
	global_store_dwordx2 v[64:65], v[4:5], off offset:64
	s_waitcnt vmcnt(15)
	v_lshlrev_b32_e32 v4, 16, v66
	v_mul_f32_e32 v2, v2, v16
	v_mul_f32_e32 v3, v3, v16
	v_mul_f32_e32 v0, v0, v7
	v_mul_f32_e32 v0, v0, v4
	v_add_f32_e32 v4, 1.0, v9
	v_mul_f32_e32 v7, 0xbfb8aa3b, v2
	v_mul_f32_e32 v9, 0xbfb8aa3b, v3
	v_rcp_f32_e32 v4, v4
	v_exp_f32_e32 v7, v7
	v_exp_f32_e32 v9, v9
	v_and_b32_e32 v5, 0xffff0000, v66
	v_mul_f32_e32 v1, v1, v4
	v_add_f32_e32 v4, 1.0, v7
	v_add_f32_e32 v7, 1.0, v9
	v_rcp_f32_e32 v4, v4
	v_rcp_f32_e32 v7, v7
	v_lshlrev_b32_e32 v6, 16, v67
	v_and_b32_e32 v8, 0xffff0000, v67
	v_mul_f32_e32 v1, v1, v5
	v_mul_f32_e32 v2, v2, v4
	v_mul_f32_e32 v3, v3, v7
	v_mul_f32_e32 v2, v2, v6
	v_mul_f32_e32 v3, v3, v8
	v_cvt_pk_bf16_f32 v0, v0, v1
	v_cvt_pk_bf16_f32 v1, v2, v3
	global_store_dwordx2 v[64:65], v[0:1], off offset:96
	s_add_i32 s23, s23, s74
	s_cmpk_lt_i32 s23, 0x800
	s_cbranch_scc1 .LBB0_1736
